# baseline (speedup 1.0000x reference)
; DEV int tid_opaque() { int t = threadIdx.x; asm volatile("" : "+v"(t)); return t; }
; #define RAW_BARRIER() do { asm volatile("s_waitcnt lgkmcnt(0)" ::: "memory"); __builtin_amdgcn_s_barrier(); } while (0)
; #define GLDS_TILE(kt, st) do { _Pragma("unroll") for (int _i = 0; _i < NP; ++_i) GLDS_PIECE(_i, kt, st); } while (0)
;     constexpr int BROWS = 32 * NI, STAGE = 8192 + BROWS * 64, NB = BROWS / 64;
;     const int t = tid_opaque(), lane = t & 63, wid = t >> 6, wm = wid >> 1, wn = wid & 1, fr = lane & 15, fq = lane >> 4;
;     const int nk = K >> 5;
;     const int srow = wid * 16 + (lane >> 2), sch = (lane & 3) ^ ((0 - (lane >> 4)) & 3);
;     const bf16_t* ga = A + (size_t)srow * lda + sch * 8;
;     const bf16_t* gb = B + (size_t)srow * ldb + sch * 8;
;     const int rd = fr * 64 + ((fq ^ ((0 - (fr >> 2)) & 3)) << 4);
;     const int rda = (wm * 64) * 64 + rd, rdb = 8192 + (wn * 16 * NI) * 64 + rd;
;     ...
;     constexpr int NH = NI >= 4 ? NI / 2 : NI;
;     constexpr int NP = 2 + NB, IVL = (4 * NI) / NP;
;     RAW_BARRIER();
;     GLDS_TILE(0, 0);
;     GLDS_TILE(1, 1);
;     int st = 0;
;     for (int kt = 0; kt < nk - 1; ++kt) {
;         if (NI == 8) asm volatile("s_waitcnt vmcnt(6)" ::: "memory"); else if (NI == 4) asm volatile("s_waitcnt vmcnt(4)" ::: "memory"); else asm volatile("s_waitcnt vmcnt(3)" ::: "memory");
;         RAW_BARRIER();
;         const int s2 = st >= 1 ? st - 1 : 2;
;         const bool ld = kt + 2 < nk;
;         STEP_TILE(st, ld, kt + 2, s2);
;         st = st == 2 ? 0 : st + 1;
;     }
;     asm volatile("s_waitcnt vmcnt(0)" ::: "memory");
;     RAW_BARRIER();
;     STEP_TILE(st, false, 0, 0);
;     RAW_BARRIER();
.LBB0_26:
	s_mul_i32 s22, s21, 0x3000
	s_add_i32 s23, s22, 0
	s_waitcnt vmcnt(3)
	v_add_u32_e32 v32, s23, v39
	s_waitcnt lgkmcnt(0)
	s_barrier
	ds_read_b128 v[42:45], v32
	ds_read_b128 v[46:49], v32 offset:1024
	ds_read_b128 v[50:53], v32 offset:2048
	ds_read_b128 v[54:57], v32 offset:3072
	v_add_u32_e32 v32, s23, v40
	ds_read_b128 v[58:61], v32 offset:8192
	s_waitcnt vmcnt(0)
	ds_read_b128 v[62:65], v32 offset:9216
	s_addk_i32 s22, 0xd000
	s_cmp_gt_i32 s21, 0
	s_setprio 1
	s_waitcnt lgkmcnt(0)
	v_mfma_f32_16x16x32_bf16 v[28:31], v[58:61], v[42:45], v[28:31]
	s_cselect_b32 s22, s22, 0x6000
	v_add_u32_e32 v32, s22, v38
	v_lshl_add_u64 v[66:67], v[36:37], 0, s[10:11]
	v_mfma_f32_16x16x32_bf16 v[24:27], v[58:61], v[46:49], v[24:27]
	v_lshl_add_u64 v[70:71], v[34:35], 0, s[10:11]
	s_mov_b64 s[22:23], 0x10d2c080
	v_lshl_add_u64 v[68:69], v[66:67], 0, s[28:29]
	v_add_u32_e32 v41, 0x2000, v32
	v_lshl_add_u64 v[72:73], v[70:71], 0, s[22:23]
	v_readfirstlane_b32 s22, v32
	s_mov_b32 m0, s22
	s_nop 0
	global_load_lds_dwordx4 v[72:73], off
	v_mfma_f32_16x16x32_bf16 v[16:19], v[58:61], v[50:53], v[16:19]
	v_mfma_f32_16x16x32_bf16 v[8:11], v[58:61], v[54:57], v[8:11]
	s_mov_b64 s[22:23], 0x10d84080
	v_add_u32_e32 v32, 0x1000, v32
	v_lshl_add_u64 v[58:59], v[70:71], 0, s[22:23]
	v_readfirstlane_b32 s22, v32
	s_mov_b32 m0, s22
	s_nop 0
	global_load_lds_dwordx4 v[58:59], off
	v_mfma_f32_16x16x32_bf16 v[20:23], v[62:65], v[42:45], v[20:23]
	v_mfma_f32_16x16x32_bf16 v[12:15], v[62:65], v[46:49], v[12:15]
	v_readfirstlane_b32 s22, v41
	s_mov_b32 m0, s22
	s_nop 0
	global_load_lds_dwordx4 v[68:69], off
	v_mfma_f32_16x16x32_bf16 v[4:7], v[62:65], v[50:53], v[4:7]
	v_mfma_f32_16x16x32_bf16 v[0:3], v[62:65], v[54:57], v[0:3]
	s_setprio 0
	s_add_i32 s22, s21, 1
	s_cmp_lg_u32 s21, 2
	s_cselect_b32 s21, s22, 0
	s_mul_i32 s22, s21, 0x3000
	s_add_i32 s23, s22, 0
	s_waitcnt vmcnt(3)
	v_add_u32_e32 v32, s23, v39
	s_waitcnt lgkmcnt(0)
	s_barrier
	ds_read_b128 v[42:45], v32
	ds_read_b128 v[46:49], v32 offset:1024
	ds_read_b128 v[50:53], v32 offset:2048
	ds_read_b128 v[54:57], v32 offset:3072
	v_add_u32_e32 v32, s23, v40
	ds_read_b128 v[58:61], v32 offset:8192
	ds_read_b128 v[62:65], v32 offset:9216
	s_addk_i32 s22, 0xd000
	s_cmp_gt_i32 s21, 0
	s_setprio 1
	s_waitcnt lgkmcnt(0)
	v_mfma_f32_16x16x32_bf16 v[28:31], v[58:61], v[42:45], v[28:31]
	s_cselect_b32 s22, s22, 0x6000
	v_add_u32_e32 v32, s22, v38
	s_mov_b64 s[22:23], 0x3500100
	v_mfma_f32_16x16x32_bf16 v[24:27], v[58:61], v[46:49], v[24:27]
	v_lshl_add_u64 v[66:67], v[66:67], 0, s[22:23]
	s_mov_b64 s[22:23], 0x10d2c100
	v_add_u32_e32 v41, 0x2000, v32
	v_lshl_add_u64 v[68:69], v[70:71], 0, s[22:23]
	v_readfirstlane_b32 s22, v32
	s_mov_b32 m0, s22
	s_nop 0
	global_load_lds_dwordx4 v[68:69], off
	v_mfma_f32_16x16x32_bf16 v[16:19], v[58:61], v[50:53], v[16:19]
	v_mfma_f32_16x16x32_bf16 v[8:11], v[58:61], v[54:57], v[8:11]
	s_mov_b64 s[22:23], 0x10d84100
	v_add_u32_e32 v32, 0x1000, v32
	v_lshl_add_u64 v[58:59], v[70:71], 0, s[22:23]
	v_readfirstlane_b32 s22, v32
	s_mov_b32 m0, s22
	s_nop 0
	global_load_lds_dwordx4 v[58:59], off
	v_mfma_f32_16x16x32_bf16 v[20:23], v[62:65], v[42:45], v[20:23]
	v_mfma_f32_16x16x32_bf16 v[12:15], v[62:65], v[46:49], v[12:15]
	v_readfirstlane_b32 s22, v41
	s_mov_b32 m0, s22
	s_nop 0
	global_load_lds_dwordx4 v[66:67], off
	v_mfma_f32_16x16x32_bf16 v[4:7], v[62:65], v[50:53], v[4:7]
	v_mfma_f32_16x16x32_bf16 v[0:3], v[62:65], v[54:57], v[0:3]
	s_setprio 0
	s_add_i32 s22, s21, 1
	s_cmp_lg_u32 s21, 2
	s_cselect_b32 s21, s22, 0
	s_add_u32 s10, s10, 0x100
	s_addc_u32 s11, s11, 0
	s_cmpk_lg_i32 s10, 0xa00
	s_cbranch_scc1 .LBB0_26
	s_waitcnt vmcnt(3)
	v_add_u32_e32 v32, 0, v39
	s_waitcnt lgkmcnt(0)
	s_barrier
	ds_read_b128 v[34:37], v32 offset:24576
	ds_read_b128 v[42:45], v32 offset:25600
	ds_read_b128 v[46:49], v32 offset:26624
	ds_read_b128 v[50:53], v32 offset:27648
	v_add_u32_e32 v58, 0, v40
	ds_read_b128 v[38:41], v58 offset:32768
	ds_read_b128 v[54:57], v58 offset:33792
	s_setprio 1
	s_waitcnt lgkmcnt(0)
	v_mfma_f32_16x16x32_bf16 v[28:31], v[38:41], v[34:37], v[28:31]
	v_mfma_f32_16x16x32_bf16 v[24:27], v[38:41], v[42:45], v[24:27]
	v_mfma_f32_16x16x32_bf16 v[16:19], v[38:41], v[46:49], v[16:19]
	v_mfma_f32_16x16x32_bf16 v[8:11], v[38:41], v[50:53], v[8:11]
	v_mfma_f32_16x16x32_bf16 v[20:23], v[54:57], v[34:37], v[20:23]
	v_mfma_f32_16x16x32_bf16 v[34:37], v[54:57], v[42:45], v[12:15]
	v_mfma_f32_16x16x32_bf16 v[38:41], v[54:57], v[46:49], v[4:7]
	v_mfma_f32_16x16x32_bf16 v[0:3], v[54:57], v[50:53], v[0:3]
	s_setprio 0
	s_waitcnt vmcnt(0)
	s_waitcnt lgkmcnt(0)
	s_barrier
	ds_read_b128 v[4:7], v58 offset:8192
	ds_read_b128 v[42:45], v32
	ds_read_b128 v[46:49], v32 offset:1024
	ds_read_b128 v[50:53], v32 offset:2048
	ds_read_b128 v[54:57], v32 offset:3072
	ds_read_b128 v[58:61], v58 offset:9216
	s_setprio 1
	s_waitcnt lgkmcnt(4)
	v_mfma_f32_16x16x32_bf16 v[28:31], v[4:7], v[42:45], v[28:31]
	s_waitcnt lgkmcnt(3)
	v_mfma_f32_16x16x32_bf16 v[24:27], v[4:7], v[46:49], v[24:27]
	s_waitcnt lgkmcnt(2)
	v_mfma_f32_16x16x32_bf16 v[12:15], v[4:7], v[50:53], v[16:19]
	s_waitcnt lgkmcnt(1)
	v_mfma_f32_16x16x32_bf16 v[4:7], v[4:7], v[54:57], v[8:11]
	s_waitcnt lgkmcnt(0)
	v_mfma_f32_16x16x32_bf16 v[42:45], v[58:61], v[42:45], v[20:23]
	v_mfma_f32_16x16x32_bf16 v[34:37], v[58:61], v[46:49], v[34:37]
	v_mfma_f32_16x16x32_bf16 v[8:11], v[58:61], v[50:53], v[38:41]
	v_mfma_f32_16x16x32_bf16 v[0:3], v[58:61], v[54:57], v[0:3]
	s_setprio 0
	v_mov_b32_e32 v17, v186
	s_waitcnt lgkmcnt(0)
	s_barrier
;     __device__ __forceinline__ float* mod() const { return (float*)(ws + OFF_mod); }
; DEV int tid_opaque() { int t = threadIdx.x; asm volatile("" : "+v"(t)); return t; }
; DEV void resid_small(const Params& p, int l, int unit, const bf16_t* A, int K, const bf16_t* W, int gate_off, char* smem) {
;     ...
;     const int t = tid_opaque(), lane = t & 63, wid = t >> 6, wm = wid >> 1, wn = wid & 1, fr = lane & 15, fq = lane >> 4;
;     const int rbase = (MT - 1) * 128 + wm * 64 + fr, c0 = nt * 64 + wn * 32 + fq * 4;
; #pragma unroll
;     for (int mi = 0; mi < 4; ++mi) {
;         const int row = rbase + mi * 16;
;         const float* gt = p.mod() + (size_t)(l * 9 + mod_index(row)) * 6144 + gate_off + c0;
;         float* dst = (float*)(p.ws + OFF_part) + ((size_t)kq * 128 + (row - SEQ)) * 1024 + c0;
; #pragma unroll
;         for (int ni = 0; ni < 2; ++ni) {
;             const f32x4 g4 = *(const f32x4*)(gt + ni * 16);
;             *(f32x4*)(dst + ni * 16) = g4 * acc[mi][ni];
;         }
;     }
	s_lshl_b32 s10, s20, 6
	v_ashrrev_i32_e32 v16, 1, v17
	v_and_b32_e32 v20, 0xffffffc0, v16
	v_and_or_b32 v16, v17, 15, v20
	v_lshrrev_b32_e32 v18, 1, v17
	v_lshrrev_b32_e32 v17, 2, v17
	v_and_b32_e32 v18, 32, v18
	v_and_b32_e32 v17, 12, v17
	v_add_u32_e32 v21, 0x4000, v16
	v_or3_b32 v18, v18, s10, v17
	v_lshrrev_b32_e32 v17, 4, v20
	s_movk_i32 s20, 0x3fff
	v_or_b32_e32 v17, 1, v17
	v_cmp_lt_i32_e32 vcc, s20, v21
	v_ashrrev_i32_e32 v19, 31, v18
	v_readlane_b32 s22, v252, 27
	v_cndmask_b32_e32 v17, 0, v17, vcc
	v_add_u32_e32 v17, s16, v17
	v_mov_b64_e32 v[20:21], s[6:7]
	v_readlane_b32 s23, v252, 28
	s_lshl_b32 s22, s19, 7
	v_mad_i64_i32 v[22:23], s[10:11], v17, s33, v[20:21]
	v_lshlrev_b64 v[18:19], 2, v[18:19]
	v_ashrrev_i32_e32 v17, 31, v16
	v_lshl_add_u64 v[22:23], v[22:23], 0, v[18:19]
	s_mov_b64 s[28:29], 0x5000
	v_lshl_add_u64 v[38:39], v[16:17], 0, s[22:23]
	s_movk_i32 s19, 0x5000
	v_lshl_add_u64 v[46:47], v[22:23], 0, s[28:29]
	v_lshlrev_b64 v[38:39], 12, v[38:39]
	v_add_co_u32_e32 v22, vcc, s19, v22
	v_lshl_add_u64 v[38:39], s[8:9], 0, v[38:39]
	s_nop 0
	v_addc_co_u32_e32 v23, vcc, 0, v23, vcc
	v_lshl_add_u64 v[48:49], v[38:39], 0, v[18:19]
	flat_load_dwordx4 v[38:41], v[22:23]
	v_or_b32_e32 v22, 16, v16
	v_add_u32_e32 v17, 0x4010, v16
	v_lshrrev_b32_e32 v23, 4, v22
	v_add_u32_e32 v23, 1, v23
	v_cmp_lt_i32_e32 vcc, s20, v17
	s_waitcnt vmcnt(0) lgkmcnt(0)
	v_pk_mul_f32 v[30:31], v[30:31], v[40:41]
	v_pk_mul_f32 v[28:29], v[28:29], v[38:39]
	flat_store_dwordx4 v[48:49], v[28:31]
	flat_load_dwordx4 v[28:31], v[46:47] offset:64
	v_cndmask_b32_e32 v17, 0, v23, vcc
	v_ashrrev_i32_e32 v23, 31, v22
	v_add_u32_e32 v17, s16, v17
	v_lshl_add_u64 v[22:23], v[22:23], 0, s[22:23]
	v_lshlrev_b64 v[22:23], 12, v[22:23]
	v_lshl_add_u64 v[22:23], s[8:9], 0, v[22:23]
	v_lshl_add_u64 v[40:41], v[22:23], 0, v[18:19]
	s_waitcnt vmcnt(0) lgkmcnt(0)
	v_pk_mul_f32 v[30:31], v[44:45], v[30:31]
	v_pk_mul_f32 v[28:29], v[42:43], v[28:29]
	flat_store_dwordx4 v[48:49], v[28:31] offset:64
	s_nop 1
	v_mad_i64_i32 v[28:29], s[10:11], v17, s33, v[20:21]
	v_lshl_add_u64 v[28:29], v[28:29], 0, v[18:19]
	v_add_co_u32_e32 v22, vcc, s19, v28
	v_lshl_add_u64 v[38:39], v[28:29], 0, s[28:29]
	s_nop 0
	v_addc_co_u32_e32 v23, vcc, 0, v29, vcc
	flat_load_dwordx4 v[28:31], v[22:23]
	v_add_u32_e32 v17, 0x4020, v16
	v_cmp_lt_i32_e32 vcc, s20, v17
	s_waitcnt vmcnt(0) lgkmcnt(0)
	v_pk_mul_f32 v[26:27], v[26:27], v[30:31]
	v_pk_mul_f32 v[24:25], v[24:25], v[28:29]
	flat_store_dwordx4 v[40:41], v[24:27]
	flat_load_dwordx4 v[22:25], v[38:39] offset:64
	s_waitcnt vmcnt(0) lgkmcnt(0)
	v_pk_mul_f32 v[22:23], v[34:35], v[22:23]
	v_pk_mul_f32 v[24:25], v[36:37], v[24:25]
	flat_store_dwordx4 v[40:41], v[22:25] offset:64
	s_nop 1
	v_or_b32_e32 v22, 32, v16
	v_lshrrev_b32_e32 v23, 4, v22
	v_or_b32_e32 v23, 1, v23
	v_cndmask_b32_e32 v17, 0, v23, vcc
	v_ashrrev_i32_e32 v23, 31, v22
	v_add_u32_e32 v17, s16, v17
	v_lshl_add_u64 v[22:23], v[22:23], 0, s[22:23]
	v_mad_i64_i32 v[24:25], s[10:11], v17, s33, v[20:21]
	v_lshlrev_b64 v[22:23], 12, v[22:23]
	v_lshl_add_u64 v[24:25], v[24:25], 0, v[18:19]
	v_lshl_add_u64 v[22:23], s[8:9], 0, v[22:23]
	v_lshl_add_u64 v[28:29], v[22:23], 0, v[18:19]
	v_add_co_u32_e32 v22, vcc, s19, v24
	v_lshl_add_u64 v[26:27], v[24:25], 0, s[28:29]
	s_nop 0
	v_addc_co_u32_e32 v23, vcc, 0, v25, vcc
	flat_load_dwordx4 v[22:25], v[22:23]
	s_waitcnt vmcnt(0) lgkmcnt(0)
	v_pk_mul_f32 v[14:15], v[14:15], v[24:25]
	v_pk_mul_f32 v[12:13], v[12:13], v[22:23]
	flat_store_dwordx4 v[28:29], v[12:15]
	flat_load_dwordx4 v[12:15], v[26:27] offset:64
	s_waitcnt vmcnt(0) lgkmcnt(0)
	v_pk_mul_f32 v[10:11], v[10:11], v[14:15]
	v_pk_mul_f32 v[8:9], v[8:9], v[12:13]
	flat_store_dwordx4 v[28:29], v[8:11] offset:64
	s_nop 1
	v_or_b32_e32 v8, 48, v16
	v_add_u32_e32 v9, 0x4030, v16
	v_lshrrev_b32_e32 v10, 4, v8
	v_add_u32_e32 v10, 1, v10
	v_cmp_lt_i32_e32 vcc, s20, v9
	s_nop 1
	v_cndmask_b32_e32 v9, 0, v10, vcc
	v_add_u32_e32 v9, s16, v9
	v_mad_i64_i32 v[10:11], s[10:11], v9, s33, v[20:21]
	v_ashrrev_i32_e32 v9, 31, v8
	v_lshl_add_u64 v[8:9], v[8:9], 0, s[22:23]
	v_lshlrev_b64 v[8:9], 12, v[8:9]
	v_lshl_add_u64 v[10:11], v[10:11], 0, v[18:19]
	v_lshl_add_u64 v[8:9], s[8:9], 0, v[8:9]
	v_lshl_add_u64 v[14:15], v[8:9], 0, v[18:19]
	v_add_co_u32_e32 v8, vcc, s19, v10
	v_lshl_add_u64 v[12:13], v[10:11], 0, s[28:29]
	s_nop 0
	v_addc_co_u32_e32 v9, vcc, 0, v11, vcc
	flat_load_dwordx4 v[8:11], v[8:9]
	s_mov_b32 s11, s23
	v_writelane_b32 v252, s10, 27
	s_waitcnt vmcnt(0) lgkmcnt(0)
	v_pk_mul_f32 v[6:7], v[6:7], v[10:11]
	v_pk_mul_f32 v[4:5], v[4:5], v[8:9]
	flat_store_dwordx4 v[14:15], v[4:7]
	flat_load_dwordx4 v[4:7], v[12:13] offset:64
	v_writelane_b32 v252, s11, 28
	v_readlane_b32 s10, v254, 4
	s_add_i32 s18, s18, s10
	s_add_i32 s17, s17, s10
	s_cmp_lt_i32 s18, 64
	v_readlane_b32 s11, v254, 5
	s_waitcnt vmcnt(0) lgkmcnt(0)
	v_pk_mul_f32 v[2:3], v[2:3], v[6:7]
	v_pk_mul_f32 v[0:1], v[0:1], v[4:5]
	flat_store_dwordx4 v[14:15], v[0:3] offset:64
	s_cbranch_scc1 .LBB0_25

; DEV int tid_opaque() { int t = threadIdx.x; asm volatile("" : "+v"(t)); return t; }
; #define RAW_BARRIER() do { asm volatile("s_waitcnt lgkmcnt(0)" ::: "memory"); __builtin_amdgcn_s_barrier(); } while (0)
; #define GLDS_TILE(kt, st) do { _Pragma("unroll") for (int _i = 0; _i < NP; ++_i) GLDS_PIECE(_i, kt, st); } while (0)
;     constexpr int BROWS = 32 * NI, STAGE = 8192 + BROWS * 64, NB = BROWS / 64;
;     const int t = tid_opaque(), lane = t & 63, wid = t >> 6, wm = wid >> 1, wn = wid & 1, fr = lane & 15, fq = lane >> 4;
;     const int nk = K >> 5;
;     const int srow = wid * 16 + (lane >> 2), sch = (lane & 3) ^ ((0 - (lane >> 4)) & 3);
;     const bf16_t* ga = A + (size_t)srow * lda + sch * 8;
;     const bf16_t* gb = B + (size_t)srow * ldb + sch * 8;
;     const int rd = fr * 64 + ((fq ^ ((0 - (fr >> 2)) & 3)) << 4);
;     const int rda = (wm * 64) * 64 + rd, rdb = 8192 + (wn * 16 * NI) * 64 + rd;
;     ...
;     constexpr int NH = NI >= 4 ? NI / 2 : NI;
;     constexpr int NP = 2 + NB, IVL = (4 * NI) / NP;
;     RAW_BARRIER();
;     GLDS_TILE(0, 0);
;     GLDS_TILE(1, 1);
;     int st = 0;
;     for (int kt = 0; kt < nk - 1; ++kt) {
;         if (NI == 8) asm volatile("s_waitcnt vmcnt(6)" ::: "memory"); else if (NI == 4) asm volatile("s_waitcnt vmcnt(4)" ::: "memory"); else asm volatile("s_waitcnt vmcnt(3)" ::: "memory");
;         RAW_BARRIER();
;         const int s2 = st >= 1 ? st - 1 : 2;
;         const bool ld = kt + 2 < nk;
;         STEP_TILE(st, ld, kt + 2, s2);
;         st = st == 2 ? 0 : st + 1;
;     }
.LBB0_98:
	s_and_b32 s14, s13, 3
	s_ashr_i32 s6, s13, 2
	s_lshl_b32 s15, s14, 9
	s_add_u32 s16, s10, s15
	s_addc_u32 s17, s11, 0
	s_ashr_i32 s7, s6, 31
	s_lshl_b64 s[18:19], s[6:7], 17
	v_mov_b32_e32 v8, v186
	s_add_u32 s7, s8, s18
	s_addc_u32 s19, s9, s19
	v_ashrrev_i32_e32 v9, 6, v8
	v_bfe_u32 v10, v8, 4, 2
	v_bfe_u32 v0, v8, 2, 4
	v_lshl_or_b32 v0, v9, 4, v0
	v_sub_u32_e32 v1, 0, v10
	s_add_u32 s18, s7, s15
	v_xor_b32_e32 v4, v8, v1
	v_ashrrev_i32_e32 v1, 31, v0
	s_addc_u32 s19, s19, 0
	v_lshlrev_b64 v[2:3], 11, v[0:1]
	v_lshlrev_b32_e32 v4, 4, v4
	v_lshl_add_u64 v[0:1], s[16:17], 0, v[2:3]
	v_and_b32_e32 v32, 48, v4
	v_lshl_add_u64 v[2:3], s[18:19], 0, v[2:3]
	v_lshl_add_u64 v[0:1], v[0:1], 0, v[32:33]
	v_lshl_add_u64 v[2:3], v[2:3], 0, v[32:33]
	v_lshl_add_u32 v32, v9, 10, 0
	v_add_u32_e32 v7, 0x1000, v32
	v_readfirstlane_b32 s19, v32
	v_add_u32_e32 v6, 0x2000, v32
	s_mov_b32 m0, s19
	v_readfirstlane_b32 s18, v7
	s_waitcnt lgkmcnt(0)
	s_barrier
	global_load_lds_dwordx4 v[0:1], off
	v_lshl_add_u64 v[4:5], v[0:1], 0, s[40:41]
	s_mov_b32 m0, s18
	v_readfirstlane_b32 s17, v6
	v_add_u32_e32 v11, 0x3000, v32
	global_load_lds_dwordx4 v[4:5], off
	s_mov_b32 m0, s17
	v_readfirstlane_b32 s16, v11
	v_add_u32_e32 v11, 0x4000, v32
	global_load_lds_dwordx4 v[2:3], off
	v_add_u32_e32 v12, 0x5000, v32
	v_lshl_add_u64 v[6:7], v[0:1], 0, 64
	s_mov_b32 m0, s16
	v_readfirstlane_b32 s15, v11
	global_load_lds_dwordx4 v[6:7], off
	v_lshl_add_u64 v[6:7], v[0:1], 0, s[42:43]
	s_mov_b32 m0, s15
	v_readfirstlane_b32 s7, v12
	v_lshl_add_u64 v[4:5], v[2:3], 0, 64
	global_load_lds_dwordx4 v[6:7], off
	s_mov_b32 m0, s7
	v_lshlrev_b32_e32 v6, 11, v9
	global_load_lds_dwordx4 v[4:5], off
	v_lshrrev_b32_e32 v5, 2, v8
	v_lshlrev_b32_e32 v4, 6, v8
	v_sub_u32_e32 v5, 0, v5
	v_and_b32_e32 v4, 0x3c0, v4
	v_bitop3_b32 v5, v10, v5, 3 bitop3:0x78
	v_lshl_or_b32 v4, v5, 4, v4
	v_lshlrev_b32_e32 v5, 5, v8
	v_and_or_b32 v5, v5, s30, v4
	s_waitcnt vmcnt(3)
	s_waitcnt vmcnt(0)
	v_add_u32_e32 v66, 0, v5
	v_and_or_b32 v20, v6, s34, v4
	s_waitcnt lgkmcnt(0)
	s_barrier
	ds_read_b128 v[4:7], v66
	ds_read_b128 v[8:11], v66 offset:1024
	ds_read_b128 v[12:15], v66 offset:2048
	ds_read_b128 v[16:19], v66 offset:3072
	v_add_u32_e32 v67, 0, v20
	ds_read_b128 v[20:23], v67 offset:8192
	ds_read_b128 v[24:27], v67 offset:9216
	s_setprio 1
	v_add_u32_e32 v40, 0x6000, v32
	s_waitcnt lgkmcnt(0)
	v_mfma_f32_16x16x32_bf16 v[28:31], v[20:23], v[4:7], 0
	v_lshl_add_u64 v[42:43], v[2:3], 0, s[38:39]
	v_add_u32_e32 v46, 0x8000, v32
	v_lshl_add_u64 v[38:39], v[0:1], 0, s[38:39]
	v_mfma_f32_16x16x32_bf16 v[34:37], v[20:23], v[8:11], 0
	v_readfirstlane_b32 s22, v40
	s_mov_b32 m0, s22
	s_nop 0
	global_load_lds_dwordx4 v[38:39], off
	v_mfma_f32_16x16x32_bf16 v[38:41], v[20:23], v[12:15], 0
	v_mfma_f32_16x16x32_bf16 v[20:23], v[20:23], v[16:19], 0
	v_add_u32_e32 v32, 0x7000, v32
	v_lshl_add_u64 v[44:45], v[0:1], 0, s[46:47]
	v_readfirstlane_b32 s23, v32
	s_mov_b32 m0, s23
	s_nop 0
	global_load_lds_dwordx4 v[44:45], off
	v_mfma_f32_16x16x32_bf16 v[4:7], v[24:27], v[4:7], 0
	v_mfma_f32_16x16x32_bf16 v[8:11], v[24:27], v[8:11], 0
	v_readfirstlane_b32 s28, v46
	s_mov_b32 m0, s28
	s_nop 0
	global_load_lds_dwordx4 v[42:43], off
	v_mfma_f32_16x16x32_bf16 v[12:15], v[24:27], v[12:15], 0
	v_mfma_f32_16x16x32_bf16 v[16:19], v[24:27], v[16:19], 0
	s_setprio 0
	s_waitcnt vmcnt(3)
	s_waitcnt lgkmcnt(0)
	s_barrier
	ds_read_b128 v[54:57], v67 offset:20480
	ds_read_b128 v[24:27], v66 offset:12288
	ds_read_b128 v[42:45], v66 offset:13312
	ds_read_b128 v[46:49], v66 offset:14336
	ds_read_b128 v[50:53], v66 offset:15360
	ds_read_b128 v[58:61], v67 offset:21504
	s_setprio 1
	s_waitcnt lgkmcnt(4)
	v_mfma_f32_16x16x32_bf16 v[28:31], v[54:57], v[24:27], v[28:31]
	v_lshl_add_u64 v[62:63], v[2:3], 0, s[48:49]
	v_lshl_add_u64 v[64:65], v[0:1], 0, s[48:49]
	s_waitcnt lgkmcnt(3)
	v_mfma_f32_16x16x32_bf16 v[34:37], v[54:57], v[42:45], v[34:37]
	s_mov_b32 m0, s19
	s_nop 0
	global_load_lds_dwordx4 v[64:65], off
	s_waitcnt lgkmcnt(2)
	v_mfma_f32_16x16x32_bf16 v[38:41], v[54:57], v[46:49], v[38:41]
	s_waitcnt lgkmcnt(1)
	v_mfma_f32_16x16x32_bf16 v[20:23], v[54:57], v[50:53], v[20:23]
	s_mov_b64 s[20:21], 0x200c0
	v_lshl_add_u64 v[54:55], v[0:1], 0, s[20:21]
	s_mov_b32 m0, s18
	s_nop 0
	global_load_lds_dwordx4 v[54:55], off
	s_waitcnt lgkmcnt(0)
	v_mfma_f32_16x16x32_bf16 v[4:7], v[58:61], v[24:27], v[4:7]
	v_mfma_f32_16x16x32_bf16 v[8:11], v[58:61], v[42:45], v[8:11]
	s_mov_b32 m0, s17
	s_nop 0
	global_load_lds_dwordx4 v[62:63], off
	v_mfma_f32_16x16x32_bf16 v[12:15], v[58:61], v[46:49], v[12:15]
	v_mfma_f32_16x16x32_bf16 v[16:19], v[58:61], v[50:53], v[16:19]
	s_setprio 0
	s_waitcnt vmcnt(3)
	s_waitcnt lgkmcnt(0)
	s_barrier
	ds_read_b128 v[54:57], v67 offset:32768
	ds_read_b128 v[24:27], v66 offset:24576
	ds_read_b128 v[42:45], v66 offset:25600
	ds_read_b128 v[46:49], v66 offset:26624
	ds_read_b128 v[50:53], v66 offset:27648
	ds_read_b128 v[58:61], v67 offset:33792
	s_setprio 1
	s_waitcnt lgkmcnt(4)
	v_mfma_f32_16x16x32_bf16 v[28:31], v[54:57], v[24:27], v[28:31]
	v_lshl_add_u64 v[62:63], v[2:3], 0, s[50:51]
	v_lshl_add_u64 v[64:65], v[0:1], 0, s[50:51]
	s_waitcnt lgkmcnt(3)
	v_mfma_f32_16x16x32_bf16 v[34:37], v[54:57], v[42:45], v[34:37]
	s_mov_b32 m0, s16
	s_nop 0
	global_load_lds_dwordx4 v[64:65], off
	s_waitcnt lgkmcnt(2)
	v_mfma_f32_16x16x32_bf16 v[38:41], v[54:57], v[46:49], v[38:41]
	s_waitcnt lgkmcnt(1)
	v_mfma_f32_16x16x32_bf16 v[20:23], v[54:57], v[50:53], v[20:23]
	s_mov_b64 s[20:21], 0x20100
	v_lshl_add_u64 v[54:55], v[0:1], 0, s[20:21]
	s_mov_b32 m0, s15
	s_nop 0
	global_load_lds_dwordx4 v[54:55], off
	s_waitcnt lgkmcnt(0)
	v_mfma_f32_16x16x32_bf16 v[4:7], v[58:61], v[24:27], v[4:7]
	v_mfma_f32_16x16x32_bf16 v[8:11], v[58:61], v[42:45], v[8:11]
	s_mov_b32 m0, s7
	s_nop 0
	global_load_lds_dwordx4 v[62:63], off
	v_mfma_f32_16x16x32_bf16 v[12:15], v[58:61], v[46:49], v[12:15]
	v_mfma_f32_16x16x32_bf16 v[16:19], v[58:61], v[50:53], v[16:19]
	s_setprio 0
	s_waitcnt vmcnt(3)
	s_waitcnt lgkmcnt(0)
	s_barrier
; #define RAW_BARRIER() do { asm volatile("s_waitcnt lgkmcnt(0)" ::: "memory"); __builtin_amdgcn_s_barrier(); } while (0)
; #define GLDS_TILE(kt, st) do { _Pragma("unroll") for (int _i = 0; _i < NP; ++_i) GLDS_PIECE(_i, kt, st); } while (0)
;     ...
;     constexpr int NH = NI >= 4 ? NI / 2 : NI;
;     constexpr int NP = 2 + NB, IVL = (4 * NI) / NP;
;     RAW_BARRIER();
;     GLDS_TILE(0, 0);
;     GLDS_TILE(1, 1);
;     int st = 0;
;     for (int kt = 0; kt < nk - 1; ++kt) {
;         if (NI == 8) asm volatile("s_waitcnt vmcnt(6)" ::: "memory"); else if (NI == 4) asm volatile("s_waitcnt vmcnt(4)" ::: "memory"); else asm volatile("s_waitcnt vmcnt(3)" ::: "memory");
;         RAW_BARRIER();
;         const int s2 = st >= 1 ? st - 1 : 2;
;         const bool ld = kt + 2 < nk;
;         STEP_TILE(st, ld, kt + 2, s2);
;         st = st == 2 ? 0 : st + 1;
;     }
;     asm volatile("s_waitcnt vmcnt(0)" ::: "memory");
;     RAW_BARRIER();
;     STEP_TILE(st, false, 0, 0);
;     RAW_BARRIER();
	ds_read_b128 v[54:57], v67 offset:8192
	ds_read_b128 v[24:27], v66
	ds_read_b128 v[42:45], v66 offset:1024
	ds_read_b128 v[46:49], v66 offset:2048
	ds_read_b128 v[50:53], v66 offset:3072
	ds_read_b128 v[58:61], v67 offset:9216
	s_setprio 1
	s_waitcnt lgkmcnt(4)
	v_mfma_f32_16x16x32_bf16 v[28:31], v[54:57], v[24:27], v[28:31]
	v_lshl_add_u64 v[62:63], v[2:3], 0, s[52:53]
	v_lshl_add_u64 v[64:65], v[0:1], 0, s[52:53]
	s_waitcnt lgkmcnt(3)
	v_mfma_f32_16x16x32_bf16 v[34:37], v[54:57], v[42:45], v[34:37]
	s_mov_b32 m0, s22
	s_nop 0
	global_load_lds_dwordx4 v[64:65], off
	s_waitcnt lgkmcnt(2)
	v_mfma_f32_16x16x32_bf16 v[38:41], v[54:57], v[46:49], v[38:41]
	s_waitcnt lgkmcnt(1)
	v_mfma_f32_16x16x32_bf16 v[20:23], v[54:57], v[50:53], v[20:23]
	s_mov_b64 s[20:21], 0x20140
	v_lshl_add_u64 v[54:55], v[0:1], 0, s[20:21]
	s_mov_b32 m0, s23
	s_nop 0
	global_load_lds_dwordx4 v[54:55], off
	s_waitcnt lgkmcnt(0)
	v_mfma_f32_16x16x32_bf16 v[4:7], v[58:61], v[24:27], v[4:7]
	v_mfma_f32_16x16x32_bf16 v[8:11], v[58:61], v[42:45], v[8:11]
	s_mov_b32 m0, s28
	s_nop 0
	global_load_lds_dwordx4 v[62:63], off
	v_mfma_f32_16x16x32_bf16 v[12:15], v[58:61], v[46:49], v[12:15]
	v_mfma_f32_16x16x32_bf16 v[16:19], v[58:61], v[50:53], v[16:19]
	s_setprio 0
	s_waitcnt vmcnt(3)
	s_waitcnt lgkmcnt(0)
	s_barrier
	ds_read_b128 v[54:57], v67 offset:20480
	ds_read_b128 v[24:27], v66 offset:12288
	ds_read_b128 v[42:45], v66 offset:13312
	ds_read_b128 v[46:49], v66 offset:14336
	ds_read_b128 v[50:53], v66 offset:15360
	ds_read_b128 v[58:61], v67 offset:21504
	s_setprio 1
	s_waitcnt lgkmcnt(4)
	v_mfma_f32_16x16x32_bf16 v[28:31], v[54:57], v[24:27], v[28:31]
	v_lshl_add_u64 v[62:63], v[2:3], 0, s[54:55]
	v_lshl_add_u64 v[64:65], v[0:1], 0, s[54:55]
	s_waitcnt lgkmcnt(3)
	v_mfma_f32_16x16x32_bf16 v[34:37], v[54:57], v[42:45], v[34:37]
	s_mov_b32 m0, s19
	s_nop 0
	global_load_lds_dwordx4 v[64:65], off
	s_waitcnt lgkmcnt(2)
	v_mfma_f32_16x16x32_bf16 v[38:41], v[54:57], v[46:49], v[38:41]
	s_waitcnt lgkmcnt(1)
	v_mfma_f32_16x16x32_bf16 v[20:23], v[54:57], v[50:53], v[20:23]
	s_mov_b64 s[20:21], 0x20180
	v_lshl_add_u64 v[54:55], v[0:1], 0, s[20:21]
	s_mov_b32 m0, s18
	s_nop 0
	global_load_lds_dwordx4 v[54:55], off
	s_waitcnt lgkmcnt(0)
	v_mfma_f32_16x16x32_bf16 v[4:7], v[58:61], v[24:27], v[4:7]
	v_mfma_f32_16x16x32_bf16 v[8:11], v[58:61], v[42:45], v[8:11]
	s_mov_b32 m0, s17
	s_nop 0
	global_load_lds_dwordx4 v[62:63], off
	v_mfma_f32_16x16x32_bf16 v[12:15], v[58:61], v[46:49], v[12:15]
	v_mfma_f32_16x16x32_bf16 v[16:19], v[58:61], v[50:53], v[16:19]
	s_setprio 0
	s_waitcnt vmcnt(3)
	s_waitcnt lgkmcnt(0)
	s_barrier
	ds_read_b128 v[54:57], v67 offset:32768
	ds_read_b128 v[24:27], v66 offset:24576
	ds_read_b128 v[42:45], v66 offset:25600
	ds_read_b128 v[46:49], v66 offset:26624
	ds_read_b128 v[50:53], v66 offset:27648
	ds_read_b128 v[58:61], v67 offset:33792
	s_setprio 1
	s_waitcnt lgkmcnt(4)
	v_mfma_f32_16x16x32_bf16 v[28:31], v[54:57], v[24:27], v[28:31]
	v_lshl_add_u64 v[62:63], v[2:3], 0, s[56:57]
	v_lshl_add_u64 v[2:3], v[0:1], 0, s[56:57]
	s_waitcnt lgkmcnt(3)
	v_mfma_f32_16x16x32_bf16 v[34:37], v[54:57], v[42:45], v[34:37]
	s_mov_b32 m0, s16
	s_nop 0
	global_load_lds_dwordx4 v[2:3], off
	s_waitcnt lgkmcnt(2)
	v_mfma_f32_16x16x32_bf16 v[38:41], v[54:57], v[46:49], v[38:41]
	s_waitcnt lgkmcnt(1)
	v_mfma_f32_16x16x32_bf16 v[20:23], v[54:57], v[50:53], v[20:23]
	s_mov_b64 s[16:17], 0x201c0
	v_lshl_add_u64 v[0:1], v[0:1], 0, s[16:17]
	s_mov_b32 m0, s15
	s_nop 0
	global_load_lds_dwordx4 v[0:1], off
	s_waitcnt lgkmcnt(0)
	v_mfma_f32_16x16x32_bf16 v[0:3], v[58:61], v[24:27], v[4:7]
	v_mfma_f32_16x16x32_bf16 v[4:7], v[58:61], v[42:45], v[8:11]
	s_mov_b32 m0, s7
	s_nop 0
	global_load_lds_dwordx4 v[62:63], off
	v_mfma_f32_16x16x32_bf16 v[8:11], v[58:61], v[46:49], v[12:15]
	v_mfma_f32_16x16x32_bf16 v[12:15], v[58:61], v[50:53], v[16:19]
	s_setprio 0
	s_waitcnt vmcnt(3)
	s_waitcnt lgkmcnt(0)
	s_barrier
	s_nop 0
	ds_read_b128 v[16:19], v66
	ds_read_b128 v[24:27], v66 offset:1024
	ds_read_b128 v[42:45], v66 offset:2048
	ds_read_b128 v[46:49], v66 offset:3072
	ds_read_b128 v[50:53], v67 offset:8192
	ds_read_b128 v[54:57], v67 offset:9216
	s_setprio 1
	s_waitcnt lgkmcnt(0)
	v_mfma_f32_16x16x32_bf16 v[28:31], v[50:53], v[16:19], v[28:31]
	v_mfma_f32_16x16x32_bf16 v[34:37], v[50:53], v[24:27], v[34:37]
	v_mfma_f32_16x16x32_bf16 v[38:41], v[50:53], v[42:45], v[38:41]
	v_mfma_f32_16x16x32_bf16 v[20:23], v[50:53], v[46:49], v[20:23]
	v_mfma_f32_16x16x32_bf16 v[0:3], v[54:57], v[16:19], v[0:3]
	v_mfma_f32_16x16x32_bf16 v[16:19], v[54:57], v[24:27], v[4:7]
	v_mfma_f32_16x16x32_bf16 v[8:11], v[54:57], v[42:45], v[8:11]
	v_mfma_f32_16x16x32_bf16 v[24:27], v[54:57], v[46:49], v[12:15]
	s_setprio 0
	s_waitcnt vmcnt(0)
	s_waitcnt lgkmcnt(0)
	s_barrier
	ds_read_b128 v[4:7], v67 offset:20480
	ds_read_b128 v[42:45], v66 offset:12288
	ds_read_b128 v[46:49], v66 offset:13312
	ds_read_b128 v[50:53], v66 offset:14336
	ds_read_b128 v[54:57], v66 offset:15360
	ds_read_b128 v[58:61], v67 offset:21504
	s_setprio 1
	s_waitcnt lgkmcnt(4)
	v_mfma_f32_16x16x32_bf16 v[28:31], v[4:7], v[42:45], v[28:31]
	s_waitcnt lgkmcnt(3)
	v_mfma_f32_16x16x32_bf16 v[34:37], v[4:7], v[46:49], v[34:37]
	s_waitcnt lgkmcnt(2)
	v_mfma_f32_16x16x32_bf16 v[12:15], v[4:7], v[50:53], v[38:41]
	s_waitcnt lgkmcnt(1)
	v_mfma_f32_16x16x32_bf16 v[4:7], v[4:7], v[54:57], v[20:23]
	s_waitcnt lgkmcnt(0)
	v_mfma_f32_16x16x32_bf16 v[38:41], v[58:61], v[42:45], v[0:3]
	v_mfma_f32_16x16x32_bf16 v[42:45], v[58:61], v[46:49], v[16:19]
	v_mfma_f32_16x16x32_bf16 v[8:11], v[58:61], v[50:53], v[8:11]
	v_mfma_f32_16x16x32_bf16 v[0:3], v[58:61], v[54:57], v[24:27]
	s_setprio 0
	v_mov_b32_e32 v17, v186
	s_waitcnt lgkmcnt(0)
	s_barrier
;     __device__ __forceinline__ float* mod() const { return (float*)(ws + OFF_mod); }
; DEV int tid_opaque() { int t = threadIdx.x; asm volatile("" : "+v"(t)); return t; }
; DEV void resid_small(const Params& p, int l, int unit, const bf16_t* A, int K, const bf16_t* W, int gate_off, char* smem) {
;     ...
;     const int t = tid_opaque(), lane = t & 63, wid = t >> 6, wm = wid >> 1, wn = wid & 1, fr = lane & 15, fq = lane >> 4;
;     const int rbase = (MT - 1) * 128 + wm * 64 + fr, c0 = nt * 64 + wn * 32 + fq * 4;
; #pragma unroll
;     for (int mi = 0; mi < 4; ++mi) {
;         const int row = rbase + mi * 16;
;         const float* gt = p.mod() + (size_t)(l * 9 + mod_index(row)) * 6144 + gate_off + c0;
;         float* dst = (float*)(p.ws + OFF_part) + ((size_t)kq * 128 + (row - SEQ)) * 1024 + c0;
; #pragma unroll
;         for (int ni = 0; ni < 2; ++ni) {
;             const f32x4 g4 = *(const f32x4*)(gt + ni * 16);
;             *(f32x4*)(dst + ni * 16) = g4 * acc[mi][ni];
;         }
;     }
	s_lshl_b32 s6, s6, 6
	v_ashrrev_i32_e32 v16, 1, v17
	v_and_b32_e32 v20, 0xffffffc0, v16
	v_and_or_b32 v16, v17, 15, v20
	v_lshrrev_b32_e32 v18, 1, v17
	v_lshrrev_b32_e32 v17, 2, v17
	v_and_b32_e32 v18, 32, v18
	v_and_b32_e32 v17, 12, v17
	v_add_u32_e32 v21, 0x4000, v16
	v_or3_b32 v18, v18, s6, v17
	v_lshrrev_b32_e32 v17, 4, v20
	v_or_b32_e32 v17, 1, v17
	v_cmp_lt_i32_e32 vcc, s31, v21
	v_ashrrev_i32_e32 v19, 31, v18
	v_mov_b64_e32 v[20:21], s[0:1]
	v_cndmask_b32_e32 v17, 0, v17, vcc
	v_add_u32_e32 v17, s12, v17
	s_lshl_b32 s92, s14, 7
	v_mad_i64_i32 v[22:23], s[6:7], v17, s33, v[20:21]
	v_lshlrev_b64 v[18:19], 2, v[18:19]
	v_ashrrev_i32_e32 v17, 31, v16
	v_lshl_add_u64 v[22:23], v[22:23], 0, v[18:19]
	v_lshl_add_u64 v[24:25], v[16:17], 0, s[92:93]
	v_lshl_add_u64 v[26:27], v[22:23], 0, s[44:45]
	v_lshlrev_b64 v[24:25], 12, v[24:25]
	v_add_co_u32_e32 v22, vcc, s29, v22
	v_lshl_add_u64 v[24:25], s[4:5], 0, v[24:25]
	s_nop 0
	v_addc_co_u32_e32 v23, vcc, 0, v23, vcc
	v_lshl_add_u64 v[46:47], v[24:25], 0, v[18:19]
	flat_load_dwordx4 v[22:25], v[22:23]
	v_add_u32_e32 v17, 0x4010, v16
	v_cmp_lt_i32_e32 vcc, s31, v17
	s_add_i32 s13, s13, s58
	s_cmp_gt_i32 s13, 63
	s_waitcnt vmcnt(0) lgkmcnt(0)
	v_pk_mul_f32 v[24:25], v[30:31], v[24:25]
	v_pk_mul_f32 v[22:23], v[28:29], v[22:23]
	flat_store_dwordx4 v[46:47], v[22:25]
	flat_load_dwordx4 v[22:25], v[26:27] offset:64
	s_waitcnt vmcnt(0) lgkmcnt(0)
	v_pk_mul_f32 v[24:25], v[40:41], v[24:25]
	v_pk_mul_f32 v[22:23], v[38:39], v[22:23]
	flat_store_dwordx4 v[46:47], v[22:25] offset:64
	s_nop 1
	v_or_b32_e32 v22, 16, v16
	v_lshrrev_b32_e32 v23, 4, v22
	v_add_u32_e32 v23, 1, v23
	v_cndmask_b32_e32 v17, 0, v23, vcc
	v_ashrrev_i32_e32 v23, 31, v22
	v_add_u32_e32 v17, s12, v17
	v_lshl_add_u64 v[22:23], v[22:23], 0, s[92:93]
	v_mad_i64_i32 v[24:25], s[6:7], v17, s33, v[20:21]
	v_lshlrev_b64 v[22:23], 12, v[22:23]
	v_lshl_add_u64 v[24:25], v[24:25], 0, v[18:19]
	v_lshl_add_u64 v[22:23], s[4:5], 0, v[22:23]
	v_lshl_add_u64 v[28:29], v[22:23], 0, v[18:19]
	v_add_co_u32_e32 v22, vcc, s29, v24
	v_lshl_add_u64 v[26:27], v[24:25], 0, s[44:45]
	s_nop 0
	v_addc_co_u32_e32 v23, vcc, 0, v25, vcc
	flat_load_dwordx4 v[22:25], v[22:23]
	v_add_u32_e32 v17, 0x4020, v16
	v_cmp_lt_i32_e32 vcc, s31, v17
	s_waitcnt vmcnt(0) lgkmcnt(0)
	v_pk_mul_f32 v[24:25], v[36:37], v[24:25]
	v_pk_mul_f32 v[22:23], v[34:35], v[22:23]
	flat_store_dwordx4 v[28:29], v[22:25]
	flat_load_dwordx4 v[22:25], v[26:27] offset:64
	s_waitcnt vmcnt(0) lgkmcnt(0)
	v_pk_mul_f32 v[24:25], v[44:45], v[24:25]
	v_pk_mul_f32 v[22:23], v[42:43], v[22:23]
	flat_store_dwordx4 v[28:29], v[22:25] offset:64
	s_nop 1
	v_or_b32_e32 v22, 32, v16
	v_lshrrev_b32_e32 v23, 4, v22
	v_or_b32_e32 v23, 1, v23
	v_cndmask_b32_e32 v17, 0, v23, vcc
	v_ashrrev_i32_e32 v23, 31, v22
	v_add_u32_e32 v17, s12, v17
	v_lshl_add_u64 v[22:23], v[22:23], 0, s[92:93]
	v_mad_i64_i32 v[24:25], s[6:7], v17, s33, v[20:21]
	v_lshlrev_b64 v[22:23], 12, v[22:23]
	v_lshl_add_u64 v[24:25], v[24:25], 0, v[18:19]
	v_lshl_add_u64 v[22:23], s[4:5], 0, v[22:23]
	v_lshl_add_u64 v[28:29], v[22:23], 0, v[18:19]
	v_add_co_u32_e32 v22, vcc, s29, v24
	v_lshl_add_u64 v[26:27], v[24:25], 0, s[44:45]
	s_nop 0
	v_addc_co_u32_e32 v23, vcc, 0, v25, vcc
	flat_load_dwordx4 v[22:25], v[22:23]
	s_waitcnt vmcnt(0) lgkmcnt(0)
	v_pk_mul_f32 v[14:15], v[14:15], v[24:25]
	v_pk_mul_f32 v[12:13], v[12:13], v[22:23]
	flat_store_dwordx4 v[28:29], v[12:15]
	flat_load_dwordx4 v[12:15], v[26:27] offset:64
	s_waitcnt vmcnt(0) lgkmcnt(0)
	v_pk_mul_f32 v[10:11], v[10:11], v[14:15]
	v_pk_mul_f32 v[8:9], v[8:9], v[12:13]
	flat_store_dwordx4 v[28:29], v[8:11] offset:64
	s_nop 1
	v_or_b32_e32 v8, 48, v16
	v_add_u32_e32 v9, 0x4030, v16
	v_lshrrev_b32_e32 v10, 4, v8
	v_add_u32_e32 v10, 1, v10
	v_cmp_lt_i32_e32 vcc, s31, v9
	s_nop 1
	v_cndmask_b32_e32 v9, 0, v10, vcc
	v_add_u32_e32 v9, s12, v9
	v_mad_i64_i32 v[10:11], s[6:7], v9, s33, v[20:21]
	v_ashrrev_i32_e32 v9, 31, v8
	v_lshl_add_u64 v[8:9], v[8:9], 0, s[92:93]
	v_lshlrev_b64 v[8:9], 12, v[8:9]
	v_lshl_add_u64 v[10:11], v[10:11], 0, v[18:19]
	v_lshl_add_u64 v[8:9], s[4:5], 0, v[8:9]
	v_lshl_add_u64 v[14:15], v[8:9], 0, v[18:19]
	v_add_co_u32_e32 v8, vcc, s29, v10
	v_lshl_add_u64 v[12:13], v[10:11], 0, s[44:45]
	s_nop 0
	v_addc_co_u32_e32 v9, vcc, 0, v11, vcc
	flat_load_dwordx4 v[8:11], v[8:9]
	s_waitcnt vmcnt(0) lgkmcnt(0)
	v_pk_mul_f32 v[6:7], v[6:7], v[10:11]
	v_pk_mul_f32 v[4:5], v[4:5], v[8:9]
	flat_store_dwordx4 v[14:15], v[4:7]
	flat_load_dwordx4 v[4:7], v[12:13] offset:64
	s_waitcnt vmcnt(0) lgkmcnt(0)
	v_pk_mul_f32 v[2:3], v[2:3], v[6:7]
	v_pk_mul_f32 v[0:1], v[0:1], v[4:5]
	flat_store_dwordx4 v[14:15], v[0:3] offset:64
	s_cbranch_scc0 .LBB0_98
	v_writelane_b32 v252, s92, 27
	s_nop 1
	v_writelane_b32 v252, s93, 28
	v_readlane_b32 s92, v254, 13
	v_readlane_b32 s93, v254, 14

;     __device__ __forceinline__ bf16_t* WbrA() const { return (bf16_t*)(ws + OFF_WbrA); }
;     __device__ __forceinline__ bf16_t* Y() const { return (bf16_t*)(ws + OFF_Y); }
; DEV int tid_opaque() { int t = threadIdx.x; asm volatile("" : "+v"(t)); return t; }
; #define RAW_BARRIER() do { asm volatile("s_waitcnt lgkmcnt(0)" ::: "memory"); __builtin_amdgcn_s_barrier(); } while (0)
; #define GLDS_TILE(kt, st) do { _Pragma("unroll") for (int _i = 0; _i < NP; ++_i) GLDS_PIECE(_i, kt, st); } while (0)
;     constexpr int BROWS = 32 * NI, STAGE = 8192 + BROWS * 64, NB = BROWS / 64;
;     const int t = tid_opaque(), lane = t & 63, wid = t >> 6, wm = wid >> 1, wn = wid & 1, fr = lane & 15, fq = lane >> 4;
;     const int nk = K >> 5;
;     const int srow = wid * 16 + (lane >> 2), sch = (lane & 3) ^ ((0 - (lane >> 4)) & 3);
;     const bf16_t* ga = A + (size_t)srow * lda + sch * 8;
;     const bf16_t* gb = B + (size_t)srow * ldb + sch * 8;
;     const int rd = fr * 64 + ((fq ^ ((0 - (fr >> 2)) & 3)) << 4);
;     const int rda = (wm * 64) * 64 + rd, rdb = 8192 + (wn * 16 * NI) * 64 + rd;
;     ...
;     constexpr int NH = NI >= 4 ? NI / 2 : NI;
;     constexpr int NP = 2 + NB, IVL = (4 * NI) / NP;
;     RAW_BARRIER();
;     GLDS_TILE(0, 0);
;     GLDS_TILE(1, 1);
;     int st = 0;
;     for (int kt = 0; kt < nk - 1; ++kt) {
;         if (NI == 8) asm volatile("s_waitcnt vmcnt(6)" ::: "memory"); else if (NI == 4) asm volatile("s_waitcnt vmcnt(4)" ::: "memory"); else asm volatile("s_waitcnt vmcnt(3)" ::: "memory");
;         RAW_BARRIER();
;         const int s2 = st >= 1 ? st - 1 : 2;
;         const bool ld = kt + 2 < nk;
;         STEP_TILE(st, ld, kt + 2, s2);
;         st = st == 2 ? 0 : st + 1;
;     }
; DEV void merge_big(const Params& p, int l, int mt, int nt, char* smem) {
;     const int t = tid_opaque(), lane = t & 63, wid = t >> 6, wm = wid >> 1, wn = wid & 1, fr = lane & 15, fq = lane >> 4;
;     const int rbase = mt * 128 + wm * 64 + fr, c0 = nt * 64 + wn * 32 + fq * 4;
;     f32x4 acc[4][2], mg[4][2];
; #pragma unroll
;     for (int br = 0; br < 3; ++br) {
;         zero_accn<2>(acc);
;         if (br == 0) gemm_glds<2>(p.Y() + (size_t)mt * 128 * 384, 384, p.WbrA() + (size_t)l * 1024 * 384 + (size_t)nt * 64 * 384, 384, 384, acc, smem);
.LBB0_106:
	s_ashr_i32 s11, s30, 4
	v_mov_b32_e32 v0, v186
	s_and_b32 s10, s30, 7
	s_and_b32 s11, s11, -8
	s_or_b32 s34, s11, s10
	v_ashrrev_i32_e32 v1, 1, v0
	v_and_b32_e32 v1, 0xffffffc0, v1
	v_lshl_add_u32 v1, s34, 7, v1
	s_bfe_u32 s39, s30, 0x40003
	v_and_or_b32 v94, v0, 15, v1
	v_lshrrev_b32_e32 v1, 1, v0
	v_lshrrev_b32_e32 v0, 2, v0
	s_lshl_b32 s10, s39, 6
	v_and_b32_e32 v1, 32, v1
	v_and_b32_e32 v0, 12, v0
	s_ashr_i32 s35, s34, 31
	v_or3_b32 v28, v1, s10, v0
	s_lshl_b64 s[10:11], s[34:35], 16
	s_lshl_b32 s31, s39, 15
	s_mul_i32 s38, s34, 0x18000
	v_mov_b32_e32 v4, v186
	s_mul_hi_i32 s35, s34, 0x18000
	s_add_u32 s40, s12, s38
	s_mul_i32 s34, s39, 0xc000
	v_ashrrev_i32_e32 v5, 6, v4
	v_bfe_u32 v6, v4, 4, 2
	v_bfe_u32 v0, v4, 2, 4
	s_addc_u32 s41, s13, s35
	v_lshl_or_b32 v7, v5, 4, v0
	v_sub_u32_e32 v0, 0, v6
	s_add_u32 s42, s14, s34
	v_xor_b32_e32 v2, v4, v0
	s_addc_u32 s43, s15, 0
	v_lshlrev_b32_e32 v2, 4, v2
	v_mov_b64_e32 v[0:1], s[40:41]
	v_and_b32_e32 v32, 48, v2
	v_mov_b64_e32 v[2:3], s[42:43]
	v_lshrrev_b32_e32 v8, 2, v4
	v_mad_i64_i32 v[0:1], s[40:41], v7, s48, v[0:1]
	v_mad_i64_i32 v[2:3], s[40:41], v7, s48, v[2:3]
	v_lshlrev_b32_e32 v7, 6, v4
	v_sub_u32_e32 v8, 0, v8
	v_lshl_add_u32 v29, v5, 10, 0
	v_and_b32_e32 v7, 0x3c0, v7
	v_bitop3_b32 v6, v6, v8, 3 bitop3:0x78
	v_readfirstlane_b32 s44, v29
	v_add_u32_e32 v10, 0x1000, v29
	v_lshl_add_u64 v[0:1], v[0:1], 0, v[32:33]
	v_lshl_or_b32 v8, v6, 4, v7
	v_add_u32_e32 v7, 0x2000, v29
	s_mov_b32 m0, s44
	v_readfirstlane_b32 s43, v10
	v_lshlrev_b32_e32 v6, 5, v4
	v_lshlrev_b32_e32 v9, 11, v5
	s_waitcnt lgkmcnt(0)
	s_barrier
	global_load_lds_dwordx4 v[0:1], off
	v_lshl_add_u64 v[4:5], v[0:1], 0, s[66:67]
	s_mov_b32 m0, s43
	v_readfirstlane_b32 s42, v7
	v_add_u32_e32 v11, 0x3000, v29
	v_lshl_add_u64 v[2:3], v[2:3], 0, v[32:33]
	global_load_lds_dwordx4 v[4:5], off
	s_mov_b32 m0, s42
	v_readfirstlane_b32 s41, v11
	v_add_u32_e32 v11, 0x4000, v29
	global_load_lds_dwordx4 v[2:3], off
	v_and_or_b32 v10, v6, s49, v8
	v_add_u32_e32 v12, 0x5000, v29
	v_lshl_add_u64 v[6:7], v[0:1], 0, 64
	s_mov_b32 m0, s41
	v_readfirstlane_b32 s40, v11
	global_load_lds_dwordx4 v[6:7], off
	v_lshl_add_u64 v[6:7], v[0:1], 0, s[68:69]
	s_mov_b32 m0, s40
	v_readfirstlane_b32 s39, v12
	v_lshl_add_u64 v[4:5], v[2:3], 0, 64
	global_load_lds_dwordx4 v[6:7], off
	s_mov_b32 m0, s39
	v_add_u32_e32 v32, 0, v10
	global_load_lds_dwordx4 v[4:5], off
	s_waitcnt vmcnt(3)
	v_and_or_b32 v20, v9, s50, v8
	s_waitcnt lgkmcnt(0)
	s_barrier
	ds_read_b128 v[4:7], v32
	ds_read_b128 v[8:11], v32 offset:1024
	ds_read_b128 v[12:15], v32 offset:2048
	ds_read_b128 v[16:19], v32 offset:3072
	s_waitcnt vmcnt(0)
	v_add_u32_e32 v70, 0, v20
	ds_read_b128 v[20:23], v70 offset:8192
	ds_read_b128 v[24:27], v70 offset:9216
	s_setprio 1
	v_add_u32_e32 v44, 0x6000, v29
	s_waitcnt lgkmcnt(0)
	v_mfma_f32_16x16x32_bf16 v[34:37], v[20:23], v[4:7], 0
	v_lshl_add_u64 v[30:31], v[2:3], 0, s[54:55]
	v_add_u32_e32 v48, 0x8000, v29
	v_lshl_add_u64 v[42:43], v[0:1], 0, s[54:55]
	v_mfma_f32_16x16x32_bf16 v[38:41], v[20:23], v[8:11], 0
	v_readfirstlane_b32 s45, v44
	s_mov_b32 m0, s45
	s_nop 0
	global_load_lds_dwordx4 v[42:43], off
	v_mfma_f32_16x16x32_bf16 v[42:45], v[20:23], v[12:15], 0
	v_mfma_f32_16x16x32_bf16 v[20:23], v[20:23], v[16:19], 0
	v_add_u32_e32 v29, 0x7000, v29
	v_lshl_add_u64 v[46:47], v[0:1], 0, s[96:97]
	v_readfirstlane_b32 s46, v29
	s_mov_b32 m0, s46
	s_nop 0
	global_load_lds_dwordx4 v[46:47], off
	v_mfma_f32_16x16x32_bf16 v[4:7], v[24:27], v[4:7], 0
	v_mfma_f32_16x16x32_bf16 v[8:11], v[24:27], v[8:11], 0
	v_readfirstlane_b32 s47, v48
	s_mov_b32 m0, s47
	s_nop 0
	global_load_lds_dwordx4 v[30:31], off
	v_mfma_f32_16x16x32_bf16 v[12:15], v[24:27], v[12:15], 0
	v_mfma_f32_16x16x32_bf16 v[16:19], v[24:27], v[16:19], 0
	s_setprio 0
	s_waitcnt vmcnt(3)
	s_waitcnt lgkmcnt(0)
	s_barrier
	ds_read_b128 v[58:61], v70 offset:20480
	ds_read_b128 v[24:27], v32 offset:12288
	ds_read_b128 v[46:49], v32 offset:13312
	ds_read_b128 v[50:53], v32 offset:14336
	ds_read_b128 v[54:57], v32 offset:15360
	ds_read_b128 v[62:65], v70 offset:21504
	s_setprio 1
	s_waitcnt lgkmcnt(4)
	v_mfma_f32_16x16x32_bf16 v[34:37], v[58:61], v[24:27], v[34:37]
	v_lshl_add_u64 v[30:31], v[2:3], 0, s[56:57]
	v_lshl_add_u64 v[66:67], v[0:1], 0, s[56:57]
	s_waitcnt lgkmcnt(3)
	v_mfma_f32_16x16x32_bf16 v[38:41], v[58:61], v[46:49], v[38:41]
	s_mov_b32 m0, s44
	s_nop 0
	global_load_lds_dwordx4 v[66:67], off
	s_waitcnt lgkmcnt(2)
	v_mfma_f32_16x16x32_bf16 v[42:45], v[58:61], v[50:53], v[42:45]
	s_waitcnt lgkmcnt(1)
	v_mfma_f32_16x16x32_bf16 v[20:23], v[58:61], v[54:57], v[20:23]
	v_lshl_add_u64 v[58:59], v[0:1], 0, s[94:95]
	s_mov_b32 m0, s43
	s_nop 0
	global_load_lds_dwordx4 v[58:59], off
	s_waitcnt lgkmcnt(0)
	v_mfma_f32_16x16x32_bf16 v[4:7], v[62:65], v[24:27], v[4:7]
	v_mfma_f32_16x16x32_bf16 v[8:11], v[62:65], v[46:49], v[8:11]
	s_mov_b32 m0, s42
	s_nop 0
	global_load_lds_dwordx4 v[30:31], off
	v_mfma_f32_16x16x32_bf16 v[12:15], v[62:65], v[50:53], v[12:15]
	v_mfma_f32_16x16x32_bf16 v[16:19], v[62:65], v[54:57], v[16:19]
	s_setprio 0
	s_waitcnt vmcnt(3)
	s_waitcnt lgkmcnt(0)
	s_barrier
; #define RAW_BARRIER() do { asm volatile("s_waitcnt lgkmcnt(0)" ::: "memory"); __builtin_amdgcn_s_barrier(); } while (0)
; #define GLDS_TILE(kt, st) do { _Pragma("unroll") for (int _i = 0; _i < NP; ++_i) GLDS_PIECE(_i, kt, st); } while (0)
;     ...
;     constexpr int NH = NI >= 4 ? NI / 2 : NI;
;     constexpr int NP = 2 + NB, IVL = (4 * NI) / NP;
;     RAW_BARRIER();
;     GLDS_TILE(0, 0);
;     GLDS_TILE(1, 1);
;     int st = 0;
;     for (int kt = 0; kt < nk - 1; ++kt) {
;         if (NI == 8) asm volatile("s_waitcnt vmcnt(6)" ::: "memory"); else if (NI == 4) asm volatile("s_waitcnt vmcnt(4)" ::: "memory"); else asm volatile("s_waitcnt vmcnt(3)" ::: "memory");
;         RAW_BARRIER();
;         const int s2 = st >= 1 ? st - 1 : 2;
;         const bool ld = kt + 2 < nk;
;         STEP_TILE(st, ld, kt + 2, s2);
;         st = st == 2 ? 0 : st + 1;
;     }
	ds_read_b128 v[58:61], v70 offset:32768
	ds_read_b128 v[24:27], v32 offset:24576
	ds_read_b128 v[46:49], v32 offset:25600
	ds_read_b128 v[50:53], v32 offset:26624
	ds_read_b128 v[54:57], v32 offset:27648
	ds_read_b128 v[62:65], v70 offset:33792
	s_setprio 1
	s_waitcnt lgkmcnt(4)
	v_mfma_f32_16x16x32_bf16 v[34:37], v[58:61], v[24:27], v[34:37]
	v_lshl_add_u64 v[30:31], v[2:3], 0, s[58:59]
	v_lshl_add_u64 v[66:67], v[0:1], 0, s[58:59]
	s_waitcnt lgkmcnt(3)
	v_mfma_f32_16x16x32_bf16 v[38:41], v[58:61], v[46:49], v[38:41]
	s_mov_b32 m0, s41
	s_nop 0
	global_load_lds_dwordx4 v[66:67], off
	s_waitcnt lgkmcnt(2)
	v_mfma_f32_16x16x32_bf16 v[42:45], v[58:61], v[50:53], v[42:45]
	s_waitcnt lgkmcnt(1)
	v_mfma_f32_16x16x32_bf16 v[20:23], v[58:61], v[54:57], v[20:23]
	v_lshl_add_u64 v[58:59], v[0:1], 0, s[70:71]
	s_mov_b32 m0, s40
	s_nop 0
	global_load_lds_dwordx4 v[58:59], off
	s_waitcnt lgkmcnt(0)
	v_mfma_f32_16x16x32_bf16 v[4:7], v[62:65], v[24:27], v[4:7]
	v_mfma_f32_16x16x32_bf16 v[8:11], v[62:65], v[46:49], v[8:11]
	s_mov_b32 m0, s39
	s_nop 0
	global_load_lds_dwordx4 v[30:31], off
	v_mfma_f32_16x16x32_bf16 v[12:15], v[62:65], v[50:53], v[12:15]
	v_mfma_f32_16x16x32_bf16 v[16:19], v[62:65], v[54:57], v[16:19]
	s_setprio 0
	s_waitcnt vmcnt(3)
	s_waitcnt lgkmcnt(0)
	s_barrier
	ds_read_b128 v[58:61], v70 offset:8192
	ds_read_b128 v[24:27], v32
	ds_read_b128 v[46:49], v32 offset:1024
	ds_read_b128 v[50:53], v32 offset:2048
	ds_read_b128 v[54:57], v32 offset:3072
	ds_read_b128 v[62:65], v70 offset:9216
	s_setprio 1
	s_waitcnt lgkmcnt(4)
	v_mfma_f32_16x16x32_bf16 v[34:37], v[58:61], v[24:27], v[34:37]
	v_lshl_add_u64 v[30:31], v[2:3], 0, s[60:61]
	v_lshl_add_u64 v[66:67], v[0:1], 0, s[60:61]
	s_waitcnt lgkmcnt(3)
	v_mfma_f32_16x16x32_bf16 v[38:41], v[58:61], v[46:49], v[38:41]
	s_mov_b32 m0, s45
	s_nop 0
	global_load_lds_dwordx4 v[66:67], off
	s_waitcnt lgkmcnt(2)
	v_mfma_f32_16x16x32_bf16 v[42:45], v[58:61], v[50:53], v[42:45]
	s_waitcnt lgkmcnt(1)
	v_mfma_f32_16x16x32_bf16 v[20:23], v[58:61], v[54:57], v[20:23]
	v_lshl_add_u64 v[58:59], v[0:1], 0, s[72:73]
	s_mov_b32 m0, s46
	s_nop 0
	global_load_lds_dwordx4 v[58:59], off
	s_waitcnt lgkmcnt(0)
	v_mfma_f32_16x16x32_bf16 v[4:7], v[62:65], v[24:27], v[4:7]
	v_mfma_f32_16x16x32_bf16 v[8:11], v[62:65], v[46:49], v[8:11]
	s_mov_b32 m0, s47
	s_nop 0
	global_load_lds_dwordx4 v[30:31], off
	v_mfma_f32_16x16x32_bf16 v[12:15], v[62:65], v[50:53], v[12:15]
	v_mfma_f32_16x16x32_bf16 v[16:19], v[62:65], v[54:57], v[16:19]
	s_setprio 0
	s_waitcnt vmcnt(3)
	s_waitcnt lgkmcnt(0)
	s_barrier
	ds_read_b128 v[58:61], v70 offset:20480
	ds_read_b128 v[24:27], v32 offset:12288
	ds_read_b128 v[46:49], v32 offset:13312
	ds_read_b128 v[50:53], v32 offset:14336
	ds_read_b128 v[54:57], v32 offset:15360
	ds_read_b128 v[62:65], v70 offset:21504
	s_setprio 1
	s_waitcnt lgkmcnt(4)
	v_mfma_f32_16x16x32_bf16 v[34:37], v[58:61], v[24:27], v[34:37]
	v_lshl_add_u64 v[30:31], v[2:3], 0, s[62:63]
	v_lshl_add_u64 v[66:67], v[0:1], 0, s[62:63]
	s_waitcnt lgkmcnt(3)
	v_mfma_f32_16x16x32_bf16 v[38:41], v[58:61], v[46:49], v[38:41]
	s_mov_b32 m0, s44
	s_nop 0
	global_load_lds_dwordx4 v[66:67], off
	s_waitcnt lgkmcnt(2)
	v_mfma_f32_16x16x32_bf16 v[42:45], v[58:61], v[50:53], v[42:45]
	s_waitcnt lgkmcnt(1)
	v_mfma_f32_16x16x32_bf16 v[20:23], v[58:61], v[54:57], v[20:23]
	v_lshl_add_u64 v[58:59], v[0:1], 0, s[84:85]
	s_mov_b32 m0, s43
	s_nop 0
	global_load_lds_dwordx4 v[58:59], off
	s_waitcnt lgkmcnt(0)
	v_mfma_f32_16x16x32_bf16 v[4:7], v[62:65], v[24:27], v[4:7]
	v_mfma_f32_16x16x32_bf16 v[8:11], v[62:65], v[46:49], v[8:11]
	s_mov_b32 m0, s42
	s_nop 0
	global_load_lds_dwordx4 v[30:31], off
	v_mfma_f32_16x16x32_bf16 v[12:15], v[62:65], v[50:53], v[12:15]
	v_mfma_f32_16x16x32_bf16 v[16:19], v[62:65], v[54:57], v[16:19]
	s_setprio 0
	s_waitcnt vmcnt(3)
	s_waitcnt lgkmcnt(0)
	s_barrier
	ds_read_b128 v[58:61], v70 offset:32768
	ds_read_b128 v[24:27], v32 offset:24576
	ds_read_b128 v[46:49], v32 offset:25600
	ds_read_b128 v[50:53], v32 offset:26624
	ds_read_b128 v[54:57], v32 offset:27648
	ds_read_b128 v[62:65], v70 offset:33792
	s_setprio 1
	s_waitcnt lgkmcnt(4)
	v_mfma_f32_16x16x32_bf16 v[34:37], v[58:61], v[24:27], v[34:37]
	v_lshl_add_u64 v[30:31], v[2:3], 0, s[64:65]
	v_lshl_add_u64 v[66:67], v[0:1], 0, s[64:65]
	s_waitcnt lgkmcnt(3)
	v_mfma_f32_16x16x32_bf16 v[38:41], v[58:61], v[46:49], v[38:41]
	s_mov_b32 m0, s41
	s_nop 0
	global_load_lds_dwordx4 v[66:67], off
	s_waitcnt lgkmcnt(2)
	v_mfma_f32_16x16x32_bf16 v[42:45], v[58:61], v[50:53], v[42:45]
	s_waitcnt lgkmcnt(1)
	v_mfma_f32_16x16x32_bf16 v[20:23], v[58:61], v[54:57], v[20:23]
	s_mov_b64 vcc, 0xc1c0
	v_lshl_add_u64 v[58:59], v[0:1], 0, vcc
	s_mov_b32 m0, s40
	s_nop 0
	global_load_lds_dwordx4 v[58:59], off
	s_waitcnt lgkmcnt(0)
	v_mfma_f32_16x16x32_bf16 v[4:7], v[62:65], v[24:27], v[4:7]
	v_mfma_f32_16x16x32_bf16 v[8:11], v[62:65], v[46:49], v[8:11]
	s_mov_b32 m0, s39
	s_nop 0
	global_load_lds_dwordx4 v[30:31], off
	v_mfma_f32_16x16x32_bf16 v[12:15], v[62:65], v[50:53], v[12:15]
	v_mfma_f32_16x16x32_bf16 v[16:19], v[62:65], v[54:57], v[16:19]
	s_setprio 0
	s_waitcnt vmcnt(3)
	s_waitcnt lgkmcnt(0)
	s_barrier
; #define RAW_BARRIER() do { asm volatile("s_waitcnt lgkmcnt(0)" ::: "memory"); __builtin_amdgcn_s_barrier(); } while (0)
; #define GLDS_TILE(kt, st) do { _Pragma("unroll") for (int _i = 0; _i < NP; ++_i) GLDS_PIECE(_i, kt, st); } while (0)
;     ...
;     constexpr int NH = NI >= 4 ? NI / 2 : NI;
;     constexpr int NP = 2 + NB, IVL = (4 * NI) / NP;
;     RAW_BARRIER();
;     GLDS_TILE(0, 0);
;     GLDS_TILE(1, 1);
;     int st = 0;
;     for (int kt = 0; kt < nk - 1; ++kt) {
;         if (NI == 8) asm volatile("s_waitcnt vmcnt(6)" ::: "memory"); else if (NI == 4) asm volatile("s_waitcnt vmcnt(4)" ::: "memory"); else asm volatile("s_waitcnt vmcnt(3)" ::: "memory");
;         RAW_BARRIER();
;         const int s2 = st >= 1 ? st - 1 : 2;
;         const bool ld = kt + 2 < nk;
;         STEP_TILE(st, ld, kt + 2, s2);
;         st = st == 2 ? 0 : st + 1;
;     }
	ds_read_b128 v[58:61], v70 offset:8192
	ds_read_b128 v[24:27], v32
	ds_read_b128 v[46:49], v32 offset:1024
	ds_read_b128 v[50:53], v32 offset:2048
	ds_read_b128 v[54:57], v32 offset:3072
	ds_read_b128 v[62:65], v70 offset:9216
	s_setprio 1
	s_mov_b64 s[76:77], 0x200
	s_waitcnt lgkmcnt(4)
	v_mfma_f32_16x16x32_bf16 v[34:37], v[58:61], v[24:27], v[34:37]
	v_lshl_add_u64 v[30:31], v[2:3], 0, s[76:77]
	v_lshl_add_u64 v[66:67], v[0:1], 0, s[76:77]
	s_waitcnt lgkmcnt(3)
	v_mfma_f32_16x16x32_bf16 v[38:41], v[58:61], v[46:49], v[38:41]
	s_mov_b32 m0, s45
	s_nop 0
	global_load_lds_dwordx4 v[66:67], off
	s_waitcnt lgkmcnt(2)
	v_mfma_f32_16x16x32_bf16 v[42:45], v[58:61], v[50:53], v[42:45]
	s_waitcnt lgkmcnt(1)
	v_mfma_f32_16x16x32_bf16 v[20:23], v[58:61], v[54:57], v[20:23]
	s_mov_b64 s[16:17], 0xc200
	v_lshl_add_u64 v[58:59], v[0:1], 0, s[16:17]
	s_mov_b32 m0, s46
	s_nop 0
	global_load_lds_dwordx4 v[58:59], off
	s_waitcnt lgkmcnt(0)
	v_mfma_f32_16x16x32_bf16 v[4:7], v[62:65], v[24:27], v[4:7]
	v_mfma_f32_16x16x32_bf16 v[8:11], v[62:65], v[46:49], v[8:11]
	s_mov_b32 m0, s47
	s_nop 0
	global_load_lds_dwordx4 v[30:31], off
	v_mfma_f32_16x16x32_bf16 v[12:15], v[62:65], v[50:53], v[12:15]
	v_mfma_f32_16x16x32_bf16 v[16:19], v[62:65], v[54:57], v[16:19]
	s_setprio 0
	s_waitcnt vmcnt(3)
	s_waitcnt lgkmcnt(0)
	s_barrier
	ds_read_b128 v[58:61], v70 offset:20480
	ds_read_b128 v[24:27], v32 offset:12288
	ds_read_b128 v[46:49], v32 offset:13312
	ds_read_b128 v[50:53], v32 offset:14336
	ds_read_b128 v[54:57], v32 offset:15360
	ds_read_b128 v[62:65], v70 offset:21504
	s_setprio 1
	s_waitcnt lgkmcnt(4)
	v_mfma_f32_16x16x32_bf16 v[34:37], v[58:61], v[24:27], v[34:37]
	v_lshl_add_u64 v[30:31], v[2:3], 0, s[86:87]
	v_lshl_add_u64 v[66:67], v[0:1], 0, s[86:87]
	s_waitcnt lgkmcnt(3)
	v_mfma_f32_16x16x32_bf16 v[38:41], v[58:61], v[46:49], v[38:41]
	s_mov_b32 m0, s44
	s_nop 0
	global_load_lds_dwordx4 v[66:67], off
	s_waitcnt lgkmcnt(2)
	v_mfma_f32_16x16x32_bf16 v[42:45], v[58:61], v[50:53], v[42:45]
	s_waitcnt lgkmcnt(1)
	v_mfma_f32_16x16x32_bf16 v[20:23], v[58:61], v[54:57], v[20:23]
	v_lshl_add_u64 v[58:59], v[0:1], 0, s[90:91]
	s_mov_b32 m0, s43
	s_nop 0
	global_load_lds_dwordx4 v[58:59], off
	s_waitcnt lgkmcnt(0)
	v_mfma_f32_16x16x32_bf16 v[4:7], v[62:65], v[24:27], v[4:7]
	v_mfma_f32_16x16x32_bf16 v[8:11], v[62:65], v[46:49], v[8:11]
	s_mov_b32 m0, s42
	s_nop 0
	global_load_lds_dwordx4 v[30:31], off
	v_mfma_f32_16x16x32_bf16 v[12:15], v[62:65], v[50:53], v[12:15]
	v_mfma_f32_16x16x32_bf16 v[16:19], v[62:65], v[54:57], v[16:19]
	s_setprio 0
	s_waitcnt vmcnt(3)
	s_waitcnt lgkmcnt(0)
	s_barrier
	ds_read_b128 v[58:61], v70 offset:32768
	ds_read_b128 v[24:27], v32 offset:24576
	ds_read_b128 v[46:49], v32 offset:25600
	ds_read_b128 v[50:53], v32 offset:26624
	ds_read_b128 v[54:57], v32 offset:27648
	ds_read_b128 v[62:65], v70 offset:33792
	s_setprio 1
	s_waitcnt lgkmcnt(4)
	v_mfma_f32_16x16x32_bf16 v[34:37], v[58:61], v[24:27], v[34:37]
	v_lshl_add_u64 v[30:31], v[2:3], 0, s[88:89]
	v_lshl_add_u64 v[66:67], v[0:1], 0, s[88:89]
	s_waitcnt lgkmcnt(3)
	v_mfma_f32_16x16x32_bf16 v[38:41], v[58:61], v[46:49], v[38:41]
	s_mov_b32 m0, s41
	s_nop 0
	global_load_lds_dwordx4 v[66:67], off
	s_waitcnt lgkmcnt(2)
	v_mfma_f32_16x16x32_bf16 v[42:45], v[58:61], v[50:53], v[42:45]
	s_waitcnt lgkmcnt(1)
	v_mfma_f32_16x16x32_bf16 v[20:23], v[58:61], v[54:57], v[20:23]
	s_mov_b64 s[92:93], 0xc280
	v_lshl_add_u64 v[58:59], v[0:1], 0, s[92:93]
	s_mov_b32 m0, s40
	s_nop 0
	global_load_lds_dwordx4 v[58:59], off
	s_waitcnt lgkmcnt(0)
	v_mfma_f32_16x16x32_bf16 v[4:7], v[62:65], v[24:27], v[4:7]
	v_mfma_f32_16x16x32_bf16 v[8:11], v[62:65], v[46:49], v[8:11]
	s_mov_b32 m0, s39
	s_nop 0
	global_load_lds_dwordx4 v[30:31], off
	v_mfma_f32_16x16x32_bf16 v[12:15], v[62:65], v[50:53], v[12:15]
	v_mfma_f32_16x16x32_bf16 v[16:19], v[62:65], v[54:57], v[16:19]
	s_setprio 0
	s_waitcnt vmcnt(3)
	s_waitcnt lgkmcnt(0)
	s_barrier
	ds_read_b128 v[58:61], v70 offset:8192
	ds_read_b128 v[24:27], v32
	ds_read_b128 v[46:49], v32 offset:1024
	ds_read_b128 v[50:53], v32 offset:2048
	ds_read_b128 v[54:57], v32 offset:3072
	ds_read_b128 v[62:65], v70 offset:9216
	s_setprio 1
	s_mov_b64 s[78:79], 0x2c0
	s_waitcnt lgkmcnt(4)
	v_mfma_f32_16x16x32_bf16 v[34:37], v[58:61], v[24:27], v[34:37]
	v_lshl_add_u64 v[30:31], v[2:3], 0, s[78:79]
	v_lshl_add_u64 v[2:3], v[0:1], 0, s[78:79]
	s_waitcnt lgkmcnt(3)
	v_mfma_f32_16x16x32_bf16 v[38:41], v[58:61], v[46:49], v[38:41]
	s_mov_b32 m0, s45
	s_nop 0
	global_load_lds_dwordx4 v[2:3], off
	s_waitcnt lgkmcnt(2)
	v_mfma_f32_16x16x32_bf16 v[42:45], v[58:61], v[50:53], v[42:45]
	s_waitcnt lgkmcnt(1)
	v_mfma_f32_16x16x32_bf16 v[20:23], v[58:61], v[54:57], v[20:23]
	s_mov_b64 s[80:81], 0xc2c0
	v_lshl_add_u64 v[0:1], v[0:1], 0, s[80:81]
	s_mov_b32 m0, s46
	s_nop 0
	global_load_lds_dwordx4 v[0:1], off
	s_waitcnt lgkmcnt(0)
	v_mfma_f32_16x16x32_bf16 v[0:3], v[62:65], v[24:27], v[4:7]
	v_mfma_f32_16x16x32_bf16 v[4:7], v[62:65], v[46:49], v[8:11]
	s_mov_b32 m0, s47
	s_nop 0
	global_load_lds_dwordx4 v[30:31], off
	v_mfma_f32_16x16x32_bf16 v[8:11], v[62:65], v[50:53], v[12:15]
	v_mfma_f32_16x16x32_bf16 v[12:15], v[62:65], v[54:57], v[16:19]
	s_setprio 0
	s_waitcnt vmcnt(3)
	s_waitcnt lgkmcnt(0)
	s_barrier
;     __device__ __forceinline__ bf16_t* WbrA() const { return (bf16_t*)(ws + OFF_WbrA); }
;     __device__ __forceinline__ bf16_t* WbrB() const { return (bf16_t*)(ws + OFF_WbrB); }
;     __device__ __forceinline__ bf16_t* WbrC() const { return (bf16_t*)(ws + OFF_WbrC); }
;     __device__ __forceinline__ bf16_t* G() const { return (bf16_t*)(ws + OFF_G); }
;     __device__ __forceinline__ bf16_t* Y() const { return (bf16_t*)(ws + OFF_Y); }
;     __device__ __forceinline__ bf16_t* Of() const { return (bf16_t*)(ws + OFF_Of); }
;     __device__ __forceinline__ bf16_t* Ob() const { return (bf16_t*)(ws + OFF_Ob); }
; DEV void ld_bf4(const bf16_t* p, float (&v)[4]) { uint2 w = *(const uint2*)p; v[0] = bf_lo(w.x); v[1] = bf_hi(w.x); v[2] = bf_lo(w.y); v[3] = bf_hi(w.y); }
; #define RAW_BARRIER() do { asm volatile("s_waitcnt lgkmcnt(0)" ::: "memory"); __builtin_amdgcn_s_barrier(); } while (0)
;     ...
;     asm volatile("s_waitcnt vmcnt(0)" ::: "memory");
;     RAW_BARRIER();
;     STEP_TILE(st, false, 0, 0);
;     RAW_BARRIER();
; DEV void merge_big(const Params& p, int l, int mt, int nt, char* smem) {
;     ...
;         if (br == 0) gemm_glds<2>(p.Y() + (size_t)mt * 128 * 384, 384, p.WbrA() + (size_t)l * 1024 * 384 + (size_t)nt * 64 * 384, 384, 384, acc, smem);
;         else if (br == 1) gemm_glds<2>(p.Of() + (size_t)mt * 128 * 384, 384, p.WbrB() + (size_t)l * 1024 * 384 + (size_t)nt * 64 * 384, 384, 384, acc, smem);
;         else gemm_glds<2>(p.Ob() + (size_t)mt * 128 * 256, 256, p.WbrC() + (size_t)l * 1024 * 256 + (size_t)nt * 64 * 256, 256, 256, acc, smem);
; #pragma unroll
;         for (int mi = 0; mi < 4; ++mi)
; #pragma unroll
;             for (int ni = 0; ni < 2; ++ni) {
;                 float g[4]; ld_bf4(p.G() + (size_t)(rbase + mi * 16) * 3072 + br * 1024 + c0 + ni * 16, g);
;                 const f32x4 gv = (f32x4){g[0], g[1], g[2], g[3]};
;                 if (br == 0) mg[mi][ni] = gv * acc[mi][ni]; else mg[mi][ni] += gv * acc[mi][ni];
;             }
	s_nop 0
	ds_read_b128 v[16:19], v32 offset:12288
	ds_read_b128 v[24:27], v32 offset:13312
	ds_read_b128 v[46:49], v32 offset:14336
	ds_read_b128 v[50:53], v32 offset:15360
	ds_read_b128 v[54:57], v70 offset:20480
	ds_read_b128 v[58:61], v70 offset:21504
	s_setprio 1
	s_waitcnt lgkmcnt(0)
	v_mfma_f32_16x16x32_bf16 v[34:37], v[54:57], v[16:19], v[34:37]
	v_mfma_f32_16x16x32_bf16 v[38:41], v[54:57], v[24:27], v[38:41]
	v_mfma_f32_16x16x32_bf16 v[42:45], v[54:57], v[46:49], v[42:45]
	v_mfma_f32_16x16x32_bf16 v[20:23], v[54:57], v[50:53], v[20:23]
	v_mfma_f32_16x16x32_bf16 v[54:57], v[58:61], v[16:19], v[0:3]
	v_mfma_f32_16x16x32_bf16 v[62:65], v[58:61], v[24:27], v[4:7]
	v_mfma_f32_16x16x32_bf16 v[46:49], v[58:61], v[46:49], v[8:11]
	v_mfma_f32_16x16x32_bf16 v[50:53], v[58:61], v[50:53], v[12:15]
	s_setprio 0
	s_waitcnt vmcnt(0)
	s_waitcnt lgkmcnt(0)
	s_barrier
	ds_read_b128 v[24:27], v70 offset:32768
	ds_read_b128 v[4:7], v32 offset:24576
	ds_read_b128 v[12:15], v32 offset:25600
	ds_read_b128 v[58:61], v32 offset:26624
	ds_read_b128 v[66:69], v32 offset:27648
	ds_read_b128 v[70:73], v70 offset:33792
	s_setprio 1
	s_waitcnt lgkmcnt(4)
	v_mfma_f32_16x16x32_bf16 v[0:3], v[24:27], v[4:7], v[34:37]
	s_waitcnt lgkmcnt(3)
	v_mfma_f32_16x16x32_bf16 v[8:11], v[24:27], v[12:15], v[38:41]
	s_waitcnt lgkmcnt(2)
	v_mfma_f32_16x16x32_bf16 v[16:19], v[24:27], v[58:61], v[42:45]
	s_waitcnt lgkmcnt(1)
	v_mfma_f32_16x16x32_bf16 v[24:27], v[24:27], v[66:69], v[20:23]
	s_waitcnt lgkmcnt(0)
	v_mfma_f32_16x16x32_bf16 v[4:7], v[70:73], v[4:7], v[54:57]
	v_mfma_f32_16x16x32_bf16 v[12:15], v[70:73], v[12:15], v[62:65]
	v_mfma_f32_16x16x32_bf16 v[20:23], v[70:73], v[58:61], v[46:49]
	v_mfma_f32_16x16x32_bf16 v[38:41], v[70:73], v[66:69], v[50:53]
	s_setprio 0
	v_lshlrev_b32_e32 v32, 1, v28
	v_lshl_add_u64 v[28:29], s[0:1], 0, v[32:33]
	v_mad_i64_i32 v[30:31], s[40:41], v94, s51, v[28:29]
	v_or_b32_e32 v100, 16, v94
	v_or_b32_e32 v98, 32, v94
	v_or_b32_e32 v96, 48, v94
	s_waitcnt lgkmcnt(0)
	s_barrier
	v_mad_i64_i32 v[34:35], s[40:41], v100, s51, v[28:29]
	s_waitcnt vmcnt(0)
	flat_load_dwordx2 v[102:103], v[30:31]
	flat_load_dwordx2 v[104:105], v[30:31] offset:32
	flat_load_dwordx2 v[106:107], v[34:35]
	flat_load_dwordx2 v[108:109], v[34:35] offset:32
	v_mad_i64_i32 v[30:31], s[40:41], v98, s51, v[28:29]
	v_mad_i64_i32 v[28:29], s[40:41], v96, s51, v[28:29]
	v_mov_b32_e32 v42, v186
	flat_load_dwordx2 v[110:111], v[30:31]
	flat_load_dwordx2 v[112:113], v[30:31] offset:32
	flat_load_dwordx2 v[114:115], v[28:29]
	flat_load_dwordx2 v[122:123], v[28:29] offset:32
	s_add_u32 s38, s18, s38
	s_addc_u32 s39, s19, s35
	v_ashrrev_i32_e32 v43, 6, v42
	v_bfe_u32 v44, v42, 4, 2
	v_bfe_u32 v28, v42, 2, 4
	v_lshl_or_b32 v36, v43, 4, v28
	v_sub_u32_e32 v28, 0, v44
	s_add_u32 s34, s20, s34
	v_xor_b32_e32 v30, v42, v28
	s_addc_u32 s35, s21, 0
	v_mov_b64_e32 v[28:29], s[38:39]
	v_lshlrev_b32_e32 v30, 4, v30
	v_lshl_add_u32 v78, v43, 10, 0
	v_mad_i64_i32 v[28:29], s[38:39], v36, s48, v[28:29]
	v_and_b32_e32 v30, 48, v30
	v_mov_b32_e32 v31, v33
	v_mov_b64_e32 v[34:35], s[34:35]
	v_readfirstlane_b32 s44, v78
	v_add_u32_e32 v37, 0x1000, v78
	v_lshl_add_u64 v[28:29], v[28:29], 0, v[30:31]
	v_mad_i64_i32 v[34:35], s[34:35], v36, s48, v[34:35]
	v_add_u32_e32 v36, 0x2000, v78
	s_mov_b32 m0, s44
	v_readfirstlane_b32 s43, v37
	v_lshl_add_u64 v[30:31], v[34:35], 0, v[30:31]
	s_waitcnt lgkmcnt(0)
	s_barrier
	global_load_lds_dwordx4 v[28:29], off
	v_lshl_add_u64 v[34:35], v[28:29], 0, s[66:67]
	s_mov_b32 m0, s43
	v_readfirstlane_b32 s42, v36
	v_add_u32_e32 v45, 0x3000, v78
	global_load_lds_dwordx4 v[34:35], off
	s_mov_b32 m0, s42
	v_readfirstlane_b32 s38, v45
	v_add_u32_e32 v45, 0x4000, v78
	global_load_lds_dwordx4 v[30:31], off
	v_add_u32_e32 v46, 0x5000, v78
	v_lshl_add_u64 v[36:37], v[28:29], 0, 64
	s_mov_b32 m0, s38
	v_readfirstlane_b32 s35, v45
	global_load_lds_dwordx4 v[36:37], off
	v_lshl_add_u64 v[36:37], v[28:29], 0, s[68:69]
	s_mov_b32 m0, s35
	v_readfirstlane_b32 s34, v46
	v_lshl_add_u64 v[34:35], v[30:31], 0, 64
	global_load_lds_dwordx4 v[36:37], off
	s_mov_b32 m0, s34
	v_lshlrev_b32_e32 v36, 11, v43
	global_load_lds_dwordx4 v[34:35], off
	v_lshrrev_b32_e32 v35, 2, v42
	v_lshlrev_b32_e32 v34, 6, v42
	v_sub_u32_e32 v35, 0, v35
	v_and_b32_e32 v34, 0x3c0, v34
	v_bitop3_b32 v35, v44, v35, 3 bitop3:0x78
	v_lshl_or_b32 v34, v35, 4, v34
	v_lshlrev_b32_e32 v35, 5, v42
	v_and_or_b32 v35, v35, s49, v34
	s_waitcnt vmcnt(3)
	v_add_u32_e32 v120, 0, v35
	v_and_or_b32 v54, v36, s50, v34
	s_waitcnt lgkmcnt(0)
	s_barrier
	ds_read_b128 v[34:37], v120
	ds_read_b128 v[42:45], v120 offset:1024
	ds_read_b128 v[46:49], v120 offset:2048
	ds_read_b128 v[50:53], v120 offset:3072
	v_add_u32_e32 v121, 0, v54
	ds_read_b128 v[54:57], v121 offset:8192
	ds_read_b128 v[58:61], v121 offset:9216
	v_ashrrev_i32_e32 v95, 31, v94
	v_ashrrev_i32_e32 v101, 31, v100
	v_ashrrev_i32_e32 v99, 31, v98
	v_ashrrev_i32_e32 v97, 31, v96
	s_setprio 1
	v_add_u32_e32 v72, 0x6000, v78
	s_waitcnt lgkmcnt(0)
	v_mfma_f32_16x16x32_bf16 v[62:65], v[54:57], v[34:37], 0
	v_lshl_add_u64 v[74:75], v[30:31], 0, s[54:55]
	v_add_u32_e32 v79, 0x8000, v78
	v_lshl_add_u64 v[70:71], v[28:29], 0, s[54:55]
	v_mfma_f32_16x16x32_bf16 v[66:69], v[54:57], v[42:45], 0
	v_readfirstlane_b32 s39, v72
	s_mov_b32 m0, s39
	s_nop 0
	global_load_lds_dwordx4 v[70:71], off
	v_mfma_f32_16x16x32_bf16 v[70:73], v[54:57], v[46:49], 0
	v_mfma_f32_16x16x32_bf16 v[54:57], v[54:57], v[50:53], 0
	v_add_u32_e32 v78, 0x7000, v78
	v_lshl_add_u64 v[76:77], v[28:29], 0, s[96:97]
	v_readfirstlane_b32 s40, v78
	s_mov_b32 m0, s40
	s_nop 0
	global_load_lds_dwordx4 v[76:77], off
	v_mfma_f32_16x16x32_bf16 v[34:37], v[58:61], v[34:37], 0
	v_mfma_f32_16x16x32_bf16 v[42:45], v[58:61], v[42:45], 0
	v_readfirstlane_b32 s41, v79
	s_mov_b32 m0, s41
	s_nop 0
	global_load_lds_dwordx4 v[74:75], off
	v_mfma_f32_16x16x32_bf16 v[46:49], v[58:61], v[46:49], 0
	v_mfma_f32_16x16x32_bf16 v[50:53], v[58:61], v[50:53], 0
	s_setprio 0
	s_waitcnt vmcnt(3)
	s_waitcnt lgkmcnt(0)
	s_barrier
; #define RAW_BARRIER() do { asm volatile("s_waitcnt lgkmcnt(0)" ::: "memory"); __builtin_amdgcn_s_barrier(); } while (0)
;     ...
;     for (int kt = 0; kt < nk - 1; ++kt) {
;         if (NI == 8) asm volatile("s_waitcnt vmcnt(6)" ::: "memory"); else if (NI == 4) asm volatile("s_waitcnt vmcnt(4)" ::: "memory"); else asm volatile("s_waitcnt vmcnt(3)" ::: "memory");
;         RAW_BARRIER();
;         const int s2 = st >= 1 ? st - 1 : 2;
;         const bool ld = kt + 2 < nk;
;         STEP_TILE(st, ld, kt + 2, s2);
;         st = st == 2 ? 0 : st + 1;
;     }
	ds_read_b128 v[86:89], v121 offset:20480
	ds_read_b128 v[58:61], v120 offset:12288
	ds_read_b128 v[74:77], v120 offset:13312
	ds_read_b128 v[78:81], v120 offset:14336
	ds_read_b128 v[82:85], v120 offset:15360
	ds_read_b128 v[90:93], v121 offset:21504
	s_setprio 1
	s_waitcnt lgkmcnt(4)
	v_mfma_f32_16x16x32_bf16 v[62:65], v[86:89], v[58:61], v[62:65]
	v_lshl_add_u64 v[116:117], v[30:31], 0, s[56:57]
	v_lshl_add_u64 v[118:119], v[28:29], 0, s[56:57]
	s_waitcnt lgkmcnt(3)
	v_mfma_f32_16x16x32_bf16 v[66:69], v[86:89], v[74:77], v[66:69]
	s_mov_b32 m0, s44
	s_nop 0
	global_load_lds_dwordx4 v[118:119], off
	s_waitcnt lgkmcnt(2)
	v_mfma_f32_16x16x32_bf16 v[70:73], v[86:89], v[78:81], v[70:73]
	s_waitcnt lgkmcnt(1)
	v_mfma_f32_16x16x32_bf16 v[54:57], v[86:89], v[82:85], v[54:57]
	v_lshl_add_u64 v[86:87], v[28:29], 0, s[94:95]
	s_mov_b32 m0, s43
	s_nop 0
	global_load_lds_dwordx4 v[86:87], off
	s_waitcnt lgkmcnt(0)
	v_mfma_f32_16x16x32_bf16 v[34:37], v[90:93], v[58:61], v[34:37]
	v_mfma_f32_16x16x32_bf16 v[42:45], v[90:93], v[74:77], v[42:45]
	s_mov_b32 m0, s42
	s_nop 0
	global_load_lds_dwordx4 v[116:117], off
	v_mfma_f32_16x16x32_bf16 v[46:49], v[90:93], v[78:81], v[46:49]
	v_mfma_f32_16x16x32_bf16 v[50:53], v[90:93], v[82:85], v[50:53]
	s_setprio 0
	s_waitcnt vmcnt(3)
	s_waitcnt lgkmcnt(0)
	s_barrier
	ds_read_b128 v[86:89], v121 offset:32768
	ds_read_b128 v[58:61], v120 offset:24576
	ds_read_b128 v[74:77], v120 offset:25600
	ds_read_b128 v[78:81], v120 offset:26624
	ds_read_b128 v[82:85], v120 offset:27648
	ds_read_b128 v[90:93], v121 offset:33792
	s_setprio 1
	s_waitcnt lgkmcnt(4)
	v_mfma_f32_16x16x32_bf16 v[62:65], v[86:89], v[58:61], v[62:65]
	v_lshl_add_u64 v[116:117], v[30:31], 0, s[58:59]
	v_lshl_add_u64 v[118:119], v[28:29], 0, s[58:59]
	s_waitcnt lgkmcnt(3)
	v_mfma_f32_16x16x32_bf16 v[66:69], v[86:89], v[74:77], v[66:69]
	s_mov_b32 m0, s38
	s_nop 0
	global_load_lds_dwordx4 v[118:119], off
	s_waitcnt lgkmcnt(2)
	v_mfma_f32_16x16x32_bf16 v[70:73], v[86:89], v[78:81], v[70:73]
	s_waitcnt lgkmcnt(1)
	v_mfma_f32_16x16x32_bf16 v[54:57], v[86:89], v[82:85], v[54:57]
	v_lshl_add_u64 v[86:87], v[28:29], 0, s[70:71]
	s_mov_b32 m0, s35
	s_nop 0
	global_load_lds_dwordx4 v[86:87], off
	s_waitcnt lgkmcnt(0)
	v_mfma_f32_16x16x32_bf16 v[34:37], v[90:93], v[58:61], v[34:37]
	v_mfma_f32_16x16x32_bf16 v[42:45], v[90:93], v[74:77], v[42:45]
	s_mov_b32 m0, s34
	s_nop 0
	global_load_lds_dwordx4 v[116:117], off
	v_mfma_f32_16x16x32_bf16 v[46:49], v[90:93], v[78:81], v[46:49]
	v_mfma_f32_16x16x32_bf16 v[50:53], v[90:93], v[82:85], v[50:53]
	s_setprio 0
	s_waitcnt vmcnt(3)
	s_waitcnt lgkmcnt(0)
	s_barrier
	ds_read_b128 v[86:89], v121 offset:8192
	ds_read_b128 v[58:61], v120
	ds_read_b128 v[74:77], v120 offset:1024
	ds_read_b128 v[78:81], v120 offset:2048
	ds_read_b128 v[82:85], v120 offset:3072
	ds_read_b128 v[90:93], v121 offset:9216
	s_setprio 1
	s_waitcnt lgkmcnt(4)
	v_mfma_f32_16x16x32_bf16 v[62:65], v[86:89], v[58:61], v[62:65]
	v_lshl_add_u64 v[116:117], v[30:31], 0, s[60:61]
	v_lshl_add_u64 v[118:119], v[28:29], 0, s[60:61]
	s_waitcnt lgkmcnt(3)
	v_mfma_f32_16x16x32_bf16 v[66:69], v[86:89], v[74:77], v[66:69]
	s_mov_b32 m0, s39
	s_nop 0
	global_load_lds_dwordx4 v[118:119], off
	s_waitcnt lgkmcnt(2)
	v_mfma_f32_16x16x32_bf16 v[70:73], v[86:89], v[78:81], v[70:73]
	s_waitcnt lgkmcnt(1)
	v_mfma_f32_16x16x32_bf16 v[54:57], v[86:89], v[82:85], v[54:57]
	v_lshl_add_u64 v[86:87], v[28:29], 0, s[72:73]
	s_mov_b32 m0, s40
	s_nop 0
	global_load_lds_dwordx4 v[86:87], off
	s_waitcnt lgkmcnt(0)
	v_mfma_f32_16x16x32_bf16 v[34:37], v[90:93], v[58:61], v[34:37]
	v_mfma_f32_16x16x32_bf16 v[42:45], v[90:93], v[74:77], v[42:45]
	s_mov_b32 m0, s41
	s_nop 0
	global_load_lds_dwordx4 v[116:117], off
	v_mfma_f32_16x16x32_bf16 v[46:49], v[90:93], v[78:81], v[46:49]
	v_mfma_f32_16x16x32_bf16 v[50:53], v[90:93], v[82:85], v[50:53]
	s_setprio 0
	s_waitcnt vmcnt(3)
	s_waitcnt lgkmcnt(0)
	s_barrier
	ds_read_b128 v[86:89], v121 offset:20480
	ds_read_b128 v[58:61], v120 offset:12288
	ds_read_b128 v[74:77], v120 offset:13312
	ds_read_b128 v[78:81], v120 offset:14336
	ds_read_b128 v[82:85], v120 offset:15360
	ds_read_b128 v[90:93], v121 offset:21504
	s_setprio 1
	s_waitcnt lgkmcnt(4)
	v_mfma_f32_16x16x32_bf16 v[62:65], v[86:89], v[58:61], v[62:65]
	v_lshl_add_u64 v[116:117], v[30:31], 0, s[62:63]
	v_lshl_add_u64 v[118:119], v[28:29], 0, s[62:63]
	s_waitcnt lgkmcnt(3)
	v_mfma_f32_16x16x32_bf16 v[66:69], v[86:89], v[74:77], v[66:69]
	s_mov_b32 m0, s44
	s_nop 0
	global_load_lds_dwordx4 v[118:119], off
	s_waitcnt lgkmcnt(2)
	v_mfma_f32_16x16x32_bf16 v[70:73], v[86:89], v[78:81], v[70:73]
	s_waitcnt lgkmcnt(1)
	v_mfma_f32_16x16x32_bf16 v[54:57], v[86:89], v[82:85], v[54:57]
	v_lshl_add_u64 v[86:87], v[28:29], 0, s[84:85]
	s_mov_b32 m0, s43
	s_nop 0
	global_load_lds_dwordx4 v[86:87], off
	s_waitcnt lgkmcnt(0)
	v_mfma_f32_16x16x32_bf16 v[34:37], v[90:93], v[58:61], v[34:37]
	v_mfma_f32_16x16x32_bf16 v[42:45], v[90:93], v[74:77], v[42:45]
	s_mov_b32 m0, s42
	s_nop 0
	global_load_lds_dwordx4 v[116:117], off
	v_mfma_f32_16x16x32_bf16 v[46:49], v[90:93], v[78:81], v[46:49]
	v_mfma_f32_16x16x32_bf16 v[50:53], v[90:93], v[82:85], v[50:53]
	s_setprio 0
	s_waitcnt vmcnt(3)
	s_waitcnt lgkmcnt(0)
	s_barrier
; #define RAW_BARRIER() do { asm volatile("s_waitcnt lgkmcnt(0)" ::: "memory"); __builtin_amdgcn_s_barrier(); } while (0)
;     ...
;     for (int kt = 0; kt < nk - 1; ++kt) {
;         if (NI == 8) asm volatile("s_waitcnt vmcnt(6)" ::: "memory"); else if (NI == 4) asm volatile("s_waitcnt vmcnt(4)" ::: "memory"); else asm volatile("s_waitcnt vmcnt(3)" ::: "memory");
;         RAW_BARRIER();
;         const int s2 = st >= 1 ? st - 1 : 2;
;         const bool ld = kt + 2 < nk;
;         STEP_TILE(st, ld, kt + 2, s2);
;         st = st == 2 ? 0 : st + 1;
;     }
	ds_read_b128 v[86:89], v121 offset:32768
	ds_read_b128 v[58:61], v120 offset:24576
	ds_read_b128 v[74:77], v120 offset:25600
	ds_read_b128 v[78:81], v120 offset:26624
	ds_read_b128 v[82:85], v120 offset:27648
	ds_read_b128 v[90:93], v121 offset:33792
	s_setprio 1
	s_waitcnt lgkmcnt(4)
	v_mfma_f32_16x16x32_bf16 v[62:65], v[86:89], v[58:61], v[62:65]
	v_lshl_add_u64 v[116:117], v[30:31], 0, s[64:65]
	v_lshl_add_u64 v[118:119], v[28:29], 0, s[64:65]
	s_waitcnt lgkmcnt(3)
	v_mfma_f32_16x16x32_bf16 v[66:69], v[86:89], v[74:77], v[66:69]
	s_mov_b32 m0, s38
	s_nop 0
	global_load_lds_dwordx4 v[118:119], off
	s_waitcnt lgkmcnt(2)
	v_mfma_f32_16x16x32_bf16 v[70:73], v[86:89], v[78:81], v[70:73]
	s_waitcnt lgkmcnt(1)
	v_mfma_f32_16x16x32_bf16 v[54:57], v[86:89], v[82:85], v[54:57]
	v_lshl_add_u64 v[86:87], v[28:29], 0, vcc
	s_mov_b32 m0, s35
	s_nop 0
	global_load_lds_dwordx4 v[86:87], off
	s_waitcnt lgkmcnt(0)
	v_mfma_f32_16x16x32_bf16 v[34:37], v[90:93], v[58:61], v[34:37]
	v_mfma_f32_16x16x32_bf16 v[42:45], v[90:93], v[74:77], v[42:45]
	s_mov_b32 m0, s34
	s_nop 0
	global_load_lds_dwordx4 v[116:117], off
	v_mfma_f32_16x16x32_bf16 v[46:49], v[90:93], v[78:81], v[46:49]
	v_mfma_f32_16x16x32_bf16 v[50:53], v[90:93], v[82:85], v[50:53]
	s_setprio 0
	s_waitcnt vmcnt(3)
	s_waitcnt lgkmcnt(0)
	s_barrier
	ds_read_b128 v[86:89], v121 offset:8192
	ds_read_b128 v[58:61], v120
	ds_read_b128 v[74:77], v120 offset:1024
	ds_read_b128 v[78:81], v120 offset:2048
	ds_read_b128 v[82:85], v120 offset:3072
	ds_read_b128 v[90:93], v121 offset:9216
	s_setprio 1
	s_waitcnt lgkmcnt(4)
	v_mfma_f32_16x16x32_bf16 v[62:65], v[86:89], v[58:61], v[62:65]
	v_lshl_add_u64 v[116:117], v[30:31], 0, s[76:77]
	v_lshl_add_u64 v[118:119], v[28:29], 0, s[76:77]
	s_mov_b64 s[76:77], 0x8040
	s_mov_b64 s[46:47], 0x8000
	s_waitcnt lgkmcnt(3)
	v_mfma_f32_16x16x32_bf16 v[66:69], v[86:89], v[74:77], v[66:69]
	s_mov_b32 m0, s39
	s_nop 0
	global_load_lds_dwordx4 v[118:119], off
	s_waitcnt lgkmcnt(2)
	v_mfma_f32_16x16x32_bf16 v[70:73], v[86:89], v[78:81], v[70:73]
	s_waitcnt lgkmcnt(1)
	v_mfma_f32_16x16x32_bf16 v[54:57], v[86:89], v[82:85], v[54:57]
	v_lshl_add_u64 v[86:87], v[28:29], 0, s[16:17]
	s_mov_b32 m0, s40
	s_nop 0
	global_load_lds_dwordx4 v[86:87], off
	s_waitcnt lgkmcnt(0)
	v_mfma_f32_16x16x32_bf16 v[34:37], v[90:93], v[58:61], v[34:37]
	v_mfma_f32_16x16x32_bf16 v[42:45], v[90:93], v[74:77], v[42:45]
	s_mov_b32 m0, s41
	s_nop 0
	global_load_lds_dwordx4 v[116:117], off
	v_mfma_f32_16x16x32_bf16 v[46:49], v[90:93], v[78:81], v[46:49]
	v_mfma_f32_16x16x32_bf16 v[50:53], v[90:93], v[82:85], v[50:53]
	s_setprio 0
	s_waitcnt vmcnt(3)
	s_waitcnt lgkmcnt(0)
	s_barrier
	ds_read_b128 v[86:89], v121 offset:20480
	ds_read_b128 v[58:61], v120 offset:12288
	ds_read_b128 v[74:77], v120 offset:13312
	ds_read_b128 v[78:81], v120 offset:14336
	ds_read_b128 v[82:85], v120 offset:15360
	ds_read_b128 v[90:93], v121 offset:21504
	s_setprio 1
	s_waitcnt lgkmcnt(4)
	v_mfma_f32_16x16x32_bf16 v[62:65], v[86:89], v[58:61], v[62:65]
	v_lshl_add_u64 v[116:117], v[30:31], 0, s[86:87]
	v_lshl_add_u64 v[118:119], v[28:29], 0, s[86:87]
	s_waitcnt lgkmcnt(3)
	v_mfma_f32_16x16x32_bf16 v[66:69], v[86:89], v[74:77], v[66:69]
	s_mov_b32 m0, s44
	s_nop 0
	global_load_lds_dwordx4 v[118:119], off
	s_waitcnt lgkmcnt(2)
	v_mfma_f32_16x16x32_bf16 v[70:73], v[86:89], v[78:81], v[70:73]
	s_waitcnt lgkmcnt(1)
	v_mfma_f32_16x16x32_bf16 v[54:57], v[86:89], v[82:85], v[54:57]
	v_lshl_add_u64 v[86:87], v[28:29], 0, s[90:91]
	s_mov_b32 m0, s43
	s_nop 0
	global_load_lds_dwordx4 v[86:87], off
	s_waitcnt lgkmcnt(0)
	v_mfma_f32_16x16x32_bf16 v[34:37], v[90:93], v[58:61], v[34:37]
	v_mfma_f32_16x16x32_bf16 v[42:45], v[90:93], v[74:77], v[42:45]
	s_mov_b32 m0, s42
	s_nop 0
	global_load_lds_dwordx4 v[116:117], off
	v_mfma_f32_16x16x32_bf16 v[46:49], v[90:93], v[78:81], v[46:49]
	v_mfma_f32_16x16x32_bf16 v[50:53], v[90:93], v[82:85], v[50:53]
	s_setprio 0
	s_waitcnt vmcnt(3)
	s_waitcnt lgkmcnt(0)
	s_barrier
	ds_read_b128 v[86:89], v121 offset:32768
	ds_read_b128 v[58:61], v120 offset:24576
	ds_read_b128 v[74:77], v120 offset:25600
	ds_read_b128 v[78:81], v120 offset:26624
	ds_read_b128 v[82:85], v120 offset:27648
	ds_read_b128 v[90:93], v121 offset:33792
	s_setprio 1
	s_waitcnt lgkmcnt(4)
	v_mfma_f32_16x16x32_bf16 v[62:65], v[86:89], v[58:61], v[62:65]
	v_lshl_add_u64 v[116:117], v[30:31], 0, s[88:89]
	v_lshl_add_u64 v[118:119], v[28:29], 0, s[88:89]
	s_waitcnt lgkmcnt(3)
	v_mfma_f32_16x16x32_bf16 v[66:69], v[86:89], v[74:77], v[66:69]
	s_mov_b32 m0, s38
	s_nop 0
	global_load_lds_dwordx4 v[118:119], off
	s_waitcnt lgkmcnt(2)
	v_mfma_f32_16x16x32_bf16 v[70:73], v[86:89], v[78:81], v[70:73]
	s_waitcnt lgkmcnt(1)
	v_mfma_f32_16x16x32_bf16 v[54:57], v[86:89], v[82:85], v[54:57]
	v_lshl_add_u64 v[86:87], v[28:29], 0, s[92:93]
	s_mov_b32 m0, s35
	s_nop 0
	global_load_lds_dwordx4 v[86:87], off
	s_waitcnt lgkmcnt(0)
	v_mfma_f32_16x16x32_bf16 v[34:37], v[90:93], v[58:61], v[34:37]
	v_mfma_f32_16x16x32_bf16 v[42:45], v[90:93], v[74:77], v[42:45]
	s_mov_b32 m0, s34
	s_nop 0
	global_load_lds_dwordx4 v[116:117], off
	v_mfma_f32_16x16x32_bf16 v[46:49], v[90:93], v[78:81], v[46:49]
	v_mfma_f32_16x16x32_bf16 v[50:53], v[90:93], v[82:85], v[50:53]
	s_setprio 0
	s_waitcnt vmcnt(3)
	s_waitcnt lgkmcnt(0)
	s_barrier
;     __device__ __forceinline__ bf16_t* G() const { return (bf16_t*)(ws + OFF_G); }
; DEV void ld_bf4(const bf16_t* p, float (&v)[4]) { uint2 w = *(const uint2*)p; v[0] = bf_lo(w.x); v[1] = bf_hi(w.x); v[2] = bf_lo(w.y); v[3] = bf_hi(w.y); }
; #define RAW_BARRIER() do { asm volatile("s_waitcnt lgkmcnt(0)" ::: "memory"); __builtin_amdgcn_s_barrier(); } while (0)
; #define GLDS_TILE(kt, st) do { _Pragma("unroll") for (int _i = 0; _i < NP; ++_i) GLDS_PIECE(_i, kt, st); } while (0)
;     ...
;     constexpr int NH = NI >= 4 ? NI / 2 : NI;
;     constexpr int NP = 2 + NB, IVL = (4 * NI) / NP;
;     RAW_BARRIER();
;     GLDS_TILE(0, 0);
;     GLDS_TILE(1, 1);
;     int st = 0;
;     for (int kt = 0; kt < nk - 1; ++kt) {
;         if (NI == 8) asm volatile("s_waitcnt vmcnt(6)" ::: "memory"); else if (NI == 4) asm volatile("s_waitcnt vmcnt(4)" ::: "memory"); else asm volatile("s_waitcnt vmcnt(3)" ::: "memory");
;         RAW_BARRIER();
;         const int s2 = st >= 1 ? st - 1 : 2;
;         const bool ld = kt + 2 < nk;
;         STEP_TILE(st, ld, kt + 2, s2);
;         st = st == 2 ? 0 : st + 1;
;     }
;     asm volatile("s_waitcnt vmcnt(0)" ::: "memory");
;     RAW_BARRIER();
;     STEP_TILE(st, false, 0, 0);
; DEV void merge_big(const Params& p, int l, int mt, int nt, char* smem) {
;     ...
; #pragma unroll
;         for (int mi = 0; mi < 4; ++mi)
; #pragma unroll
;             for (int ni = 0; ni < 2; ++ni) {
;                 float g[4]; ld_bf4(p.G() + (size_t)(rbase + mi * 16) * 3072 + br * 1024 + c0 + ni * 16, g);
;                 const f32x4 gv = (f32x4){g[0], g[1], g[2], g[3]};
;                 if (br == 0) mg[mi][ni] = gv * acc[mi][ni]; else mg[mi][ni] += gv * acc[mi][ni];
	ds_read_b128 v[86:89], v121 offset:8192
	ds_read_b128 v[58:61], v120
	ds_read_b128 v[74:77], v120 offset:1024
	ds_read_b128 v[78:81], v120 offset:2048
	ds_read_b128 v[82:85], v120 offset:3072
	ds_read_b128 v[90:93], v121 offset:9216
	s_setprio 1
	s_waitcnt lgkmcnt(4)
	v_mfma_f32_16x16x32_bf16 v[62:65], v[86:89], v[58:61], v[62:65]
	v_lshl_add_u64 v[116:117], v[30:31], 0, s[78:79]
	v_lshl_add_u64 v[30:31], v[28:29], 0, s[78:79]
	s_waitcnt lgkmcnt(3)
	v_mfma_f32_16x16x32_bf16 v[66:69], v[86:89], v[74:77], v[66:69]
	s_mov_b32 m0, s39
	s_nop 0
	global_load_lds_dwordx4 v[30:31], off
	s_waitcnt lgkmcnt(2)
	v_mfma_f32_16x16x32_bf16 v[70:73], v[86:89], v[78:81], v[70:73]
	s_waitcnt lgkmcnt(1)
	v_mfma_f32_16x16x32_bf16 v[54:57], v[86:89], v[82:85], v[54:57]
	v_lshl_add_u64 v[28:29], v[28:29], 0, s[80:81]
	s_mov_b32 m0, s40
	s_nop 0
	global_load_lds_dwordx4 v[28:29], off
	s_waitcnt lgkmcnt(0)
	v_mfma_f32_16x16x32_bf16 v[28:31], v[90:93], v[58:61], v[34:37]
	v_mfma_f32_16x16x32_bf16 v[34:37], v[90:93], v[74:77], v[42:45]
	s_mov_b32 m0, s41
	s_nop 0
	global_load_lds_dwordx4 v[116:117], off
	v_mfma_f32_16x16x32_bf16 v[42:45], v[90:93], v[78:81], v[46:49]
	v_mfma_f32_16x16x32_bf16 v[46:49], v[90:93], v[82:85], v[50:53]
	s_setprio 0
	s_waitcnt vmcnt(3)
	s_waitcnt lgkmcnt(0)
	s_barrier
	s_nop 0
	ds_read_b128 v[50:53], v120 offset:12288
	ds_read_b128 v[58:61], v120 offset:13312
	ds_read_b128 v[74:77], v120 offset:14336
	ds_read_b128 v[78:81], v120 offset:15360
	ds_read_b128 v[82:85], v121 offset:20480
	ds_read_b128 v[86:89], v121 offset:21504
	s_setprio 1
	s_waitcnt lgkmcnt(0)
	v_mfma_f32_16x16x32_bf16 v[62:65], v[82:85], v[50:53], v[62:65]
	v_mfma_f32_16x16x32_bf16 v[66:69], v[82:85], v[58:61], v[66:69]
	v_mfma_f32_16x16x32_bf16 v[70:73], v[82:85], v[74:77], v[70:73]
	v_mfma_f32_16x16x32_bf16 v[54:57], v[82:85], v[78:81], v[54:57]
	v_mfma_f32_16x16x32_bf16 v[82:85], v[86:89], v[50:53], v[28:31]
	v_mfma_f32_16x16x32_bf16 v[58:61], v[86:89], v[58:61], v[34:37]
	v_mfma_f32_16x16x32_bf16 v[74:77], v[86:89], v[74:77], v[42:45]
	v_mfma_f32_16x16x32_bf16 v[78:81], v[86:89], v[78:81], v[46:49]
	s_setprio 0
	s_waitcnt vmcnt(0)
	s_waitcnt lgkmcnt(0)
	s_barrier
	ds_read_b128 v[116:119], v121 offset:32768
	ds_read_b128 v[34:37], v120 offset:24576
	ds_read_b128 v[46:49], v120 offset:25600
	ds_read_b128 v[86:89], v120 offset:26624
	ds_read_b128 v[90:93], v120 offset:27648
	ds_read_b128 v[124:127], v121 offset:33792
	s_setprio 1
	s_waitcnt lgkmcnt(4)
	v_mfma_f32_16x16x32_bf16 v[28:31], v[116:119], v[34:37], v[62:65]
	s_waitcnt lgkmcnt(3)
	v_mfma_f32_16x16x32_bf16 v[42:45], v[116:119], v[46:49], v[66:69]
	s_waitcnt lgkmcnt(2)
	v_mfma_f32_16x16x32_bf16 v[50:53], v[116:119], v[86:89], v[70:73]
	s_waitcnt lgkmcnt(1)
	v_mfma_f32_16x16x32_bf16 v[66:69], v[116:119], v[90:93], v[54:57]
	s_waitcnt lgkmcnt(0)
	v_mfma_f32_16x16x32_bf16 v[34:37], v[124:127], v[34:37], v[82:85]
	v_mfma_f32_16x16x32_bf16 v[46:49], v[124:127], v[46:49], v[58:61]
	v_mfma_f32_16x16x32_bf16 v[54:57], v[124:127], v[86:89], v[74:77]
	v_mfma_f32_16x16x32_bf16 v[82:85], v[124:127], v[90:93], v[78:81]
	s_setprio 0
	v_lshl_add_u64 v[58:59], s[4:5], 0, v[32:33]
	v_mad_i64_i32 v[60:61], s[34:35], v94, s51, v[58:59]
	s_waitcnt lgkmcnt(0)
	s_barrier
	v_mad_i64_i32 v[62:63], s[34:35], v100, s51, v[58:59]
	s_waitcnt vmcnt(0)
	flat_load_dwordx2 v[116:117], v[60:61]
	flat_load_dwordx2 v[118:119], v[60:61] offset:32
	flat_load_dwordx2 v[120:121], v[62:63]
	flat_load_dwordx2 v[124:125], v[62:63] offset:32
	v_mad_i64_i32 v[60:61], s[34:35], v98, s51, v[58:59]
	v_mad_i64_i32 v[58:59], s[34:35], v96, s51, v[58:59]
	v_mov_b32_e32 v70, v186
	flat_load_dwordx2 v[126:127], v[60:61]
	flat_load_dwordx2 v[128:129], v[60:61] offset:32
	flat_load_dwordx2 v[134:135], v[58:59]
	flat_load_dwordx2 v[142:143], v[58:59] offset:32
	s_add_u32 s10, s22, s10
	v_ashrrev_i32_e32 v71, 6, v70
	v_bfe_u32 v72, v70, 4, 2
	v_bfe_u32 v58, v70, 2, 4
	v_lshl_or_b32 v58, v71, 4, v58
	v_sub_u32_e32 v59, 0, v72
	s_addc_u32 s11, s23, s11
	v_xor_b32_e32 v62, v70, v59
	v_ashrrev_i32_e32 v59, 31, v58
	s_add_u32 s34, s28, s31
	v_lshlrev_b64 v[60:61], 9, v[58:59]
	v_lshlrev_b32_e32 v62, 4, v62
	v_lshl_add_u32 v150, v71, 10, 0
	s_addc_u32 s35, s29, 0
	v_lshl_add_u64 v[58:59], s[10:11], 0, v[60:61]
	v_and_b32_e32 v62, 48, v62
	v_mov_b32_e32 v63, v33
	v_readfirstlane_b32 s38, v150
	v_add_u32_e32 v65, 0x1000, v150
	v_lshl_add_u64 v[58:59], v[58:59], 0, v[62:63]
	v_lshl_add_u64 v[60:61], s[34:35], 0, v[60:61]
	v_add_u32_e32 v64, 0x2000, v150
	s_mov_b32 m0, s38
	v_readfirstlane_b32 s35, v65
	v_lshl_add_u64 v[60:61], v[60:61], 0, v[62:63]
	s_waitcnt lgkmcnt(0)
	s_barrier
	global_load_lds_dwordx4 v[58:59], off
	v_lshl_add_u64 v[62:63], v[58:59], 0, s[46:47]
	s_mov_b32 m0, s35
	v_readfirstlane_b32 s34, v64
	v_add_u32_e32 v73, 0x3000, v150
	global_load_lds_dwordx4 v[62:63], off
	s_mov_b32 m0, s34
	v_readfirstlane_b32 s31, v73
	v_add_u32_e32 v73, 0x4000, v150
	global_load_lds_dwordx4 v[60:61], off
	v_add_u32_e32 v74, 0x5000, v150
	v_lshl_add_u64 v[64:65], v[58:59], 0, 64
	s_mov_b32 m0, s31
	v_readfirstlane_b32 s11, v73
	global_load_lds_dwordx4 v[64:65], off
	v_lshl_add_u64 v[64:65], v[58:59], 0, s[76:77]
	s_mov_b32 m0, s11
	v_readfirstlane_b32 s10, v74
	v_lshl_add_u64 v[62:63], v[60:61], 0, 64
	global_load_lds_dwordx4 v[64:65], off
	s_mov_b32 m0, s10
	v_lshlrev_b32_e32 v64, 11, v71
	global_load_lds_dwordx4 v[62:63], off
	v_lshrrev_b32_e32 v63, 2, v70
	v_lshlrev_b32_e32 v62, 6, v70
	v_sub_u32_e32 v63, 0, v63
	v_and_b32_e32 v62, 0x3c0, v62
	v_bitop3_b32 v63, v72, v63, 3 bitop3:0x78
	v_lshl_or_b32 v62, v63, 4, v62
	v_lshlrev_b32_e32 v63, 5, v70
	v_and_or_b32 v63, v63, s49, v62
	s_waitcnt vmcnt(3)
	v_add_u32_e32 v155, 0, v63
	v_and_or_b32 v86, v64, s50, v62
	s_waitcnt lgkmcnt(0)
	s_barrier
; #define RAW_BARRIER() do { asm volatile("s_waitcnt lgkmcnt(0)" ::: "memory"); __builtin_amdgcn_s_barrier(); } while (0)
; #define GLDS_TILE(kt, st) do { _Pragma("unroll") for (int _i = 0; _i < NP; ++_i) GLDS_PIECE(_i, kt, st); } while (0)
;     ...
;     constexpr int NH = NI >= 4 ? NI / 2 : NI;
;     constexpr int NP = 2 + NB, IVL = (4 * NI) / NP;
;     RAW_BARRIER();
;     GLDS_TILE(0, 0);
;     GLDS_TILE(1, 1);
;     int st = 0;
;     for (int kt = 0; kt < nk - 1; ++kt) {
;         if (NI == 8) asm volatile("s_waitcnt vmcnt(6)" ::: "memory"); else if (NI == 4) asm volatile("s_waitcnt vmcnt(4)" ::: "memory"); else asm volatile("s_waitcnt vmcnt(3)" ::: "memory");
;         RAW_BARRIER();
;         const int s2 = st >= 1 ? st - 1 : 2;
;         const bool ld = kt + 2 < nk;
;         STEP_TILE(st, ld, kt + 2, s2);
;         st = st == 2 ? 0 : st + 1;
;     }
;     asm volatile("s_waitcnt vmcnt(0)" ::: "memory");
;     RAW_BARRIER();
;     STEP_TILE(st, false, 0, 0);
	ds_read_b128 v[62:65], v155
	ds_read_b128 v[70:73], v155 offset:1024
	ds_read_b128 v[74:77], v155 offset:2048
	ds_read_b128 v[78:81], v155 offset:3072
	v_add_u32_e32 v157, 0, v86
	ds_read_b128 v[86:89], v157 offset:8192
	ds_read_b128 v[90:93], v157 offset:9216
	s_mov_b64 s[76:77], 0x8180
	s_mov_b64 s[46:47], 0x8140
	s_mov_b64 s[44:45], 0x8100
	s_mov_b64 s[42:43], 0x80c0
	s_mov_b64 s[16:17], 0x8080
	s_setprio 1
	v_add_u32_e32 v146, 0x6000, v150
	s_waitcnt lgkmcnt(0)
	v_mfma_f32_16x16x32_bf16 v[130:133], v[86:89], v[62:65], 0
	v_lshl_add_u64 v[140:141], v[60:61], 0, s[54:55]
	v_add_u32_e32 v151, 0x8000, v150
	v_lshl_add_u64 v[144:145], v[58:59], 0, s[54:55]
	v_mfma_f32_16x16x32_bf16 v[136:139], v[86:89], v[70:73], 0
	v_readfirstlane_b32 s39, v146
	s_mov_b32 m0, s39
	s_nop 0
	global_load_lds_dwordx4 v[144:145], off
	v_mfma_f32_16x16x32_bf16 v[144:147], v[86:89], v[74:77], 0
	v_mfma_f32_16x16x32_bf16 v[86:89], v[86:89], v[78:81], 0
	v_add_u32_e32 v150, 0x7000, v150
	v_lshl_add_u64 v[148:149], v[58:59], 0, s[16:17]
	v_readfirstlane_b32 s40, v150
	s_mov_b32 m0, s40
	s_nop 0
	global_load_lds_dwordx4 v[148:149], off
	v_mfma_f32_16x16x32_bf16 v[62:65], v[90:93], v[62:65], 0
	v_mfma_f32_16x16x32_bf16 v[70:73], v[90:93], v[70:73], 0
	v_readfirstlane_b32 s41, v151
	s_mov_b32 m0, s41
	s_nop 0
	global_load_lds_dwordx4 v[140:141], off
	v_mfma_f32_16x16x32_bf16 v[74:77], v[90:93], v[74:77], 0
	v_mfma_f32_16x16x32_bf16 v[78:81], v[90:93], v[78:81], 0
	s_setprio 0
	s_waitcnt vmcnt(3)
	s_waitcnt lgkmcnt(0)
	s_barrier
	ds_read_b128 v[166:169], v157 offset:20480
	ds_read_b128 v[90:93], v155 offset:12288
	ds_read_b128 v[148:151], v155 offset:13312
	ds_read_b128 v[158:161], v155 offset:14336
	ds_read_b128 v[162:165], v155 offset:15360
	ds_read_b128 v[170:173], v157 offset:21504
	s_setprio 1
	s_waitcnt lgkmcnt(4)
	v_mfma_f32_16x16x32_bf16 v[130:133], v[166:169], v[90:93], v[130:133]
	v_lshl_add_u64 v[140:141], v[60:61], 0, s[56:57]
	v_lshl_add_u64 v[152:153], v[58:59], 0, s[56:57]
	s_waitcnt lgkmcnt(3)
	v_mfma_f32_16x16x32_bf16 v[136:139], v[166:169], v[148:151], v[136:139]
	s_mov_b32 m0, s38
	s_nop 0
	global_load_lds_dwordx4 v[152:153], off
	s_waitcnt lgkmcnt(2)
	v_mfma_f32_16x16x32_bf16 v[144:147], v[166:169], v[158:161], v[144:147]
	s_waitcnt lgkmcnt(1)
	v_mfma_f32_16x16x32_bf16 v[86:89], v[166:169], v[162:165], v[86:89]
	v_lshl_add_u64 v[152:153], v[58:59], 0, s[42:43]
	s_mov_b32 m0, s35
	s_nop 0
	global_load_lds_dwordx4 v[152:153], off
	s_waitcnt lgkmcnt(0)
	v_mfma_f32_16x16x32_bf16 v[62:65], v[170:173], v[90:93], v[62:65]
	v_mfma_f32_16x16x32_bf16 v[70:73], v[170:173], v[148:151], v[70:73]
	s_mov_b32 m0, s34
	s_nop 0
	global_load_lds_dwordx4 v[140:141], off
	v_mfma_f32_16x16x32_bf16 v[74:77], v[170:173], v[158:161], v[74:77]
	v_mfma_f32_16x16x32_bf16 v[78:81], v[170:173], v[162:165], v[78:81]
	s_setprio 0
	s_waitcnt vmcnt(3)
	s_waitcnt lgkmcnt(0)
	s_barrier
	ds_read_b128 v[166:169], v157 offset:32768
	ds_read_b128 v[90:93], v155 offset:24576
	ds_read_b128 v[148:151], v155 offset:25600
	ds_read_b128 v[158:161], v155 offset:26624
	ds_read_b128 v[162:165], v155 offset:27648
	ds_read_b128 v[170:173], v157 offset:33792
	s_setprio 1
	s_waitcnt lgkmcnt(4)
	v_mfma_f32_16x16x32_bf16 v[130:133], v[166:169], v[90:93], v[130:133]
	v_lshl_add_u64 v[140:141], v[60:61], 0, s[58:59]
	v_lshl_add_u64 v[152:153], v[58:59], 0, s[58:59]
	s_waitcnt lgkmcnt(3)
	v_mfma_f32_16x16x32_bf16 v[136:139], v[166:169], v[148:151], v[136:139]
	s_mov_b32 m0, s31
	s_nop 0
	global_load_lds_dwordx4 v[152:153], off
	s_waitcnt lgkmcnt(2)
	v_mfma_f32_16x16x32_bf16 v[144:147], v[166:169], v[158:161], v[144:147]
	s_waitcnt lgkmcnt(1)
	v_mfma_f32_16x16x32_bf16 v[86:89], v[166:169], v[162:165], v[86:89]
	v_lshl_add_u64 v[152:153], v[58:59], 0, s[44:45]
	s_mov_b32 m0, s11
	s_nop 0
	global_load_lds_dwordx4 v[152:153], off
	s_waitcnt lgkmcnt(0)
	v_mfma_f32_16x16x32_bf16 v[62:65], v[170:173], v[90:93], v[62:65]
	v_mfma_f32_16x16x32_bf16 v[70:73], v[170:173], v[148:151], v[70:73]
	s_mov_b32 m0, s10
	s_nop 0
	global_load_lds_dwordx4 v[140:141], off
	v_mfma_f32_16x16x32_bf16 v[74:77], v[170:173], v[158:161], v[74:77]
	v_mfma_f32_16x16x32_bf16 v[78:81], v[170:173], v[162:165], v[78:81]
	s_setprio 0
	s_waitcnt vmcnt(3)
	s_waitcnt lgkmcnt(0)
	s_barrier
	ds_read_b128 v[166:169], v157 offset:8192
	ds_read_b128 v[90:93], v155
	ds_read_b128 v[148:151], v155 offset:1024
	ds_read_b128 v[158:161], v155 offset:2048
	ds_read_b128 v[162:165], v155 offset:3072
	ds_read_b128 v[170:173], v157 offset:9216
	s_setprio 1
	s_waitcnt lgkmcnt(4)
	v_mfma_f32_16x16x32_bf16 v[130:133], v[166:169], v[90:93], v[130:133]
	v_lshl_add_u64 v[140:141], v[60:61], 0, s[60:61]
	v_lshl_add_u64 v[152:153], v[58:59], 0, s[60:61]
	s_waitcnt lgkmcnt(3)
	v_mfma_f32_16x16x32_bf16 v[136:139], v[166:169], v[148:151], v[136:139]
	s_mov_b32 m0, s39
	s_nop 0
	global_load_lds_dwordx4 v[152:153], off
	s_waitcnt lgkmcnt(2)
	v_mfma_f32_16x16x32_bf16 v[144:147], v[166:169], v[158:161], v[144:147]
	s_waitcnt lgkmcnt(1)
	v_mfma_f32_16x16x32_bf16 v[86:89], v[166:169], v[162:165], v[86:89]
	v_lshl_add_u64 v[152:153], v[58:59], 0, s[46:47]
	s_mov_b32 m0, s40
	s_nop 0
	global_load_lds_dwordx4 v[152:153], off
	s_waitcnt lgkmcnt(0)
	v_mfma_f32_16x16x32_bf16 v[62:65], v[170:173], v[90:93], v[62:65]
	v_mfma_f32_16x16x32_bf16 v[70:73], v[170:173], v[148:151], v[70:73]
	s_mov_b32 m0, s41
	s_nop 0
	global_load_lds_dwordx4 v[140:141], off
	v_mfma_f32_16x16x32_bf16 v[74:77], v[170:173], v[158:161], v[74:77]
	v_mfma_f32_16x16x32_bf16 v[78:81], v[170:173], v[162:165], v[78:81]
	s_setprio 0
	s_waitcnt vmcnt(3)
	s_waitcnt lgkmcnt(0)
	s_barrier
;     __device__ __forceinline__ bf16_t* G() const { return (bf16_t*)(ws + OFF_G); }
; DEV void ld_bf4(const bf16_t* p, float (&v)[4]) { uint2 w = *(const uint2*)p; v[0] = bf_lo(w.x); v[1] = bf_hi(w.x); v[2] = bf_lo(w.y); v[3] = bf_hi(w.y); }
; #define RAW_BARRIER() do { asm volatile("s_waitcnt lgkmcnt(0)" ::: "memory"); __builtin_amdgcn_s_barrier(); } while (0)
; #define GLDS_TILE(kt, st) do { _Pragma("unroll") for (int _i = 0; _i < NP; ++_i) GLDS_PIECE(_i, kt, st); } while (0)
;     ...
;     constexpr int NH = NI >= 4 ? NI / 2 : NI;
;     constexpr int NP = 2 + NB, IVL = (4 * NI) / NP;
;     RAW_BARRIER();
;     GLDS_TILE(0, 0);
;     GLDS_TILE(1, 1);
;     int st = 0;
;     for (int kt = 0; kt < nk - 1; ++kt) {
;         if (NI == 8) asm volatile("s_waitcnt vmcnt(6)" ::: "memory"); else if (NI == 4) asm volatile("s_waitcnt vmcnt(4)" ::: "memory"); else asm volatile("s_waitcnt vmcnt(3)" ::: "memory");
;         RAW_BARRIER();
;         const int s2 = st >= 1 ? st - 1 : 2;
;         const bool ld = kt + 2 < nk;
;         STEP_TILE(st, ld, kt + 2, s2);
;         st = st == 2 ? 0 : st + 1;
;     }
;     asm volatile("s_waitcnt vmcnt(0)" ::: "memory");
;     RAW_BARRIER();
;     STEP_TILE(st, false, 0, 0);
; DEV void merge_big(const Params& p, int l, int mt, int nt, char* smem) {
;     ...
; #pragma unroll
;         for (int mi = 0; mi < 4; ++mi)
; #pragma unroll
;             for (int ni = 0; ni < 2; ++ni) {
;                 float g[4]; ld_bf4(p.G() + (size_t)(rbase + mi * 16) * 3072 + br * 1024 + c0 + ni * 16, g);
;                 const f32x4 gv = (f32x4){g[0], g[1], g[2], g[3]};
;                 if (br == 0) mg[mi][ni] = gv * acc[mi][ni]; else mg[mi][ni] += gv * acc[mi][ni];
	ds_read_b128 v[166:169], v157 offset:20480
	ds_read_b128 v[90:93], v155 offset:12288
	ds_read_b128 v[148:151], v155 offset:13312
	ds_read_b128 v[158:161], v155 offset:14336
	ds_read_b128 v[162:165], v155 offset:15360
	ds_read_b128 v[170:173], v157 offset:21504
	s_setprio 1
	s_waitcnt lgkmcnt(4)
	v_mfma_f32_16x16x32_bf16 v[130:133], v[166:169], v[90:93], v[130:133]
	v_lshl_add_u64 v[140:141], v[60:61], 0, s[62:63]
	v_lshl_add_u64 v[152:153], v[58:59], 0, s[62:63]
	s_waitcnt lgkmcnt(3)
	v_mfma_f32_16x16x32_bf16 v[136:139], v[166:169], v[148:151], v[136:139]
	s_mov_b32 m0, s38
	s_nop 0
	global_load_lds_dwordx4 v[152:153], off
	s_waitcnt lgkmcnt(2)
	v_mfma_f32_16x16x32_bf16 v[144:147], v[166:169], v[158:161], v[144:147]
	s_waitcnt lgkmcnt(1)
	v_mfma_f32_16x16x32_bf16 v[86:89], v[166:169], v[162:165], v[86:89]
	v_lshl_add_u64 v[152:153], v[58:59], 0, s[76:77]
	s_mov_b32 m0, s35
	s_mov_b64 s[16:17], 0x81c0
	global_load_lds_dwordx4 v[152:153], off
	s_waitcnt lgkmcnt(0)
	v_mfma_f32_16x16x32_bf16 v[62:65], v[170:173], v[90:93], v[62:65]
	v_mfma_f32_16x16x32_bf16 v[70:73], v[170:173], v[148:151], v[70:73]
	s_mov_b32 m0, s34
	s_nop 0
	global_load_lds_dwordx4 v[140:141], off
	v_mfma_f32_16x16x32_bf16 v[74:77], v[170:173], v[158:161], v[74:77]
	v_mfma_f32_16x16x32_bf16 v[78:81], v[170:173], v[162:165], v[78:81]
	s_setprio 0
	s_waitcnt vmcnt(3)
	s_waitcnt lgkmcnt(0)
	s_barrier
	ds_read_b128 v[166:169], v157 offset:32768
	ds_read_b128 v[90:93], v155 offset:24576
	ds_read_b128 v[148:151], v155 offset:25600
	ds_read_b128 v[158:161], v155 offset:26624
	ds_read_b128 v[162:165], v155 offset:27648
	ds_read_b128 v[170:173], v157 offset:33792
	s_setprio 1
	s_waitcnt lgkmcnt(4)
	v_mfma_f32_16x16x32_bf16 v[130:133], v[166:169], v[90:93], v[130:133]
	v_lshl_add_u64 v[140:141], v[60:61], 0, s[64:65]
	v_lshl_add_u64 v[60:61], v[58:59], 0, s[64:65]
	s_waitcnt lgkmcnt(3)
	v_mfma_f32_16x16x32_bf16 v[136:139], v[166:169], v[148:151], v[136:139]
	s_mov_b32 m0, s31
	s_nop 0
	global_load_lds_dwordx4 v[60:61], off
	s_waitcnt lgkmcnt(2)
	v_mfma_f32_16x16x32_bf16 v[144:147], v[166:169], v[158:161], v[144:147]
	s_waitcnt lgkmcnt(1)
	v_mfma_f32_16x16x32_bf16 v[86:89], v[166:169], v[162:165], v[86:89]
	v_lshl_add_u64 v[58:59], v[58:59], 0, s[16:17]
	s_mov_b32 m0, s11
	s_nop 0
	global_load_lds_dwordx4 v[58:59], off
	s_waitcnt lgkmcnt(0)
	v_mfma_f32_16x16x32_bf16 v[58:61], v[170:173], v[90:93], v[62:65]
	v_mfma_f32_16x16x32_bf16 v[62:65], v[170:173], v[148:151], v[70:73]
	s_mov_b32 m0, s10
	s_nop 0
	global_load_lds_dwordx4 v[140:141], off
	v_mfma_f32_16x16x32_bf16 v[70:73], v[170:173], v[158:161], v[74:77]
	v_mfma_f32_16x16x32_bf16 v[74:77], v[170:173], v[162:165], v[78:81]
	s_setprio 0
	s_waitcnt vmcnt(3)
	s_waitcnt lgkmcnt(0)
	s_barrier
	s_nop 0
	ds_read_b128 v[78:81], v155
	ds_read_b128 v[90:93], v155 offset:1024
	ds_read_b128 v[148:151], v155 offset:2048
	ds_read_b128 v[158:161], v155 offset:3072
	ds_read_b128 v[162:165], v157 offset:8192
	ds_read_b128 v[166:169], v157 offset:9216
	s_setprio 1
	s_waitcnt lgkmcnt(0)
	v_mfma_f32_16x16x32_bf16 v[130:133], v[162:165], v[78:81], v[130:133]
	v_mfma_f32_16x16x32_bf16 v[136:139], v[162:165], v[90:93], v[136:139]
	v_mfma_f32_16x16x32_bf16 v[144:147], v[162:165], v[148:151], v[144:147]
	v_mfma_f32_16x16x32_bf16 v[86:89], v[162:165], v[158:161], v[86:89]
	v_mfma_f32_16x16x32_bf16 v[162:165], v[166:169], v[78:81], v[58:61]
	v_mfma_f32_16x16x32_bf16 v[170:173], v[166:169], v[90:93], v[62:65]
	v_mfma_f32_16x16x32_bf16 v[148:151], v[166:169], v[148:151], v[70:73]
	v_mfma_f32_16x16x32_bf16 v[158:161], v[166:169], v[158:161], v[74:77]
	s_setprio 0
	s_waitcnt vmcnt(0)
	s_waitcnt lgkmcnt(0)
	s_barrier
	ds_read_b128 v[90:93], v157 offset:20480
	ds_read_b128 v[62:65], v155 offset:12288
	ds_read_b128 v[74:77], v155 offset:13312
	ds_read_b128 v[166:169], v155 offset:14336
	ds_read_b128 v[174:177], v155 offset:15360
	ds_read_b128 v[178:181], v157 offset:21504
	s_setprio 1
	s_waitcnt lgkmcnt(4)
	v_mfma_f32_16x16x32_bf16 v[58:61], v[90:93], v[62:65], v[130:133]
	s_waitcnt lgkmcnt(3)
	v_mfma_f32_16x16x32_bf16 v[70:73], v[90:93], v[74:77], v[136:139]
	s_waitcnt lgkmcnt(2)
	v_mfma_f32_16x16x32_bf16 v[78:81], v[90:93], v[166:169], v[144:147]
	s_waitcnt lgkmcnt(1)
	v_mfma_f32_16x16x32_bf16 v[90:93], v[90:93], v[174:177], v[86:89]
	s_waitcnt lgkmcnt(0)
	v_mfma_f32_16x16x32_bf16 v[62:65], v[178:181], v[62:65], v[162:165]
	v_mfma_f32_16x16x32_bf16 v[74:77], v[178:181], v[74:77], v[170:173]
	v_mfma_f32_16x16x32_bf16 v[86:89], v[178:181], v[166:169], v[148:151]
	v_mfma_f32_16x16x32_bf16 v[146:149], v[178:181], v[174:177], v[158:161]
	s_setprio 0
	s_nop 0
	v_lshl_add_u64 v[150:151], s[6:7], 0, v[32:33]
	s_waitcnt vmcnt(0)
	v_lshlrev_b32_e32 v160, 16, v142
	v_and_b32_e32 v161, 0xffff0000, v142
	v_lshlrev_b32_e32 v142, 16, v143
	v_and_b32_e32 v143, 0xffff0000, v143
	v_mad_i64_i32 v[132:133], s[10:11], v94, s51, v[150:151]
	v_mad_i64_i32 v[138:139], s[10:11], v100, s51, v[150:151]
	v_mad_i64_i32 v[144:145], s[10:11], v98, s51, v[150:151]
	v_mad_i64_i32 v[150:151], s[10:11], v96, s51, v[150:151]
	v_lshlrev_b32_e32 v158, 16, v122
	v_and_b32_e32 v159, 0xffff0000, v122
	v_lshlrev_b32_e32 v122, 16, v123
	v_and_b32_e32 v123, 0xffff0000, v123
	v_pk_mul_f32 v[84:85], v[84:85], v[142:143]
	v_pk_mul_f32 v[82:83], v[82:83], v[160:161]
	s_waitcnt lgkmcnt(0)
	s_barrier
;     __device__ __forceinline__ bf16_t* G() const { return (bf16_t*)(ws + OFF_G); }
;     __device__ __forceinline__ bf16_t* Mg() const { return (bf16_t*)(ws + OFF_Mg); }
; DEV void st_bf4(bf16_t* p, float a, float b, float c, float d) { uint2 w; w.x = pk_bf16(a, b); w.y = pk_bf16(c, d); *(uint2*)p = w; }
; DEV void ld_bf4(const bf16_t* p, float (&v)[4]) { uint2 w = *(const uint2*)p; v[0] = bf_lo(w.x); v[1] = bf_hi(w.x); v[2] = bf_lo(w.y); v[3] = bf_hi(w.y); }
; DEV void merge_big(const Params& p, int l, int mt, int nt, char* smem) {
;     ...
; #pragma unroll
;         for (int mi = 0; mi < 4; ++mi)
; #pragma unroll
;             for (int ni = 0; ni < 2; ++ni) {
;                 float g[4]; ld_bf4(p.G() + (size_t)(rbase + mi * 16) * 3072 + br * 1024 + c0 + ni * 16, g);
;                 const f32x4 gv = (f32x4){g[0], g[1], g[2], g[3]};
;                 if (br == 0) mg[mi][ni] = gv * acc[mi][ni]; else mg[mi][ni] += gv * acc[mi][ni];
;             }
;     }
; #pragma unroll
;     for (int mi = 0; mi < 4; ++mi)
; #pragma unroll
;         for (int ni = 0; ni < 2; ++ni) st_bf4(p.Mg() + (size_t)(rbase + mi * 16) * 1024 + c0 + ni * 16, mg[mi][ni][0], mg[mi][ni][1], mg[mi][ni][2], mg[mi][ni][3]);
	flat_load_dwordx2 v[130:131], v[132:133]
	s_nop 0
	flat_load_dwordx2 v[132:133], v[132:133] offset:32
	s_nop 0
	flat_load_dwordx2 v[136:137], v[138:139]
	s_nop 0
	flat_load_dwordx2 v[138:139], v[138:139] offset:32
	s_nop 0
	flat_load_dwordx2 v[140:141], v[144:145]
	s_nop 0
	flat_load_dwordx2 v[144:145], v[144:145] offset:32
	v_pk_fma_f32 v[82:83], v[38:39], v[158:159], v[82:83]
	flat_load_dwordx2 v[152:153], v[150:151]
	v_pk_fma_f32 v[38:39], v[40:41], v[122:123], v[84:85]
	flat_load_dwordx2 v[40:41], v[150:151] offset:32
	v_lshlrev_b32_e32 v122, 16, v135
	v_and_b32_e32 v123, 0xffff0000, v135
	v_pk_mul_f32 v[68:69], v[68:69], v[122:123]
	v_readlane_b32 s2, v254, 1
	v_readlane_b32 s3, v254, 2
	s_add_i32 s30, s30, s82
	s_cmpk_gt_i32 s30, 0x7ff
	s_waitcnt vmcnt(0) lgkmcnt(0)
	v_lshlrev_b32_e32 v84, 16, v40
	v_and_b32_e32 v85, 0xffff0000, v40
	v_lshlrev_b32_e32 v40, 16, v41
	v_and_b32_e32 v41, 0xffff0000, v41
	v_pk_fma_f32 v[38:39], v[148:149], v[40:41], v[38:39]
	v_pk_fma_f32 v[40:41], v[146:147], v[84:85], v[82:83]
	v_lshlrev_b32_e32 v82, 16, v114
	v_and_b32_e32 v83, 0xffff0000, v114
	v_lshlrev_b32_e32 v84, 16, v115
	v_and_b32_e32 v85, 0xffff0000, v115
	v_lshlrev_b32_e32 v114, 16, v134
	v_and_b32_e32 v115, 0xffff0000, v134
	v_pk_mul_f32 v[66:67], v[66:67], v[114:115]
	s_nop 0
	v_pk_fma_f32 v[66:67], v[24:25], v[82:83], v[66:67]
	v_pk_fma_f32 v[24:25], v[26:27], v[84:85], v[68:69]
	v_lshlrev_b32_e32 v26, 16, v152
	v_and_b32_e32 v27, 0xffff0000, v152
	v_lshlrev_b32_e32 v68, 16, v153
	v_and_b32_e32 v69, 0xffff0000, v153
	v_lshlrev_b32_e32 v82, 16, v128
	v_and_b32_e32 v83, 0xffff0000, v128
	v_lshlrev_b32_e32 v84, 16, v129
	v_and_b32_e32 v85, 0xffff0000, v129
	v_pk_fma_f32 v[24:25], v[92:93], v[68:69], v[24:25]
	v_pk_fma_f32 v[26:27], v[90:91], v[26:27], v[66:67]
	v_lshlrev_b32_e32 v66, 16, v112
	v_and_b32_e32 v67, 0xffff0000, v112
	v_lshlrev_b32_e32 v68, 16, v113
	v_and_b32_e32 v69, 0xffff0000, v113
	v_pk_mul_f32 v[56:57], v[56:57], v[84:85]
	v_pk_mul_f32 v[54:55], v[54:55], v[82:83]
	s_nop 0
	v_pk_fma_f32 v[54:55], v[20:21], v[66:67], v[54:55]
	v_pk_fma_f32 v[20:21], v[22:23], v[68:69], v[56:57]
	v_lshlrev_b32_e32 v22, 16, v144
	v_and_b32_e32 v23, 0xffff0000, v144
	v_lshlrev_b32_e32 v66, 16, v126
	v_and_b32_e32 v67, 0xffff0000, v126
	v_lshlrev_b32_e32 v56, 16, v145
	v_and_b32_e32 v57, 0xffff0000, v145
	v_pk_fma_f32 v[22:23], v[86:87], v[22:23], v[54:55]
	v_lshlrev_b32_e32 v54, 16, v110
	v_and_b32_e32 v55, 0xffff0000, v110
	v_lshlrev_b32_e32 v68, 16, v127
	v_and_b32_e32 v69, 0xffff0000, v127
	v_pk_mul_f32 v[50:51], v[50:51], v[66:67]
	v_pk_fma_f32 v[20:21], v[88:89], v[56:57], v[20:21]
	v_lshlrev_b32_e32 v56, 16, v111
	v_and_b32_e32 v57, 0xffff0000, v111
	v_pk_mul_f32 v[52:53], v[52:53], v[68:69]
	v_pk_fma_f32 v[16:17], v[16:17], v[54:55], v[50:51]
	v_lshlrev_b32_e32 v50, 16, v140
	v_and_b32_e32 v51, 0xffff0000, v140
	v_lshlrev_b32_e32 v54, 16, v124
	v_and_b32_e32 v55, 0xffff0000, v124
	v_pk_fma_f32 v[18:19], v[18:19], v[56:57], v[52:53]
	v_lshlrev_b32_e32 v52, 16, v141
	v_and_b32_e32 v53, 0xffff0000, v141
	v_pk_fma_f32 v[16:17], v[78:79], v[50:51], v[16:17]
	v_lshlrev_b32_e32 v50, 16, v108
	v_and_b32_e32 v51, 0xffff0000, v108
	v_lshlrev_b32_e32 v56, 16, v125
	v_and_b32_e32 v57, 0xffff0000, v125
	v_pk_mul_f32 v[46:47], v[46:47], v[54:55]
	v_pk_fma_f32 v[18:19], v[80:81], v[52:53], v[18:19]
	v_lshlrev_b32_e32 v52, 16, v109
	v_and_b32_e32 v53, 0xffff0000, v109
	v_pk_mul_f32 v[48:49], v[48:49], v[56:57]
	v_pk_fma_f32 v[12:13], v[12:13], v[50:51], v[46:47]
	v_lshlrev_b32_e32 v46, 16, v138
	v_and_b32_e32 v47, 0xffff0000, v138
	v_lshlrev_b32_e32 v50, 16, v120
	v_and_b32_e32 v51, 0xffff0000, v120
	v_pk_fma_f32 v[14:15], v[14:15], v[52:53], v[48:49]
	v_lshlrev_b32_e32 v48, 16, v139
	v_and_b32_e32 v49, 0xffff0000, v139
	v_pk_fma_f32 v[12:13], v[74:75], v[46:47], v[12:13]
	v_lshlrev_b32_e32 v46, 16, v106
	v_and_b32_e32 v47, 0xffff0000, v106
	v_lshlrev_b32_e32 v52, 16, v121
	v_and_b32_e32 v53, 0xffff0000, v121
;     __device__ __forceinline__ bf16_t* G() const { return (bf16_t*)(ws + OFF_G); }
;     __device__ __forceinline__ bf16_t* Mg() const { return (bf16_t*)(ws + OFF_Mg); }
; DEV void st_bf4(bf16_t* p, float a, float b, float c, float d) { uint2 w; w.x = pk_bf16(a, b); w.y = pk_bf16(c, d); *(uint2*)p = w; }
; DEV void ld_bf4(const bf16_t* p, float (&v)[4]) { uint2 w = *(const uint2*)p; v[0] = bf_lo(w.x); v[1] = bf_hi(w.x); v[2] = bf_lo(w.y); v[3] = bf_hi(w.y); }
; DEV void merge_big(const Params& p, int l, int mt, int nt, char* smem) {
;     ...
; #pragma unroll
;         for (int mi = 0; mi < 4; ++mi)
; #pragma unroll
;             for (int ni = 0; ni < 2; ++ni) {
;                 float g[4]; ld_bf4(p.G() + (size_t)(rbase + mi * 16) * 3072 + br * 1024 + c0 + ni * 16, g);
;                 const f32x4 gv = (f32x4){g[0], g[1], g[2], g[3]};
;                 if (br == 0) mg[mi][ni] = gv * acc[mi][ni]; else mg[mi][ni] += gv * acc[mi][ni];
;             }
;     }
; #pragma unroll
;     for (int mi = 0; mi < 4; ++mi)
; #pragma unroll
;         for (int ni = 0; ni < 2; ++ni) st_bf4(p.Mg() + (size_t)(rbase + mi * 16) * 1024 + c0 + ni * 16, mg[mi][ni][0], mg[mi][ni][1], mg[mi][ni][2], mg[mi][ni][3]);
	v_pk_mul_f32 v[42:43], v[42:43], v[50:51]
	v_pk_fma_f32 v[14:15], v[76:77], v[48:49], v[14:15]
	v_lshlrev_b32_e32 v48, 16, v107
	v_and_b32_e32 v49, 0xffff0000, v107
	v_pk_mul_f32 v[44:45], v[44:45], v[52:53]
	v_pk_fma_f32 v[8:9], v[8:9], v[46:47], v[42:43]
	v_lshlrev_b32_e32 v42, 16, v136
	v_and_b32_e32 v43, 0xffff0000, v136
	v_lshlrev_b32_e32 v46, 16, v118
	v_and_b32_e32 v47, 0xffff0000, v118
	v_pk_fma_f32 v[10:11], v[10:11], v[48:49], v[44:45]
	v_lshlrev_b32_e32 v44, 16, v137
	v_and_b32_e32 v45, 0xffff0000, v137
	v_pk_fma_f32 v[8:9], v[70:71], v[42:43], v[8:9]
	v_lshlrev_b32_e32 v42, 16, v104
	v_and_b32_e32 v43, 0xffff0000, v104
	v_lshlrev_b32_e32 v48, 16, v119
	v_and_b32_e32 v49, 0xffff0000, v119
	v_pk_mul_f32 v[34:35], v[34:35], v[46:47]
	v_pk_fma_f32 v[10:11], v[72:73], v[44:45], v[10:11]
	v_lshlrev_b32_e32 v44, 16, v105
	v_and_b32_e32 v45, 0xffff0000, v105
	v_pk_mul_f32 v[36:37], v[36:37], v[48:49]
	v_pk_fma_f32 v[4:5], v[4:5], v[42:43], v[34:35]
	v_lshlrev_b32_e32 v34, 16, v132
	v_and_b32_e32 v35, 0xffff0000, v132
	v_lshlrev_b32_e32 v42, 16, v116
	v_and_b32_e32 v43, 0xffff0000, v116
	v_pk_fma_f32 v[6:7], v[6:7], v[44:45], v[36:37]
	v_lshlrev_b32_e32 v36, 16, v133
	v_and_b32_e32 v37, 0xffff0000, v133
	v_pk_fma_f32 v[4:5], v[62:63], v[34:35], v[4:5]
	v_lshlrev_b32_e32 v34, 16, v102
	v_and_b32_e32 v35, 0xffff0000, v102
	v_lshlrev_b32_e32 v44, 16, v117
	v_and_b32_e32 v45, 0xffff0000, v117
	v_pk_mul_f32 v[28:29], v[28:29], v[42:43]
	v_pk_fma_f32 v[6:7], v[64:65], v[36:37], v[6:7]
	v_lshlrev_b32_e32 v36, 16, v103
	v_and_b32_e32 v37, 0xffff0000, v103
	v_pk_mul_f32 v[30:31], v[30:31], v[44:45]
	v_pk_fma_f32 v[0:1], v[0:1], v[34:35], v[28:29]
	v_lshlrev_b32_e32 v28, 16, v130
	v_and_b32_e32 v29, 0xffff0000, v130
	v_pk_fma_f32 v[2:3], v[2:3], v[36:37], v[30:31]
	v_lshlrev_b32_e32 v30, 16, v131
	v_and_b32_e32 v31, 0xffff0000, v131
	v_pk_fma_f32 v[0:1], v[58:59], v[28:29], v[0:1]
	v_lshlrev_b64 v[28:29], 11, v[94:95]
	v_pk_fma_f32 v[2:3], v[60:61], v[30:31], v[2:3]
	v_lshl_add_u64 v[30:31], s[8:9], 0, v[28:29]
	v_lshl_add_u64 v[30:31], v[30:31], 0, v[32:33]
	v_cvt_pk_bf16_f32 v0, v0, v1
	v_cvt_pk_bf16_f32 v1, v2, v3
	flat_store_dwordx2 v[30:31], v[0:1]
	v_lshl_add_u64 v[0:1], s[2:3], 0, v[28:29]
	v_lshl_add_u64 v[0:1], v[0:1], 0, v[32:33]
	v_add_co_u32_e32 v0, vcc, s52, v0
	v_cvt_pk_bf16_f32 v2, v4, v5
	v_cvt_pk_bf16_f32 v3, v6, v7
	v_addc_co_u32_e32 v1, vcc, 0, v1, vcc
	flat_store_dwordx2 v[0:1], v[2:3] offset:32
	v_lshlrev_b64 v[0:1], 11, v[100:101]
	v_lshl_add_u64 v[2:3], s[8:9], 0, v[0:1]
	v_lshl_add_u64 v[0:1], s[2:3], 0, v[0:1]
	v_lshl_add_u64 v[0:1], v[0:1], 0, v[32:33]
	v_lshl_add_u64 v[2:3], v[2:3], 0, v[32:33]
	v_cvt_pk_bf16_f32 v4, v8, v9
	v_cvt_pk_bf16_f32 v5, v10, v11
	v_add_co_u32_e32 v0, vcc, s52, v0
	flat_store_dwordx2 v[2:3], v[4:5]
	v_cvt_pk_bf16_f32 v2, v12, v13
	v_cvt_pk_bf16_f32 v3, v14, v15
	v_addc_co_u32_e32 v1, vcc, 0, v1, vcc
	flat_store_dwordx2 v[0:1], v[2:3] offset:32
	v_lshlrev_b64 v[0:1], 11, v[98:99]
	v_lshl_add_u64 v[2:3], s[8:9], 0, v[0:1]
	v_lshl_add_u64 v[0:1], s[2:3], 0, v[0:1]
	v_lshl_add_u64 v[0:1], v[0:1], 0, v[32:33]
	v_lshl_add_u64 v[2:3], v[2:3], 0, v[32:33]
	v_cvt_pk_bf16_f32 v4, v16, v17
	v_cvt_pk_bf16_f32 v5, v18, v19
	v_add_co_u32_e32 v0, vcc, s52, v0
	flat_store_dwordx2 v[2:3], v[4:5]
	v_cvt_pk_bf16_f32 v2, v22, v23
	v_cvt_pk_bf16_f32 v3, v20, v21
	v_addc_co_u32_e32 v1, vcc, 0, v1, vcc
	flat_store_dwordx2 v[0:1], v[2:3] offset:32
	v_lshlrev_b64 v[0:1], 11, v[96:97]
	v_lshl_add_u64 v[2:3], s[8:9], 0, v[0:1]
	v_lshl_add_u64 v[0:1], s[2:3], 0, v[0:1]
	v_lshl_add_u64 v[0:1], v[0:1], 0, v[32:33]
	v_lshl_add_u64 v[2:3], v[2:3], 0, v[32:33]
	v_cvt_pk_bf16_f32 v4, v26, v27
	v_cvt_pk_bf16_f32 v5, v24, v25
	v_add_co_u32_e32 v0, vcc, 0x60ac000, v0
	flat_store_dwordx2 v[2:3], v[4:5]
	v_cvt_pk_bf16_f32 v2, v40, v41
	v_cvt_pk_bf16_f32 v3, v38, v39
	v_addc_co_u32_e32 v1, vcc, 0, v1, vcc
	flat_store_dwordx2 v[0:1], v[2:3] offset:32
	s_cbranch_scc0 .LBB0_106

; DEV int tid_opaque() { int t = threadIdx.x; asm volatile("" : "+v"(t)); return t; }
; #define RAW_BARRIER() do { asm volatile("s_waitcnt lgkmcnt(0)" ::: "memory"); __builtin_amdgcn_s_barrier(); } while (0)
; #define GLDS_TILE(kt, st) do { _Pragma("unroll") for (int _i = 0; _i < NP; ++_i) GLDS_PIECE(_i, kt, st); } while (0)
;     ...
;     const int t = tid_opaque(), lane = t & 63, wid = t >> 6, wm = wid >> 1, wn = wid & 1, fr = lane & 15, fq = lane >> 4;
;     const int nk = K >> 5;
;     const int srow = wid * 16 + (lane >> 2), sch = (lane & 3) ^ ((0 - (lane >> 4)) & 3);
;     const bf16_t* ga = A + (size_t)srow * lda + sch * 8;
;     const bf16_t* gb = B + (size_t)srow * ldb + sch * 8;
;     const int rd = fr * 64 + ((fq ^ ((0 - (fr >> 2)) & 3)) << 4);
;     const int rda = (wm * 64) * 64 + rd, rdb = 8192 + (wn * 16 * NI) * 64 + rd;
;     ...
;     constexpr int NH = NI >= 4 ? NI / 2 : NI;
;     constexpr int NP = 2 + NB, IVL = (4 * NI) / NP;
;     RAW_BARRIER();
;     GLDS_TILE(0, 0);
;     GLDS_TILE(1, 1);
;     int st = 0;
;     for (int kt = 0; kt < nk - 1; ++kt) {
;         if (NI == 8) asm volatile("s_waitcnt vmcnt(6)" ::: "memory"); else if (NI == 4) asm volatile("s_waitcnt vmcnt(4)" ::: "memory"); else asm volatile("s_waitcnt vmcnt(3)" ::: "memory");
;         RAW_BARRIER();
;         const int s2 = st >= 1 ? st - 1 : 2;
;         const bool ld = kt + 2 < nk;
;         STEP_TILE(st, ld, kt + 2, s2);
;         st = st == 2 ? 0 : st + 1;
;     }
.LBB0_109:
	v_mov_b32_e32 v0, v186
	s_movk_i32 s18, 0xffc0
	v_and_b32_e32 v1, 15, v0
	v_ashrrev_i32_e32 v2, 1, v0
	v_and_or_b32 v30, v2, s18, v1
	v_lshrrev_b32_e32 v1, 1, v0
	v_lshrrev_b32_e32 v0, 2, v0
	v_mov_b32_e32 v6, v186
	v_and_b32_e32 v0, 12, v0
	v_and_or_b32 v0, v1, 32, v0
	v_bfe_u32 v8, v6, 4, 2
	v_sub_u32_e32 v4, 0, v8
	v_add_u32_e32 v28, s20, v0
	v_ashrrev_i32_e32 v7, 6, v6
	v_bfe_u32 v0, v6, 2, 4
	v_xor_b32_e32 v3, v6, v4
	v_lshl_or_b32 v2, v7, 4, v0
	v_mov_b64_e32 v[0:1], s[0:1]
	v_lshlrev_b32_e32 v3, 4, v3
	v_mad_i64_i32 v[0:1], s[18:19], v2, s48, v[0:1]
	v_and_b32_e32 v32, 48, v3
	v_mad_i64_i32 v[2:3], s[18:19], v2, s48, 0
	v_readlane_b32 s2, v254, 1
	v_lshrrev_b32_e32 v10, 2, v6
	v_lshl_add_u32 v31, v7, 10, 0
	v_bitop3_b32 v4, v6, 3, v4 bitop3:0x48
	v_readlane_b32 s3, v254, 2
	s_add_u32 s18, s2, s22
	v_lshlrev_b32_e32 v9, 6, v6
	v_sub_u32_e32 v10, 0, v10
	v_readfirstlane_b32 s40, v31
	v_add_u32_e32 v12, 0x1000, v31
	v_lshl_add_u64 v[0:1], v[0:1], 0, v[32:33]
	v_lshl_or_b32 v2, v4, 4, v2
	s_addc_u32 s19, s3, s23
	v_and_b32_e32 v9, 0x3c0, v9
	v_bitop3_b32 v8, v8, v10, 3 bitop3:0x78
	v_add_u32_e32 v11, 0x2000, v31
	s_mov_b32 m0, s40
	v_readfirstlane_b32 s39, v12
	v_lshl_add_u64 v[2:3], s[18:19], 0, v[2:3]
	s_mov_b64 s[34:35], 0x1700000
	v_lshl_or_b32 v8, v8, 4, v9
	v_lshlrev_b32_e32 v9, 5, v6
	v_lshlrev_b32_e32 v10, 11, v7
	s_waitcnt lgkmcnt(0)
	s_barrier
	global_load_lds_dwordx4 v[0:1], off
	v_lshl_add_u64 v[6:7], v[0:1], 0, s[66:67]
	s_mov_b32 m0, s39
	v_readfirstlane_b32 s38, v11
	v_lshl_add_u64 v[4:5], v[2:3], 0, s[34:35]
	global_load_lds_dwordx4 v[6:7], off
	s_mov_b32 m0, s38
	v_add_u32_e32 v11, 0x3000, v31
	s_mov_b64 s[34:35], 0x1700040
	global_load_lds_dwordx4 v[4:5], off
	v_lshl_add_u64 v[4:5], v[2:3], 0, s[34:35]
	v_readfirstlane_b32 s35, v11
	v_add_u32_e32 v11, 0x4000, v31
	v_add_u32_e32 v12, 0x5000, v31
	v_lshl_add_u64 v[6:7], v[0:1], 0, 64
	s_mov_b32 m0, s35
	v_readfirstlane_b32 s34, v11
	global_load_lds_dwordx4 v[6:7], off
	v_lshl_add_u64 v[6:7], v[0:1], 0, s[68:69]
	s_mov_b32 m0, s34
	v_readfirstlane_b32 s31, v12
	global_load_lds_dwordx4 v[6:7], off
	s_mov_b32 m0, s31
	v_and_or_b32 v9, v9, s49, v8
	global_load_lds_dwordx4 v[4:5], off
	s_waitcnt vmcnt(3)
	v_add_u32_e32 v32, 0, v9
	v_and_or_b32 v20, v10, s50, v8
	s_waitcnt lgkmcnt(0)
	s_barrier
	ds_read_b128 v[4:7], v32
	ds_read_b128 v[8:11], v32 offset:1024
	ds_read_b128 v[12:15], v32 offset:2048
	ds_read_b128 v[16:19], v32 offset:3072
	s_waitcnt vmcnt(0)
	v_add_u32_e32 v70, 0, v20
	ds_read_b128 v[20:23], v70 offset:8192
	ds_read_b128 v[24:27], v70 offset:9216
	v_add_u32_e32 v94, 0x4000, v30
	v_ashrrev_i32_e32 v29, 31, v28
	s_setprio 1
	s_mov_b64 s[42:43], 0x1700080
	v_add_u32_e32 v44, 0x6000, v31
	s_waitcnt lgkmcnt(0)
	v_mfma_f32_16x16x32_bf16 v[34:37], v[20:23], v[4:7], 0
	v_lshl_add_u64 v[46:47], v[2:3], 0, s[42:43]
	v_add_u32_e32 v50, 0x8000, v31
	v_lshl_add_u64 v[42:43], v[0:1], 0, s[54:55]
	v_mfma_f32_16x16x32_bf16 v[38:41], v[20:23], v[8:11], 0
	v_readfirstlane_b32 s41, v44
	s_mov_b32 m0, s41
	s_nop 0
	global_load_lds_dwordx4 v[42:43], off
	v_mfma_f32_16x16x32_bf16 v[42:45], v[20:23], v[12:15], 0
	v_mfma_f32_16x16x32_bf16 v[20:23], v[20:23], v[16:19], 0
	v_add_u32_e32 v31, 0x7000, v31
	v_lshl_add_u64 v[48:49], v[0:1], 0, s[96:97]
	v_readfirstlane_b32 s42, v31
	s_mov_b32 m0, s42
	s_nop 0
	global_load_lds_dwordx4 v[48:49], off
	v_mfma_f32_16x16x32_bf16 v[4:7], v[24:27], v[4:7], 0
	v_mfma_f32_16x16x32_bf16 v[8:11], v[24:27], v[8:11], 0
	v_readfirstlane_b32 s43, v50
	s_mov_b32 m0, s43
	s_nop 0
	global_load_lds_dwordx4 v[46:47], off
	v_mfma_f32_16x16x32_bf16 v[12:15], v[24:27], v[12:15], 0
	v_mfma_f32_16x16x32_bf16 v[16:19], v[24:27], v[16:19], 0
	s_setprio 0
	s_waitcnt vmcnt(3)
	s_waitcnt lgkmcnt(0)
	s_barrier
	ds_read_b128 v[58:61], v70 offset:20480
	ds_read_b128 v[24:27], v32 offset:12288
	ds_read_b128 v[46:49], v32 offset:13312
	ds_read_b128 v[50:53], v32 offset:14336
	ds_read_b128 v[54:57], v32 offset:15360
	ds_read_b128 v[62:65], v70 offset:21504
	s_setprio 1
	s_mov_b64 s[44:45], 0x17000c0
	s_waitcnt lgkmcnt(4)
	v_mfma_f32_16x16x32_bf16 v[34:37], v[58:61], v[24:27], v[34:37]
	v_lshl_add_u64 v[66:67], v[2:3], 0, s[44:45]
	v_lshl_add_u64 v[68:69], v[0:1], 0, s[56:57]
	s_waitcnt lgkmcnt(3)
	v_mfma_f32_16x16x32_bf16 v[38:41], v[58:61], v[46:49], v[38:41]
	s_mov_b32 m0, s40
	s_nop 0
	global_load_lds_dwordx4 v[68:69], off
	s_waitcnt lgkmcnt(2)
	v_mfma_f32_16x16x32_bf16 v[42:45], v[58:61], v[50:53], v[42:45]
	s_waitcnt lgkmcnt(1)
	v_mfma_f32_16x16x32_bf16 v[20:23], v[58:61], v[54:57], v[20:23]
	v_lshl_add_u64 v[58:59], v[0:1], 0, s[94:95]
	s_mov_b32 m0, s39
	s_nop 0
	global_load_lds_dwordx4 v[58:59], off
	s_waitcnt lgkmcnt(0)
	v_mfma_f32_16x16x32_bf16 v[4:7], v[62:65], v[24:27], v[4:7]
	v_mfma_f32_16x16x32_bf16 v[8:11], v[62:65], v[46:49], v[8:11]
	s_mov_b32 m0, s38
	s_nop 0
	global_load_lds_dwordx4 v[66:67], off
	v_mfma_f32_16x16x32_bf16 v[12:15], v[62:65], v[50:53], v[12:15]
	v_mfma_f32_16x16x32_bf16 v[16:19], v[62:65], v[54:57], v[16:19]
	s_setprio 0
	s_waitcnt vmcnt(3)
	s_waitcnt lgkmcnt(0)
	s_barrier
; #define RAW_BARRIER() do { asm volatile("s_waitcnt lgkmcnt(0)" ::: "memory"); __builtin_amdgcn_s_barrier(); } while (0)
; #define GLDS_TILE(kt, st) do { _Pragma("unroll") for (int _i = 0; _i < NP; ++_i) GLDS_PIECE(_i, kt, st); } while (0)
;     ...
;     constexpr int NH = NI >= 4 ? NI / 2 : NI;
;     constexpr int NP = 2 + NB, IVL = (4 * NI) / NP;
;     RAW_BARRIER();
;     GLDS_TILE(0, 0);
;     GLDS_TILE(1, 1);
;     int st = 0;
;     for (int kt = 0; kt < nk - 1; ++kt) {
;         if (NI == 8) asm volatile("s_waitcnt vmcnt(6)" ::: "memory"); else if (NI == 4) asm volatile("s_waitcnt vmcnt(4)" ::: "memory"); else asm volatile("s_waitcnt vmcnt(3)" ::: "memory");
;         RAW_BARRIER();
;         const int s2 = st >= 1 ? st - 1 : 2;
;         const bool ld = kt + 2 < nk;
;         STEP_TILE(st, ld, kt + 2, s2);
;         st = st == 2 ? 0 : st + 1;
;     }
	ds_read_b128 v[58:61], v70 offset:32768
	ds_read_b128 v[24:27], v32 offset:24576
	ds_read_b128 v[46:49], v32 offset:25600
	ds_read_b128 v[50:53], v32 offset:26624
	ds_read_b128 v[54:57], v32 offset:27648
	ds_read_b128 v[62:65], v70 offset:33792
	s_setprio 1
	s_mov_b64 s[44:45], 0x1700100
	s_waitcnt lgkmcnt(4)
	v_mfma_f32_16x16x32_bf16 v[34:37], v[58:61], v[24:27], v[34:37]
	v_lshl_add_u64 v[66:67], v[2:3], 0, s[44:45]
	v_lshl_add_u64 v[68:69], v[0:1], 0, s[58:59]
	s_waitcnt lgkmcnt(3)
	v_mfma_f32_16x16x32_bf16 v[38:41], v[58:61], v[46:49], v[38:41]
	s_mov_b32 m0, s35
	s_nop 0
	global_load_lds_dwordx4 v[68:69], off
	s_waitcnt lgkmcnt(2)
	v_mfma_f32_16x16x32_bf16 v[42:45], v[58:61], v[50:53], v[42:45]
	s_waitcnt lgkmcnt(1)
	v_mfma_f32_16x16x32_bf16 v[20:23], v[58:61], v[54:57], v[20:23]
	v_lshl_add_u64 v[58:59], v[0:1], 0, s[70:71]
	s_mov_b32 m0, s34
	s_nop 0
	global_load_lds_dwordx4 v[58:59], off
	s_waitcnt lgkmcnt(0)
	v_mfma_f32_16x16x32_bf16 v[4:7], v[62:65], v[24:27], v[4:7]
	v_mfma_f32_16x16x32_bf16 v[8:11], v[62:65], v[46:49], v[8:11]
	s_mov_b32 m0, s31
	s_nop 0
	global_load_lds_dwordx4 v[66:67], off
	v_mfma_f32_16x16x32_bf16 v[12:15], v[62:65], v[50:53], v[12:15]
	v_mfma_f32_16x16x32_bf16 v[16:19], v[62:65], v[54:57], v[16:19]
	s_setprio 0
	s_waitcnt vmcnt(3)
	s_waitcnt lgkmcnt(0)
	s_barrier
	ds_read_b128 v[58:61], v70 offset:8192
	ds_read_b128 v[24:27], v32
	ds_read_b128 v[46:49], v32 offset:1024
	ds_read_b128 v[50:53], v32 offset:2048
	ds_read_b128 v[54:57], v32 offset:3072
	ds_read_b128 v[62:65], v70 offset:9216
	s_setprio 1
	s_mov_b64 s[44:45], 0x1700140
	s_waitcnt lgkmcnt(4)
	v_mfma_f32_16x16x32_bf16 v[34:37], v[58:61], v[24:27], v[34:37]
	v_lshl_add_u64 v[66:67], v[2:3], 0, s[44:45]
	v_lshl_add_u64 v[68:69], v[0:1], 0, s[60:61]
	s_waitcnt lgkmcnt(3)
	v_mfma_f32_16x16x32_bf16 v[38:41], v[58:61], v[46:49], v[38:41]
	s_mov_b32 m0, s41
	s_nop 0
	global_load_lds_dwordx4 v[68:69], off
	s_waitcnt lgkmcnt(2)
	v_mfma_f32_16x16x32_bf16 v[42:45], v[58:61], v[50:53], v[42:45]
	s_waitcnt lgkmcnt(1)
	v_mfma_f32_16x16x32_bf16 v[20:23], v[58:61], v[54:57], v[20:23]
	v_lshl_add_u64 v[58:59], v[0:1], 0, s[72:73]
	s_mov_b32 m0, s42
	s_nop 0
	global_load_lds_dwordx4 v[58:59], off
	s_waitcnt lgkmcnt(0)
	v_mfma_f32_16x16x32_bf16 v[4:7], v[62:65], v[24:27], v[4:7]
	v_mfma_f32_16x16x32_bf16 v[8:11], v[62:65], v[46:49], v[8:11]
	s_mov_b32 m0, s43
	s_nop 0
	global_load_lds_dwordx4 v[66:67], off
	v_mfma_f32_16x16x32_bf16 v[12:15], v[62:65], v[50:53], v[12:15]
	v_mfma_f32_16x16x32_bf16 v[16:19], v[62:65], v[54:57], v[16:19]
	s_setprio 0
	s_waitcnt vmcnt(3)
	s_waitcnt lgkmcnt(0)
	s_barrier
	ds_read_b128 v[58:61], v70 offset:20480
	ds_read_b128 v[24:27], v32 offset:12288
	ds_read_b128 v[46:49], v32 offset:13312
	ds_read_b128 v[50:53], v32 offset:14336
	ds_read_b128 v[54:57], v32 offset:15360
	ds_read_b128 v[62:65], v70 offset:21504
	s_setprio 1
	s_mov_b64 s[44:45], 0x1700180
	s_waitcnt lgkmcnt(4)
	v_mfma_f32_16x16x32_bf16 v[34:37], v[58:61], v[24:27], v[34:37]
	v_lshl_add_u64 v[66:67], v[2:3], 0, s[44:45]
	v_lshl_add_u64 v[68:69], v[0:1], 0, s[62:63]
	s_waitcnt lgkmcnt(3)
	v_mfma_f32_16x16x32_bf16 v[38:41], v[58:61], v[46:49], v[38:41]
	s_mov_b32 m0, s40
	s_nop 0
	global_load_lds_dwordx4 v[68:69], off
	s_waitcnt lgkmcnt(2)
	v_mfma_f32_16x16x32_bf16 v[42:45], v[58:61], v[50:53], v[42:45]
	s_waitcnt lgkmcnt(1)
	v_mfma_f32_16x16x32_bf16 v[20:23], v[58:61], v[54:57], v[20:23]
	v_lshl_add_u64 v[58:59], v[0:1], 0, s[84:85]
	s_mov_b32 m0, s39
	s_nop 0
	global_load_lds_dwordx4 v[58:59], off
	s_waitcnt lgkmcnt(0)
	v_mfma_f32_16x16x32_bf16 v[4:7], v[62:65], v[24:27], v[4:7]
	v_mfma_f32_16x16x32_bf16 v[8:11], v[62:65], v[46:49], v[8:11]
	s_mov_b32 m0, s38
	s_nop 0
	global_load_lds_dwordx4 v[66:67], off
	v_mfma_f32_16x16x32_bf16 v[12:15], v[62:65], v[50:53], v[12:15]
	v_mfma_f32_16x16x32_bf16 v[16:19], v[62:65], v[54:57], v[16:19]
	s_setprio 0
	s_waitcnt vmcnt(3)
	s_waitcnt lgkmcnt(0)
	s_barrier
	ds_read_b128 v[58:61], v70 offset:32768
	ds_read_b128 v[24:27], v32 offset:24576
	ds_read_b128 v[46:49], v32 offset:25600
	ds_read_b128 v[50:53], v32 offset:26624
	ds_read_b128 v[54:57], v32 offset:27648
	ds_read_b128 v[62:65], v70 offset:33792
	s_setprio 1
	s_mov_b64 s[44:45], 0x17001c0
	s_waitcnt lgkmcnt(4)
	v_mfma_f32_16x16x32_bf16 v[34:37], v[58:61], v[24:27], v[34:37]
	v_lshl_add_u64 v[66:67], v[2:3], 0, s[44:45]
	v_lshl_add_u64 v[68:69], v[0:1], 0, s[64:65]
	s_waitcnt lgkmcnt(3)
	v_mfma_f32_16x16x32_bf16 v[38:41], v[58:61], v[46:49], v[38:41]
	s_mov_b32 m0, s35
	s_nop 0
	global_load_lds_dwordx4 v[68:69], off
	s_waitcnt lgkmcnt(2)
	v_mfma_f32_16x16x32_bf16 v[42:45], v[58:61], v[50:53], v[42:45]
	s_waitcnt lgkmcnt(1)
	v_mfma_f32_16x16x32_bf16 v[20:23], v[58:61], v[54:57], v[20:23]
	s_mov_b64 s[46:47], 0xc1c0
	v_lshl_add_u64 v[58:59], v[0:1], 0, s[46:47]
	s_mov_b32 m0, s34
	s_nop 0
	global_load_lds_dwordx4 v[58:59], off
	s_waitcnt lgkmcnt(0)
	v_mfma_f32_16x16x32_bf16 v[4:7], v[62:65], v[24:27], v[4:7]
	v_mfma_f32_16x16x32_bf16 v[8:11], v[62:65], v[46:49], v[8:11]
	s_mov_b32 m0, s31
	s_nop 0
	global_load_lds_dwordx4 v[66:67], off
	v_mfma_f32_16x16x32_bf16 v[12:15], v[62:65], v[50:53], v[12:15]
	v_mfma_f32_16x16x32_bf16 v[16:19], v[62:65], v[54:57], v[16:19]
	s_setprio 0
	s_waitcnt vmcnt(3)
	s_waitcnt lgkmcnt(0)
	s_barrier
; #define RAW_BARRIER() do { asm volatile("s_waitcnt lgkmcnt(0)" ::: "memory"); __builtin_amdgcn_s_barrier(); } while (0)
; #define GLDS_TILE(kt, st) do { _Pragma("unroll") for (int _i = 0; _i < NP; ++_i) GLDS_PIECE(_i, kt, st); } while (0)
;     ...
;     constexpr int NH = NI >= 4 ? NI / 2 : NI;
;     constexpr int NP = 2 + NB, IVL = (4 * NI) / NP;
;     RAW_BARRIER();
;     GLDS_TILE(0, 0);
;     GLDS_TILE(1, 1);
;     int st = 0;
;     for (int kt = 0; kt < nk - 1; ++kt) {
;         if (NI == 8) asm volatile("s_waitcnt vmcnt(6)" ::: "memory"); else if (NI == 4) asm volatile("s_waitcnt vmcnt(4)" ::: "memory"); else asm volatile("s_waitcnt vmcnt(3)" ::: "memory");
;         RAW_BARRIER();
;         const int s2 = st >= 1 ? st - 1 : 2;
;         const bool ld = kt + 2 < nk;
;         STEP_TILE(st, ld, kt + 2, s2);
;         st = st == 2 ? 0 : st + 1;
;     }
	ds_read_b128 v[58:61], v70 offset:8192
	ds_read_b128 v[24:27], v32
	ds_read_b128 v[46:49], v32 offset:1024
	ds_read_b128 v[50:53], v32 offset:2048
	ds_read_b128 v[54:57], v32 offset:3072
	ds_read_b128 v[62:65], v70 offset:9216
	s_setprio 1
	s_mov_b64 s[44:45], 0x1700200
	s_mov_b64 s[76:77], 0x200
	s_waitcnt lgkmcnt(4)
	v_mfma_f32_16x16x32_bf16 v[34:37], v[58:61], v[24:27], v[34:37]
	v_lshl_add_u64 v[66:67], v[2:3], 0, s[44:45]
	v_lshl_add_u64 v[68:69], v[0:1], 0, s[76:77]
	s_waitcnt lgkmcnt(3)
	v_mfma_f32_16x16x32_bf16 v[38:41], v[58:61], v[46:49], v[38:41]
	s_mov_b32 m0, s41
	s_nop 0
	global_load_lds_dwordx4 v[68:69], off
	s_waitcnt lgkmcnt(2)
	v_mfma_f32_16x16x32_bf16 v[42:45], v[58:61], v[50:53], v[42:45]
	s_waitcnt lgkmcnt(1)
	v_mfma_f32_16x16x32_bf16 v[20:23], v[58:61], v[54:57], v[20:23]
	s_mov_b64 vcc, 0xc200
	v_lshl_add_u64 v[58:59], v[0:1], 0, vcc
	s_mov_b32 m0, s42
	s_nop 0
	global_load_lds_dwordx4 v[58:59], off
	s_waitcnt lgkmcnt(0)
	v_mfma_f32_16x16x32_bf16 v[4:7], v[62:65], v[24:27], v[4:7]
	v_mfma_f32_16x16x32_bf16 v[8:11], v[62:65], v[46:49], v[8:11]
	s_mov_b32 m0, s43
	s_nop 0
	global_load_lds_dwordx4 v[66:67], off
	v_mfma_f32_16x16x32_bf16 v[12:15], v[62:65], v[50:53], v[12:15]
	v_mfma_f32_16x16x32_bf16 v[16:19], v[62:65], v[54:57], v[16:19]
	s_setprio 0
	s_waitcnt vmcnt(3)
	s_waitcnt lgkmcnt(0)
	s_barrier
	ds_read_b128 v[58:61], v70 offset:20480
	ds_read_b128 v[24:27], v32 offset:12288
	ds_read_b128 v[46:49], v32 offset:13312
	ds_read_b128 v[50:53], v32 offset:14336
	ds_read_b128 v[54:57], v32 offset:15360
	ds_read_b128 v[62:65], v70 offset:21504
	s_setprio 1
	s_mov_b64 s[44:45], 0x1700240
	s_waitcnt lgkmcnt(4)
	v_mfma_f32_16x16x32_bf16 v[34:37], v[58:61], v[24:27], v[34:37]
	v_lshl_add_u64 v[66:67], v[2:3], 0, s[44:45]
	v_lshl_add_u64 v[68:69], v[0:1], 0, s[86:87]
	s_waitcnt lgkmcnt(3)
	v_mfma_f32_16x16x32_bf16 v[38:41], v[58:61], v[46:49], v[38:41]
	s_mov_b32 m0, s40
	s_nop 0
	global_load_lds_dwordx4 v[68:69], off
	s_waitcnt lgkmcnt(2)
	v_mfma_f32_16x16x32_bf16 v[42:45], v[58:61], v[50:53], v[42:45]
	s_waitcnt lgkmcnt(1)
	v_mfma_f32_16x16x32_bf16 v[20:23], v[58:61], v[54:57], v[20:23]
	v_lshl_add_u64 v[58:59], v[0:1], 0, s[90:91]
	s_mov_b32 m0, s39
	s_nop 0
	global_load_lds_dwordx4 v[58:59], off
	s_waitcnt lgkmcnt(0)
	v_mfma_f32_16x16x32_bf16 v[4:7], v[62:65], v[24:27], v[4:7]
	v_mfma_f32_16x16x32_bf16 v[8:11], v[62:65], v[46:49], v[8:11]
	s_mov_b32 m0, s38
	s_nop 0
	global_load_lds_dwordx4 v[66:67], off
	v_mfma_f32_16x16x32_bf16 v[12:15], v[62:65], v[50:53], v[12:15]
	v_mfma_f32_16x16x32_bf16 v[16:19], v[62:65], v[54:57], v[16:19]
	s_setprio 0
	s_waitcnt vmcnt(3)
	s_waitcnt lgkmcnt(0)
	s_barrier
	ds_read_b128 v[58:61], v70 offset:32768
	ds_read_b128 v[24:27], v32 offset:24576
	ds_read_b128 v[46:49], v32 offset:25600
	ds_read_b128 v[50:53], v32 offset:26624
	ds_read_b128 v[54:57], v32 offset:27648
	ds_read_b128 v[62:65], v70 offset:33792
	s_setprio 1
	s_mov_b64 s[38:39], 0x1700280
	s_waitcnt lgkmcnt(4)
	v_mfma_f32_16x16x32_bf16 v[34:37], v[58:61], v[24:27], v[34:37]
	v_lshl_add_u64 v[66:67], v[2:3], 0, s[38:39]
	v_lshl_add_u64 v[68:69], v[0:1], 0, s[88:89]
	s_waitcnt lgkmcnt(3)
	v_mfma_f32_16x16x32_bf16 v[38:41], v[58:61], v[46:49], v[38:41]
	s_mov_b32 m0, s35
	s_nop 0
	global_load_lds_dwordx4 v[68:69], off
	s_waitcnt lgkmcnt(2)
	v_mfma_f32_16x16x32_bf16 v[42:45], v[58:61], v[50:53], v[42:45]
	s_waitcnt lgkmcnt(1)
	v_mfma_f32_16x16x32_bf16 v[20:23], v[58:61], v[54:57], v[20:23]
	s_mov_b64 s[80:81], 0xc280
	v_lshl_add_u64 v[58:59], v[0:1], 0, s[80:81]
	s_mov_b32 m0, s34
	s_nop 0
	global_load_lds_dwordx4 v[58:59], off
	s_waitcnt lgkmcnt(0)
	v_mfma_f32_16x16x32_bf16 v[4:7], v[62:65], v[24:27], v[4:7]
	v_mfma_f32_16x16x32_bf16 v[8:11], v[62:65], v[46:49], v[8:11]
	s_mov_b32 m0, s31
	s_nop 0
	global_load_lds_dwordx4 v[66:67], off
	v_mfma_f32_16x16x32_bf16 v[12:15], v[62:65], v[50:53], v[12:15]
	v_mfma_f32_16x16x32_bf16 v[16:19], v[62:65], v[54:57], v[16:19]
	s_setprio 0
	s_waitcnt vmcnt(3)
	s_waitcnt lgkmcnt(0)
	s_barrier
	ds_read_b128 v[58:61], v70 offset:8192
	ds_read_b128 v[24:27], v32
	ds_read_b128 v[46:49], v32 offset:1024
	ds_read_b128 v[50:53], v32 offset:2048
	ds_read_b128 v[54:57], v32 offset:3072
	ds_read_b128 v[62:65], v70 offset:9216
	s_setprio 1
	s_mov_b64 s[34:35], 0x17002c0
	s_mov_b64 s[92:93], 0x2c0
	s_waitcnt lgkmcnt(4)
	v_mfma_f32_16x16x32_bf16 v[34:37], v[58:61], v[24:27], v[34:37]
	v_lshl_add_u64 v[66:67], v[2:3], 0, s[34:35]
	v_lshl_add_u64 v[2:3], v[0:1], 0, s[92:93]
	s_waitcnt lgkmcnt(3)
	v_mfma_f32_16x16x32_bf16 v[38:41], v[58:61], v[46:49], v[38:41]
	s_mov_b32 m0, s41
	s_nop 0
	global_load_lds_dwordx4 v[2:3], off
	s_waitcnt lgkmcnt(2)
	v_mfma_f32_16x16x32_bf16 v[42:45], v[58:61], v[50:53], v[42:45]
	s_waitcnt lgkmcnt(1)
	v_mfma_f32_16x16x32_bf16 v[20:23], v[58:61], v[54:57], v[20:23]
	s_mov_b64 s[78:79], 0xc2c0
	v_lshl_add_u64 v[0:1], v[0:1], 0, s[78:79]
	s_mov_b32 m0, s42
	s_nop 0
	global_load_lds_dwordx4 v[0:1], off
	s_waitcnt lgkmcnt(0)
	v_mfma_f32_16x16x32_bf16 v[0:3], v[62:65], v[24:27], v[4:7]
	v_mfma_f32_16x16x32_bf16 v[4:7], v[62:65], v[46:49], v[8:11]
	s_mov_b32 m0, s43
	s_nop 0
	global_load_lds_dwordx4 v[66:67], off
	v_mfma_f32_16x16x32_bf16 v[8:11], v[62:65], v[50:53], v[12:15]
	v_mfma_f32_16x16x32_bf16 v[12:15], v[62:65], v[54:57], v[16:19]
	s_setprio 0
	s_waitcnt vmcnt(3)
	s_waitcnt lgkmcnt(0)
	s_barrier
;     __device__ __forceinline__ bf16_t* G() const { return (bf16_t*)(ws + OFF_G); }
; DEV void ld_bf4(const bf16_t* p, float (&v)[4]) { uint2 w = *(const uint2*)p; v[0] = bf_lo(w.x); v[1] = bf_hi(w.x); v[2] = bf_lo(w.y); v[3] = bf_hi(w.y); }
; #define RAW_BARRIER() do { asm volatile("s_waitcnt lgkmcnt(0)" ::: "memory"); __builtin_amdgcn_s_barrier(); } while (0)
; #define GLDS_TILE(kt, st) do { _Pragma("unroll") for (int _i = 0; _i < NP; ++_i) GLDS_PIECE(_i, kt, st); } while (0)
;     ...
;     constexpr int NH = NI >= 4 ? NI / 2 : NI;
;     constexpr int NP = 2 + NB, IVL = (4 * NI) / NP;
;     RAW_BARRIER();
;     GLDS_TILE(0, 0);
;     GLDS_TILE(1, 1);
;     int st = 0;
;     for (int kt = 0; kt < nk - 1; ++kt) {
;         if (NI == 8) asm volatile("s_waitcnt vmcnt(6)" ::: "memory"); else if (NI == 4) asm volatile("s_waitcnt vmcnt(4)" ::: "memory"); else asm volatile("s_waitcnt vmcnt(3)" ::: "memory");
;         RAW_BARRIER();
;         const int s2 = st >= 1 ? st - 1 : 2;
;         const bool ld = kt + 2 < nk;
;         STEP_TILE(st, ld, kt + 2, s2);
;         st = st == 2 ? 0 : st + 1;
;     }
;     asm volatile("s_waitcnt vmcnt(0)" ::: "memory");
;     RAW_BARRIER();
;     STEP_TILE(st, false, 0, 0);
; DEV void merge_big(const Params& p, int l, int mt, int nt, char* smem) {
;     ...
; #pragma unroll
;         for (int mi = 0; mi < 4; ++mi)
; #pragma unroll
;             for (int ni = 0; ni < 2; ++ni) {
;                 float g[4]; ld_bf4(p.G() + (size_t)(rbase + mi * 16) * 3072 + br * 1024 + c0 + ni * 16, g);
;                 const f32x4 gv = (f32x4){g[0], g[1], g[2], g[3]};
;                 if (br == 0) mg[mi][ni] = gv * acc[mi][ni]; else mg[mi][ni] += gv * acc[mi][ni];
	s_nop 0
	ds_read_b128 v[16:19], v32 offset:12288
	ds_read_b128 v[24:27], v32 offset:13312
	ds_read_b128 v[46:49], v32 offset:14336
	ds_read_b128 v[50:53], v32 offset:15360
	ds_read_b128 v[54:57], v70 offset:20480
	ds_read_b128 v[58:61], v70 offset:21504
	s_setprio 1
	s_waitcnt lgkmcnt(0)
	v_mfma_f32_16x16x32_bf16 v[34:37], v[54:57], v[16:19], v[34:37]
	v_mfma_f32_16x16x32_bf16 v[38:41], v[54:57], v[24:27], v[38:41]
	v_mfma_f32_16x16x32_bf16 v[42:45], v[54:57], v[46:49], v[42:45]
	v_mfma_f32_16x16x32_bf16 v[20:23], v[54:57], v[50:53], v[20:23]
	v_mfma_f32_16x16x32_bf16 v[54:57], v[58:61], v[16:19], v[0:3]
	v_mfma_f32_16x16x32_bf16 v[62:65], v[58:61], v[24:27], v[4:7]
	v_mfma_f32_16x16x32_bf16 v[46:49], v[58:61], v[46:49], v[8:11]
	v_mfma_f32_16x16x32_bf16 v[50:53], v[58:61], v[50:53], v[12:15]
	s_setprio 0
	s_waitcnt vmcnt(0)
	s_waitcnt lgkmcnt(0)
	s_barrier
	ds_read_b128 v[24:27], v70 offset:32768
	ds_read_b128 v[4:7], v32 offset:24576
	ds_read_b128 v[12:15], v32 offset:25600
	ds_read_b128 v[58:61], v32 offset:26624
	ds_read_b128 v[66:69], v32 offset:27648
	ds_read_b128 v[70:73], v70 offset:33792
	s_setprio 1
	s_waitcnt lgkmcnt(4)
	v_mfma_f32_16x16x32_bf16 v[0:3], v[24:27], v[4:7], v[34:37]
	s_waitcnt lgkmcnt(3)
	v_mfma_f32_16x16x32_bf16 v[8:11], v[24:27], v[12:15], v[38:41]
	s_waitcnt lgkmcnt(2)
	v_mfma_f32_16x16x32_bf16 v[16:19], v[24:27], v[58:61], v[42:45]
	s_waitcnt lgkmcnt(1)
	v_mfma_f32_16x16x32_bf16 v[24:27], v[24:27], v[66:69], v[20:23]
	s_waitcnt lgkmcnt(0)
	v_mfma_f32_16x16x32_bf16 v[4:7], v[70:73], v[4:7], v[54:57]
	v_mfma_f32_16x16x32_bf16 v[12:15], v[70:73], v[12:15], v[62:65]
	v_mfma_f32_16x16x32_bf16 v[20:23], v[70:73], v[58:61], v[46:49]
	v_mfma_f32_16x16x32_bf16 v[38:41], v[70:73], v[66:69], v[50:53]
	s_setprio 0
	v_lshlrev_b64 v[96:97], 1, v[28:29]
	v_lshl_add_u64 v[28:29], s[4:5], 0, v[96:97]
	v_mad_i64_i32 v[34:35], s[34:35], v94, s51, v[28:29]
	v_add_u32_e32 v102, 0x4010, v30
	v_add_u32_e32 v100, 0x4020, v30
	s_waitcnt lgkmcnt(0)
	s_barrier
	v_mad_i64_i32 v[36:37], s[34:35], v102, s51, v[28:29]
	s_waitcnt vmcnt(0)
	flat_load_dwordx2 v[104:105], v[34:35]
	flat_load_dwordx2 v[106:107], v[34:35] offset:32
	flat_load_dwordx2 v[108:109], v[36:37]
	flat_load_dwordx2 v[110:111], v[36:37] offset:32
	v_mad_i64_i32 v[34:35], s[34:35], v100, s51, v[28:29]
	v_add_u32_e32 v98, 0x4030, v30
	v_mov_b32_e32 v42, v186
	v_mad_i64_i32 v[28:29], s[34:35], v98, s51, v[28:29]
	flat_load_dwordx2 v[112:113], v[34:35]
	flat_load_dwordx2 v[114:115], v[34:35] offset:32
	flat_load_dwordx2 v[116:117], v[28:29]
	flat_load_dwordx2 v[122:123], v[28:29] offset:32
	s_waitcnt lgkmcnt(0)
	s_barrier
	v_bfe_u32 v44, v42, 4, 2
	v_sub_u32_e32 v34, 0, v44
	v_ashrrev_i32_e32 v43, 6, v42
	v_bfe_u32 v28, v42, 2, 4
	v_xor_b32_e32 v31, v42, v34
	v_lshl_or_b32 v30, v43, 4, v28
	v_mov_b64_e32 v[28:29], s[6:7]
	v_lshlrev_b32_e32 v31, 4, v31
	v_mad_i64_i32 v[28:29], s[34:35], v30, s48, v[28:29]
	v_and_b32_e32 v32, 48, v31
	v_lshl_add_u64 v[28:29], v[28:29], 0, v[32:33]
	v_mad_i64_i32 v[30:31], s[34:35], v30, s48, 0
	v_bitop3_b32 v32, v42, 3, v34 bitop3:0x48
	v_lshl_or_b32 v30, v32, 4, v30
	v_lshl_add_u32 v32, v43, 10, 0
	v_add_u32_e32 v46, 0x1000, v32
	v_readfirstlane_b32 s41, v32
	v_add_u32_e32 v45, 0x2000, v32
	s_mov_b32 m0, s41
	v_readfirstlane_b32 s40, v46
	v_lshl_add_u64 v[30:31], s[18:19], 0, v[30:31]
	s_mov_b64 s[18:19], 0x1880000
	global_load_lds_dwordx4 v[28:29], off
	v_lshl_add_u64 v[36:37], v[28:29], 0, s[66:67]
	s_mov_b32 m0, s40
	v_readfirstlane_b32 s39, v45
	v_add_u32_e32 v45, 0x3000, v32
	v_lshl_add_u64 v[34:35], v[30:31], 0, s[18:19]
	global_load_lds_dwordx4 v[36:37], off
	s_mov_b32 m0, s39
	s_mov_b64 s[18:19], 0x1880040
	v_readfirstlane_b32 s31, v45
	v_add_u32_e32 v45, 0x4000, v32
	global_load_lds_dwordx4 v[34:35], off
	v_lshl_add_u64 v[34:35], v[30:31], 0, s[18:19]
	v_add_u32_e32 v46, 0x5000, v32
	v_lshl_add_u64 v[36:37], v[28:29], 0, 64
	s_mov_b32 m0, s31
	v_readfirstlane_b32 s19, v45
	global_load_lds_dwordx4 v[36:37], off
	v_lshl_add_u64 v[36:37], v[28:29], 0, s[68:69]
	s_mov_b32 m0, s19
	v_readfirstlane_b32 s18, v46
	global_load_lds_dwordx4 v[36:37], off
	s_mov_b32 m0, s18
	v_lshlrev_b32_e32 v36, 11, v43
	global_load_lds_dwordx4 v[34:35], off
	v_lshrrev_b32_e32 v35, 2, v42
	v_lshlrev_b32_e32 v34, 6, v42
	v_sub_u32_e32 v35, 0, v35
	v_and_b32_e32 v34, 0x3c0, v34
	v_bitop3_b32 v35, v44, v35, 3 bitop3:0x78
	v_lshl_or_b32 v34, v35, 4, v34
	v_lshlrev_b32_e32 v35, 5, v42
	v_and_or_b32 v35, v35, s49, v34
	s_waitcnt vmcnt(3)
	v_add_u32_e32 v124, 0, v35
	v_and_or_b32 v54, v36, s50, v34
	s_waitcnt lgkmcnt(0)
	s_barrier
	ds_read_b128 v[34:37], v124
	ds_read_b128 v[42:45], v124 offset:1024
	ds_read_b128 v[46:49], v124 offset:2048
	ds_read_b128 v[50:53], v124 offset:3072
	v_add_u32_e32 v125, 0, v54
	ds_read_b128 v[54:57], v125 offset:8192
	ds_read_b128 v[58:61], v125 offset:9216
	v_ashrrev_i32_e32 v95, 31, v94
	v_ashrrev_i32_e32 v103, 31, v102
	v_ashrrev_i32_e32 v101, 31, v100
	v_ashrrev_i32_e32 v99, 31, v98
	s_setprio 1
	s_mov_b64 s[34:35], 0x1880080
	v_add_u32_e32 v72, 0x6000, v32
	s_waitcnt lgkmcnt(0)
	v_mfma_f32_16x16x32_bf16 v[62:65], v[54:57], v[34:37], 0
	v_lshl_add_u64 v[74:75], v[30:31], 0, s[34:35]
	v_add_u32_e32 v78, 0x8000, v32
	v_lshl_add_u64 v[70:71], v[28:29], 0, s[54:55]
	v_mfma_f32_16x16x32_bf16 v[66:69], v[54:57], v[42:45], 0
	v_readfirstlane_b32 s34, v72
	s_mov_b32 m0, s34
	s_nop 0
	global_load_lds_dwordx4 v[70:71], off
	v_mfma_f32_16x16x32_bf16 v[70:73], v[54:57], v[46:49], 0
	v_mfma_f32_16x16x32_bf16 v[54:57], v[54:57], v[50:53], 0
	v_add_u32_e32 v32, 0x7000, v32
	v_lshl_add_u64 v[76:77], v[28:29], 0, s[96:97]
	v_readfirstlane_b32 s35, v32
	s_mov_b32 m0, s35
	s_nop 0
	global_load_lds_dwordx4 v[76:77], off
	v_mfma_f32_16x16x32_bf16 v[34:37], v[58:61], v[34:37], 0
	v_mfma_f32_16x16x32_bf16 v[42:45], v[58:61], v[42:45], 0
	v_readfirstlane_b32 s38, v78
	s_mov_b32 m0, s38
	s_nop 0
	global_load_lds_dwordx4 v[74:75], off
	v_mfma_f32_16x16x32_bf16 v[46:49], v[58:61], v[46:49], 0
	v_mfma_f32_16x16x32_bf16 v[50:53], v[58:61], v[50:53], 0
	s_setprio 0
	s_waitcnt vmcnt(3)
	s_waitcnt lgkmcnt(0)
	s_barrier
; #define RAW_BARRIER() do { asm volatile("s_waitcnt lgkmcnt(0)" ::: "memory"); __builtin_amdgcn_s_barrier(); } while (0)
; #define GLDS_TILE(kt, st) do { _Pragma("unroll") for (int _i = 0; _i < NP; ++_i) GLDS_PIECE(_i, kt, st); } while (0)
;     ...
;     constexpr int NH = NI >= 4 ? NI / 2 : NI;
;     constexpr int NP = 2 + NB, IVL = (4 * NI) / NP;
;     RAW_BARRIER();
;     GLDS_TILE(0, 0);
;     GLDS_TILE(1, 1);
;     int st = 0;
;     for (int kt = 0; kt < nk - 1; ++kt) {
;         if (NI == 8) asm volatile("s_waitcnt vmcnt(6)" ::: "memory"); else if (NI == 4) asm volatile("s_waitcnt vmcnt(4)" ::: "memory"); else asm volatile("s_waitcnt vmcnt(3)" ::: "memory");
;         RAW_BARRIER();
;         const int s2 = st >= 1 ? st - 1 : 2;
;         const bool ld = kt + 2 < nk;
;         STEP_TILE(st, ld, kt + 2, s2);
;         st = st == 2 ? 0 : st + 1;
;     }
	ds_read_b128 v[86:89], v125 offset:20480
	ds_read_b128 v[58:61], v124 offset:12288
	ds_read_b128 v[74:77], v124 offset:13312
	ds_read_b128 v[78:81], v124 offset:14336
	ds_read_b128 v[82:85], v124 offset:15360
	ds_read_b128 v[90:93], v125 offset:21504
	s_setprio 1
	s_mov_b64 s[42:43], 0x18800c0
	s_waitcnt lgkmcnt(4)
	v_mfma_f32_16x16x32_bf16 v[62:65], v[86:89], v[58:61], v[62:65]
	v_lshl_add_u64 v[118:119], v[30:31], 0, s[42:43]
	v_lshl_add_u64 v[120:121], v[28:29], 0, s[56:57]
	s_waitcnt lgkmcnt(3)
	v_mfma_f32_16x16x32_bf16 v[66:69], v[86:89], v[74:77], v[66:69]
	s_mov_b32 m0, s41
	s_nop 0
	global_load_lds_dwordx4 v[120:121], off
	s_waitcnt lgkmcnt(2)
	v_mfma_f32_16x16x32_bf16 v[70:73], v[86:89], v[78:81], v[70:73]
	s_waitcnt lgkmcnt(1)
	v_mfma_f32_16x16x32_bf16 v[54:57], v[86:89], v[82:85], v[54:57]
	v_lshl_add_u64 v[86:87], v[28:29], 0, s[94:95]
	s_mov_b32 m0, s40
	s_nop 0
	global_load_lds_dwordx4 v[86:87], off
	s_waitcnt lgkmcnt(0)
	v_mfma_f32_16x16x32_bf16 v[34:37], v[90:93], v[58:61], v[34:37]
	v_mfma_f32_16x16x32_bf16 v[42:45], v[90:93], v[74:77], v[42:45]
	s_mov_b32 m0, s39
	s_nop 0
	global_load_lds_dwordx4 v[118:119], off
	v_mfma_f32_16x16x32_bf16 v[46:49], v[90:93], v[78:81], v[46:49]
	v_mfma_f32_16x16x32_bf16 v[50:53], v[90:93], v[82:85], v[50:53]
	s_setprio 0
	s_waitcnt vmcnt(3)
	s_waitcnt lgkmcnt(0)
	s_barrier
	ds_read_b128 v[86:89], v125 offset:32768
	ds_read_b128 v[58:61], v124 offset:24576
	ds_read_b128 v[74:77], v124 offset:25600
	ds_read_b128 v[78:81], v124 offset:26624
	ds_read_b128 v[82:85], v124 offset:27648
	ds_read_b128 v[90:93], v125 offset:33792
	s_setprio 1
	s_mov_b64 s[42:43], 0x1880100
	s_waitcnt lgkmcnt(4)
	v_mfma_f32_16x16x32_bf16 v[62:65], v[86:89], v[58:61], v[62:65]
	v_lshl_add_u64 v[118:119], v[30:31], 0, s[42:43]
	v_lshl_add_u64 v[120:121], v[28:29], 0, s[58:59]
	s_waitcnt lgkmcnt(3)
	v_mfma_f32_16x16x32_bf16 v[66:69], v[86:89], v[74:77], v[66:69]
	s_mov_b32 m0, s31
	s_nop 0
	global_load_lds_dwordx4 v[120:121], off
	s_waitcnt lgkmcnt(2)
	v_mfma_f32_16x16x32_bf16 v[70:73], v[86:89], v[78:81], v[70:73]
	s_waitcnt lgkmcnt(1)
	v_mfma_f32_16x16x32_bf16 v[54:57], v[86:89], v[82:85], v[54:57]
	v_lshl_add_u64 v[86:87], v[28:29], 0, s[70:71]
	s_mov_b32 m0, s19
	s_nop 0
	global_load_lds_dwordx4 v[86:87], off
	s_waitcnt lgkmcnt(0)
	v_mfma_f32_16x16x32_bf16 v[34:37], v[90:93], v[58:61], v[34:37]
	v_mfma_f32_16x16x32_bf16 v[42:45], v[90:93], v[74:77], v[42:45]
	s_mov_b32 m0, s18
	s_nop 0
	global_load_lds_dwordx4 v[118:119], off
	v_mfma_f32_16x16x32_bf16 v[46:49], v[90:93], v[78:81], v[46:49]
	v_mfma_f32_16x16x32_bf16 v[50:53], v[90:93], v[82:85], v[50:53]
	s_setprio 0
	s_waitcnt vmcnt(3)
	s_waitcnt lgkmcnt(0)
	s_barrier
	ds_read_b128 v[86:89], v125 offset:8192
	ds_read_b128 v[58:61], v124
	ds_read_b128 v[74:77], v124 offset:1024
	ds_read_b128 v[78:81], v124 offset:2048
	ds_read_b128 v[82:85], v124 offset:3072
	ds_read_b128 v[90:93], v125 offset:9216
	s_setprio 1
	s_mov_b64 s[42:43], 0x1880140
	s_waitcnt lgkmcnt(4)
	v_mfma_f32_16x16x32_bf16 v[62:65], v[86:89], v[58:61], v[62:65]
	v_lshl_add_u64 v[118:119], v[30:31], 0, s[42:43]
	v_lshl_add_u64 v[120:121], v[28:29], 0, s[60:61]
	s_waitcnt lgkmcnt(3)
	v_mfma_f32_16x16x32_bf16 v[66:69], v[86:89], v[74:77], v[66:69]
	s_mov_b32 m0, s34
	s_nop 0
	global_load_lds_dwordx4 v[120:121], off
	s_waitcnt lgkmcnt(2)
	v_mfma_f32_16x16x32_bf16 v[70:73], v[86:89], v[78:81], v[70:73]
	s_waitcnt lgkmcnt(1)
	v_mfma_f32_16x16x32_bf16 v[54:57], v[86:89], v[82:85], v[54:57]
	v_lshl_add_u64 v[86:87], v[28:29], 0, s[72:73]
	s_mov_b32 m0, s35
	s_nop 0
	global_load_lds_dwordx4 v[86:87], off
	s_waitcnt lgkmcnt(0)
	v_mfma_f32_16x16x32_bf16 v[34:37], v[90:93], v[58:61], v[34:37]
	v_mfma_f32_16x16x32_bf16 v[42:45], v[90:93], v[74:77], v[42:45]
	s_mov_b32 m0, s38
	s_nop 0
	global_load_lds_dwordx4 v[118:119], off
	v_mfma_f32_16x16x32_bf16 v[46:49], v[90:93], v[78:81], v[46:49]
	v_mfma_f32_16x16x32_bf16 v[50:53], v[90:93], v[82:85], v[50:53]
	s_setprio 0
	s_waitcnt vmcnt(3)
	s_waitcnt lgkmcnt(0)
	s_barrier
	ds_read_b128 v[86:89], v125 offset:20480
	ds_read_b128 v[58:61], v124 offset:12288
	ds_read_b128 v[74:77], v124 offset:13312
	ds_read_b128 v[78:81], v124 offset:14336
	ds_read_b128 v[82:85], v124 offset:15360
	ds_read_b128 v[90:93], v125 offset:21504
	s_setprio 1
	s_mov_b64 s[42:43], 0x1880180
	s_waitcnt lgkmcnt(4)
	v_mfma_f32_16x16x32_bf16 v[62:65], v[86:89], v[58:61], v[62:65]
	v_lshl_add_u64 v[118:119], v[30:31], 0, s[42:43]
	v_lshl_add_u64 v[120:121], v[28:29], 0, s[62:63]
	s_waitcnt lgkmcnt(3)
	v_mfma_f32_16x16x32_bf16 v[66:69], v[86:89], v[74:77], v[66:69]
	s_mov_b32 m0, s41
	s_nop 0
	global_load_lds_dwordx4 v[120:121], off
	s_waitcnt lgkmcnt(2)
	v_mfma_f32_16x16x32_bf16 v[70:73], v[86:89], v[78:81], v[70:73]
	s_waitcnt lgkmcnt(1)
	v_mfma_f32_16x16x32_bf16 v[54:57], v[86:89], v[82:85], v[54:57]
	v_lshl_add_u64 v[86:87], v[28:29], 0, s[84:85]
	s_mov_b32 m0, s40
	s_nop 0
	global_load_lds_dwordx4 v[86:87], off
	s_waitcnt lgkmcnt(0)
	v_mfma_f32_16x16x32_bf16 v[34:37], v[90:93], v[58:61], v[34:37]
	v_mfma_f32_16x16x32_bf16 v[42:45], v[90:93], v[74:77], v[42:45]
	s_mov_b32 m0, s39
	s_nop 0
	global_load_lds_dwordx4 v[118:119], off
	v_mfma_f32_16x16x32_bf16 v[46:49], v[90:93], v[78:81], v[46:49]
	v_mfma_f32_16x16x32_bf16 v[50:53], v[90:93], v[82:85], v[50:53]
	s_setprio 0
	s_waitcnt vmcnt(3)
	s_waitcnt lgkmcnt(0)
	s_barrier
; #define RAW_BARRIER() do { asm volatile("s_waitcnt lgkmcnt(0)" ::: "memory"); __builtin_amdgcn_s_barrier(); } while (0)
; #define GLDS_TILE(kt, st) do { _Pragma("unroll") for (int _i = 0; _i < NP; ++_i) GLDS_PIECE(_i, kt, st); } while (0)
;     ...
;     constexpr int NH = NI >= 4 ? NI / 2 : NI;
;     constexpr int NP = 2 + NB, IVL = (4 * NI) / NP;
;     RAW_BARRIER();
;     GLDS_TILE(0, 0);
;     GLDS_TILE(1, 1);
;     int st = 0;
;     for (int kt = 0; kt < nk - 1; ++kt) {
;         if (NI == 8) asm volatile("s_waitcnt vmcnt(6)" ::: "memory"); else if (NI == 4) asm volatile("s_waitcnt vmcnt(4)" ::: "memory"); else asm volatile("s_waitcnt vmcnt(3)" ::: "memory");
;         RAW_BARRIER();
;         const int s2 = st >= 1 ? st - 1 : 2;
;         const bool ld = kt + 2 < nk;
;         STEP_TILE(st, ld, kt + 2, s2);
;         st = st == 2 ? 0 : st + 1;
;     }
	ds_read_b128 v[86:89], v125 offset:32768
	ds_read_b128 v[58:61], v124 offset:24576
	ds_read_b128 v[74:77], v124 offset:25600
	ds_read_b128 v[78:81], v124 offset:26624
	ds_read_b128 v[82:85], v124 offset:27648
	ds_read_b128 v[90:93], v125 offset:33792
	s_setprio 1
	s_mov_b64 s[42:43], 0x18801c0
	s_waitcnt lgkmcnt(4)
	v_mfma_f32_16x16x32_bf16 v[62:65], v[86:89], v[58:61], v[62:65]
	v_lshl_add_u64 v[118:119], v[30:31], 0, s[42:43]
	v_lshl_add_u64 v[120:121], v[28:29], 0, s[64:65]
	s_waitcnt lgkmcnt(3)
	v_mfma_f32_16x16x32_bf16 v[66:69], v[86:89], v[74:77], v[66:69]
	s_mov_b32 m0, s31
	s_nop 0
	global_load_lds_dwordx4 v[120:121], off
	s_waitcnt lgkmcnt(2)
	v_mfma_f32_16x16x32_bf16 v[70:73], v[86:89], v[78:81], v[70:73]
	s_waitcnt lgkmcnt(1)
	v_mfma_f32_16x16x32_bf16 v[54:57], v[86:89], v[82:85], v[54:57]
	v_lshl_add_u64 v[86:87], v[28:29], 0, s[46:47]
	s_mov_b32 m0, s19
	s_nop 0
	global_load_lds_dwordx4 v[86:87], off
	s_waitcnt lgkmcnt(0)
	v_mfma_f32_16x16x32_bf16 v[34:37], v[90:93], v[58:61], v[34:37]
	v_mfma_f32_16x16x32_bf16 v[42:45], v[90:93], v[74:77], v[42:45]
	s_mov_b32 m0, s18
	s_nop 0
	global_load_lds_dwordx4 v[118:119], off
	v_mfma_f32_16x16x32_bf16 v[46:49], v[90:93], v[78:81], v[46:49]
	v_mfma_f32_16x16x32_bf16 v[50:53], v[90:93], v[82:85], v[50:53]
	s_setprio 0
	s_waitcnt vmcnt(3)
	s_waitcnt lgkmcnt(0)
	s_barrier
	ds_read_b128 v[86:89], v125 offset:8192
	ds_read_b128 v[58:61], v124
	ds_read_b128 v[74:77], v124 offset:1024
	ds_read_b128 v[78:81], v124 offset:2048
	ds_read_b128 v[82:85], v124 offset:3072
	ds_read_b128 v[90:93], v125 offset:9216
	s_setprio 1
	s_mov_b64 s[42:43], 0x1880200
	s_waitcnt lgkmcnt(4)
	v_mfma_f32_16x16x32_bf16 v[62:65], v[86:89], v[58:61], v[62:65]
	v_lshl_add_u64 v[118:119], v[30:31], 0, s[42:43]
	v_lshl_add_u64 v[120:121], v[28:29], 0, s[76:77]
	s_mov_b64 s[76:77], 0x8080
	s_mov_b64 s[46:47], 0x8040
	s_mov_b64 s[44:45], 0x8000
	s_waitcnt lgkmcnt(3)
	v_mfma_f32_16x16x32_bf16 v[66:69], v[86:89], v[74:77], v[66:69]
	s_mov_b32 m0, s34
	s_nop 0
	global_load_lds_dwordx4 v[120:121], off
	s_waitcnt lgkmcnt(2)
	v_mfma_f32_16x16x32_bf16 v[70:73], v[86:89], v[78:81], v[70:73]
	s_waitcnt lgkmcnt(1)
	v_mfma_f32_16x16x32_bf16 v[54:57], v[86:89], v[82:85], v[54:57]
	v_lshl_add_u64 v[86:87], v[28:29], 0, vcc
	s_mov_b32 m0, s35
	s_nop 0
	global_load_lds_dwordx4 v[86:87], off
	s_waitcnt lgkmcnt(0)
	v_mfma_f32_16x16x32_bf16 v[34:37], v[90:93], v[58:61], v[34:37]
	v_mfma_f32_16x16x32_bf16 v[42:45], v[90:93], v[74:77], v[42:45]
	s_mov_b32 m0, s38
	s_nop 0
	global_load_lds_dwordx4 v[118:119], off
	v_mfma_f32_16x16x32_bf16 v[46:49], v[90:93], v[78:81], v[46:49]
	v_mfma_f32_16x16x32_bf16 v[50:53], v[90:93], v[82:85], v[50:53]
	s_setprio 0
	s_waitcnt vmcnt(3)
	s_waitcnt lgkmcnt(0)
	s_barrier
	ds_read_b128 v[86:89], v125 offset:20480
	ds_read_b128 v[58:61], v124 offset:12288
	ds_read_b128 v[74:77], v124 offset:13312
	ds_read_b128 v[78:81], v124 offset:14336
	ds_read_b128 v[82:85], v124 offset:15360
	ds_read_b128 v[90:93], v125 offset:21504
	s_setprio 1
	s_mov_b64 s[42:43], 0x1880240
	s_waitcnt lgkmcnt(4)
	v_mfma_f32_16x16x32_bf16 v[62:65], v[86:89], v[58:61], v[62:65]
	v_lshl_add_u64 v[118:119], v[30:31], 0, s[42:43]
	v_lshl_add_u64 v[120:121], v[28:29], 0, s[86:87]
	s_waitcnt lgkmcnt(3)
	v_mfma_f32_16x16x32_bf16 v[66:69], v[86:89], v[74:77], v[66:69]
	s_mov_b32 m0, s41
	s_nop 0
	global_load_lds_dwordx4 v[120:121], off
	s_waitcnt lgkmcnt(2)
	v_mfma_f32_16x16x32_bf16 v[70:73], v[86:89], v[78:81], v[70:73]
	s_waitcnt lgkmcnt(1)
	v_mfma_f32_16x16x32_bf16 v[54:57], v[86:89], v[82:85], v[54:57]
	v_lshl_add_u64 v[86:87], v[28:29], 0, s[90:91]
	s_mov_b32 m0, s40
	s_nop 0
	global_load_lds_dwordx4 v[86:87], off
	s_waitcnt lgkmcnt(0)
	v_mfma_f32_16x16x32_bf16 v[34:37], v[90:93], v[58:61], v[34:37]
	v_mfma_f32_16x16x32_bf16 v[42:45], v[90:93], v[74:77], v[42:45]
	s_mov_b32 m0, s39
	s_nop 0
	global_load_lds_dwordx4 v[118:119], off
	v_mfma_f32_16x16x32_bf16 v[46:49], v[90:93], v[78:81], v[46:49]
	v_mfma_f32_16x16x32_bf16 v[50:53], v[90:93], v[82:85], v[50:53]
	s_setprio 0
	s_waitcnt vmcnt(3)
	s_waitcnt lgkmcnt(0)
	s_barrier
	ds_read_b128 v[86:89], v125 offset:32768
	ds_read_b128 v[58:61], v124 offset:24576
	ds_read_b128 v[74:77], v124 offset:25600
	ds_read_b128 v[78:81], v124 offset:26624
	ds_read_b128 v[82:85], v124 offset:27648
	ds_read_b128 v[90:93], v125 offset:33792
	s_setprio 1
	s_mov_b64 s[40:41], 0x1880280
	s_waitcnt lgkmcnt(4)
	v_mfma_f32_16x16x32_bf16 v[62:65], v[86:89], v[58:61], v[62:65]
	v_lshl_add_u64 v[118:119], v[30:31], 0, s[40:41]
	v_lshl_add_u64 v[120:121], v[28:29], 0, s[88:89]
	s_waitcnt lgkmcnt(3)
	v_mfma_f32_16x16x32_bf16 v[66:69], v[86:89], v[74:77], v[66:69]
	s_mov_b32 m0, s31
	s_nop 0
	global_load_lds_dwordx4 v[120:121], off
	s_waitcnt lgkmcnt(2)
	v_mfma_f32_16x16x32_bf16 v[70:73], v[86:89], v[78:81], v[70:73]
	s_waitcnt lgkmcnt(1)
	v_mfma_f32_16x16x32_bf16 v[54:57], v[86:89], v[82:85], v[54:57]
	v_lshl_add_u64 v[86:87], v[28:29], 0, s[80:81]
	s_mov_b32 m0, s19
	s_nop 0
	global_load_lds_dwordx4 v[86:87], off
	s_waitcnt lgkmcnt(0)
	v_mfma_f32_16x16x32_bf16 v[34:37], v[90:93], v[58:61], v[34:37]
	v_mfma_f32_16x16x32_bf16 v[42:45], v[90:93], v[74:77], v[42:45]
	s_mov_b32 m0, s18
	s_nop 0
	global_load_lds_dwordx4 v[118:119], off
	v_mfma_f32_16x16x32_bf16 v[46:49], v[90:93], v[78:81], v[46:49]
	v_mfma_f32_16x16x32_bf16 v[50:53], v[90:93], v[82:85], v[50:53]
	s_setprio 0
	s_waitcnt vmcnt(3)
	s_waitcnt lgkmcnt(0)
	s_barrier
;     __device__ __forceinline__ bf16_t* G() const { return (bf16_t*)(ws + OFF_G); }
; DEV void ld_bf4(const bf16_t* p, float (&v)[4]) { uint2 w = *(const uint2*)p; v[0] = bf_lo(w.x); v[1] = bf_hi(w.x); v[2] = bf_lo(w.y); v[3] = bf_hi(w.y); }
; #define RAW_BARRIER() do { asm volatile("s_waitcnt lgkmcnt(0)" ::: "memory"); __builtin_amdgcn_s_barrier(); } while (0)
; #define GLDS_TILE(kt, st) do { _Pragma("unroll") for (int _i = 0; _i < NP; ++_i) GLDS_PIECE(_i, kt, st); } while (0)
;     ...
;     constexpr int NH = NI >= 4 ? NI / 2 : NI;
;     constexpr int NP = 2 + NB, IVL = (4 * NI) / NP;
;     RAW_BARRIER();
;     GLDS_TILE(0, 0);
;     GLDS_TILE(1, 1);
;     int st = 0;
;     for (int kt = 0; kt < nk - 1; ++kt) {
;         if (NI == 8) asm volatile("s_waitcnt vmcnt(6)" ::: "memory"); else if (NI == 4) asm volatile("s_waitcnt vmcnt(4)" ::: "memory"); else asm volatile("s_waitcnt vmcnt(3)" ::: "memory");
;         RAW_BARRIER();
;         const int s2 = st >= 1 ? st - 1 : 2;
;         const bool ld = kt + 2 < nk;
;         STEP_TILE(st, ld, kt + 2, s2);
;         st = st == 2 ? 0 : st + 1;
;     }
;     asm volatile("s_waitcnt vmcnt(0)" ::: "memory");
;     RAW_BARRIER();
;     STEP_TILE(st, false, 0, 0);
; DEV void merge_big(const Params& p, int l, int mt, int nt, char* smem) {
;     ...
; #pragma unroll
;         for (int mi = 0; mi < 4; ++mi)
; #pragma unroll
;             for (int ni = 0; ni < 2; ++ni) {
;                 float g[4]; ld_bf4(p.G() + (size_t)(rbase + mi * 16) * 3072 + br * 1024 + c0 + ni * 16, g);
;                 const f32x4 gv = (f32x4){g[0], g[1], g[2], g[3]};
;                 if (br == 0) mg[mi][ni] = gv * acc[mi][ni]; else mg[mi][ni] += gv * acc[mi][ni];
	ds_read_b128 v[86:89], v125 offset:8192
	ds_read_b128 v[58:61], v124
	ds_read_b128 v[74:77], v124 offset:1024
	ds_read_b128 v[78:81], v124 offset:2048
	ds_read_b128 v[82:85], v124 offset:3072
	ds_read_b128 v[90:93], v125 offset:9216
	s_setprio 1
	s_mov_b64 s[18:19], 0x18802c0
	s_waitcnt lgkmcnt(4)
	v_mfma_f32_16x16x32_bf16 v[62:65], v[86:89], v[58:61], v[62:65]
	v_lshl_add_u64 v[118:119], v[30:31], 0, s[18:19]
	v_lshl_add_u64 v[30:31], v[28:29], 0, s[92:93]
	s_waitcnt lgkmcnt(3)
	v_mfma_f32_16x16x32_bf16 v[66:69], v[86:89], v[74:77], v[66:69]
	s_mov_b32 m0, s34
	s_nop 0
	global_load_lds_dwordx4 v[30:31], off
	s_waitcnt lgkmcnt(2)
	v_mfma_f32_16x16x32_bf16 v[70:73], v[86:89], v[78:81], v[70:73]
	s_waitcnt lgkmcnt(1)
	v_mfma_f32_16x16x32_bf16 v[54:57], v[86:89], v[82:85], v[54:57]
	v_lshl_add_u64 v[28:29], v[28:29], 0, s[78:79]
	s_mov_b32 m0, s35
	s_nop 0
	global_load_lds_dwordx4 v[28:29], off
	s_waitcnt lgkmcnt(0)
	v_mfma_f32_16x16x32_bf16 v[28:31], v[90:93], v[58:61], v[34:37]
	v_mfma_f32_16x16x32_bf16 v[34:37], v[90:93], v[74:77], v[42:45]
	s_mov_b32 m0, s38
	s_nop 0
	global_load_lds_dwordx4 v[118:119], off
	v_mfma_f32_16x16x32_bf16 v[42:45], v[90:93], v[78:81], v[46:49]
	v_mfma_f32_16x16x32_bf16 v[46:49], v[90:93], v[82:85], v[50:53]
	s_setprio 0
	s_waitcnt vmcnt(3)
	s_waitcnt lgkmcnt(0)
	s_barrier
	s_nop 0
	ds_read_b128 v[50:53], v124 offset:12288
	ds_read_b128 v[58:61], v124 offset:13312
	ds_read_b128 v[74:77], v124 offset:14336
	ds_read_b128 v[78:81], v124 offset:15360
	ds_read_b128 v[82:85], v125 offset:20480
	ds_read_b128 v[86:89], v125 offset:21504
	s_setprio 1
	s_waitcnt lgkmcnt(0)
	v_mfma_f32_16x16x32_bf16 v[62:65], v[82:85], v[50:53], v[62:65]
	v_mfma_f32_16x16x32_bf16 v[66:69], v[82:85], v[58:61], v[66:69]
	v_mfma_f32_16x16x32_bf16 v[70:73], v[82:85], v[74:77], v[70:73]
	v_mfma_f32_16x16x32_bf16 v[54:57], v[82:85], v[78:81], v[54:57]
	v_mfma_f32_16x16x32_bf16 v[82:85], v[86:89], v[50:53], v[28:31]
	v_mfma_f32_16x16x32_bf16 v[58:61], v[86:89], v[58:61], v[34:37]
	v_mfma_f32_16x16x32_bf16 v[74:77], v[86:89], v[74:77], v[42:45]
	v_mfma_f32_16x16x32_bf16 v[78:81], v[86:89], v[78:81], v[46:49]
	s_setprio 0
	s_waitcnt vmcnt(0)
	s_waitcnt lgkmcnt(0)
	s_barrier
	ds_read_b128 v[118:121], v125 offset:32768
	ds_read_b128 v[34:37], v124 offset:24576
	ds_read_b128 v[46:49], v124 offset:25600
	ds_read_b128 v[86:89], v124 offset:26624
	ds_read_b128 v[90:93], v124 offset:27648
	ds_read_b128 v[124:127], v125 offset:33792
	s_setprio 1
	s_waitcnt lgkmcnt(4)
	v_mfma_f32_16x16x32_bf16 v[28:31], v[118:121], v[34:37], v[62:65]
	s_waitcnt lgkmcnt(3)
	v_mfma_f32_16x16x32_bf16 v[42:45], v[118:121], v[46:49], v[66:69]
	s_waitcnt lgkmcnt(2)
	v_mfma_f32_16x16x32_bf16 v[50:53], v[118:121], v[86:89], v[70:73]
	s_waitcnt lgkmcnt(1)
	v_mfma_f32_16x16x32_bf16 v[66:69], v[118:121], v[90:93], v[54:57]
	s_waitcnt lgkmcnt(0)
	v_mfma_f32_16x16x32_bf16 v[34:37], v[124:127], v[34:37], v[82:85]
	v_mfma_f32_16x16x32_bf16 v[46:49], v[124:127], v[46:49], v[58:61]
	v_mfma_f32_16x16x32_bf16 v[54:57], v[124:127], v[86:89], v[74:77]
	v_mfma_f32_16x16x32_bf16 v[82:85], v[124:127], v[90:93], v[78:81]
	s_setprio 0
	v_lshl_add_u64 v[58:59], s[8:9], 0, v[96:97]
	v_mad_i64_i32 v[60:61], s[18:19], v94, s51, v[58:59]
	s_waitcnt lgkmcnt(0)
	s_barrier
	v_mad_i64_i32 v[62:63], s[18:19], v102, s51, v[58:59]
	s_waitcnt vmcnt(0)
	flat_load_dwordx2 v[118:119], v[60:61]
	flat_load_dwordx2 v[120:121], v[60:61] offset:32
	flat_load_dwordx2 v[124:125], v[62:63]
	flat_load_dwordx2 v[126:127], v[62:63] offset:32
	v_mad_i64_i32 v[60:61], s[18:19], v100, s51, v[58:59]
	v_mov_b32_e32 v70, v186
	v_mad_i64_i32 v[58:59], s[18:19], v98, s51, v[58:59]
	flat_load_dwordx2 v[128:129], v[60:61]
	flat_load_dwordx2 v[130:131], v[60:61] offset:32
	flat_load_dwordx2 v[136:137], v[58:59]
	flat_load_dwordx2 v[144:145], v[58:59] offset:32
	s_add_u32 s18, s2, s28
	v_ashrrev_i32_e32 v71, 6, v70
	v_bfe_u32 v72, v70, 4, 2
	v_bfe_u32 v32, v70, 2, 4
	v_lshl_or_b32 v58, v71, 4, v32
	v_sub_u32_e32 v62, 0, v72
	v_xor_b32_e32 v32, v70, v62
	v_ashrrev_i32_e32 v59, 31, v58
	v_lshlrev_b64 v[60:61], 9, v[58:59]
	v_lshlrev_b32_e32 v32, 4, v32
	v_lshl_add_u64 v[58:59], s[10:11], 0, v[60:61]
	v_and_b32_e32 v32, 48, v32
	v_lshl_add_u64 v[58:59], v[58:59], 0, v[32:33]
	v_bitop3_b32 v32, v70, 3, v62 bitop3:0x48
	v_lshl_or_b32 v60, v32, 4, v60
	v_lshl_add_u32 v32, v71, 10, 0
	v_add_u32_e32 v74, 0x1000, v32
	v_readfirstlane_b32 s38, v32
	s_addc_u32 s19, s3, s29
	v_add_u32_e32 v73, 0x2000, v32
	s_mov_b32 m0, s38
	v_readfirstlane_b32 s35, v74
	v_lshl_add_u64 v[60:61], s[18:19], 0, v[60:61]
	s_mov_b64 s[18:19], 0x1a00000
	s_waitcnt lgkmcnt(0)
	s_barrier
	global_load_lds_dwordx4 v[58:59], off
	v_lshl_add_u64 v[64:65], v[58:59], 0, s[44:45]
	s_mov_b32 m0, s35
	v_readfirstlane_b32 s34, v73
	v_add_u32_e32 v73, 0x3000, v32
	v_lshl_add_u64 v[62:63], v[60:61], 0, s[18:19]
	global_load_lds_dwordx4 v[64:65], off
	s_mov_b32 m0, s34
	s_mov_b64 s[18:19], 0x1a00040
	v_readfirstlane_b32 s31, v73
	v_add_u32_e32 v73, 0x4000, v32
	global_load_lds_dwordx4 v[62:63], off
	v_lshl_add_u64 v[62:63], v[60:61], 0, s[18:19]
	v_add_u32_e32 v74, 0x5000, v32
	v_lshl_add_u64 v[64:65], v[58:59], 0, 64
	s_mov_b32 m0, s31
	v_readfirstlane_b32 s19, v73
	global_load_lds_dwordx4 v[64:65], off
	v_lshl_add_u64 v[64:65], v[58:59], 0, s[46:47]
	s_mov_b32 m0, s19
	v_readfirstlane_b32 s18, v74
	global_load_lds_dwordx4 v[64:65], off
	s_mov_b32 m0, s18
	v_lshlrev_b32_e32 v64, 11, v71
	global_load_lds_dwordx4 v[62:63], off
	v_lshrrev_b32_e32 v63, 2, v70
	v_lshlrev_b32_e32 v62, 6, v70
	v_sub_u32_e32 v63, 0, v63
	v_and_b32_e32 v62, 0x3c0, v62
	v_bitop3_b32 v63, v72, v63, 3 bitop3:0x78
	v_lshl_or_b32 v62, v63, 4, v62
	v_lshlrev_b32_e32 v63, 5, v70
	v_and_or_b32 v63, v63, s49, v62
	s_waitcnt vmcnt(3)
	v_add_u32_e32 v155, 0, v63
	v_and_or_b32 v86, v64, s50, v62
	s_waitcnt lgkmcnt(0)
	s_barrier
; #define RAW_BARRIER() do { asm volatile("s_waitcnt lgkmcnt(0)" ::: "memory"); __builtin_amdgcn_s_barrier(); } while (0)
; #define GLDS_TILE(kt, st) do { _Pragma("unroll") for (int _i = 0; _i < NP; ++_i) GLDS_PIECE(_i, kt, st); } while (0)
;     ...
;     constexpr int NH = NI >= 4 ? NI / 2 : NI;
;     constexpr int NP = 2 + NB, IVL = (4 * NI) / NP;
;     RAW_BARRIER();
;     GLDS_TILE(0, 0);
;     GLDS_TILE(1, 1);
;     int st = 0;
;     for (int kt = 0; kt < nk - 1; ++kt) {
;         if (NI == 8) asm volatile("s_waitcnt vmcnt(6)" ::: "memory"); else if (NI == 4) asm volatile("s_waitcnt vmcnt(4)" ::: "memory"); else asm volatile("s_waitcnt vmcnt(3)" ::: "memory");
;         RAW_BARRIER();
;         const int s2 = st >= 1 ? st - 1 : 2;
;         const bool ld = kt + 2 < nk;
;         STEP_TILE(st, ld, kt + 2, s2);
;         st = st == 2 ? 0 : st + 1;
;     }
	ds_read_b128 v[62:65], v155
	ds_read_b128 v[70:73], v155 offset:1024
	ds_read_b128 v[74:77], v155 offset:2048
	ds_read_b128 v[78:81], v155 offset:3072
	v_add_u32_e32 v157, 0, v86
	ds_read_b128 v[86:89], v157 offset:8192
	ds_read_b128 v[90:93], v157 offset:9216
	s_setprio 1
	s_mov_b64 s[40:41], 0x1a00080
	v_add_u32_e32 v148, 0x6000, v32
	s_waitcnt lgkmcnt(0)
	v_mfma_f32_16x16x32_bf16 v[132:135], v[86:89], v[62:65], 0
	v_lshl_add_u64 v[142:143], v[60:61], 0, s[40:41]
	v_add_u32_e32 v152, 0x8000, v32
	v_lshl_add_u64 v[146:147], v[58:59], 0, s[54:55]
	v_mfma_f32_16x16x32_bf16 v[138:141], v[86:89], v[70:73], 0
	v_readfirstlane_b32 s39, v148
	s_mov_b32 m0, s39
	s_nop 0
	global_load_lds_dwordx4 v[146:147], off
	v_mfma_f32_16x16x32_bf16 v[146:149], v[86:89], v[74:77], 0
	v_mfma_f32_16x16x32_bf16 v[86:89], v[86:89], v[78:81], 0
	v_add_u32_e32 v32, 0x7000, v32
	v_lshl_add_u64 v[150:151], v[58:59], 0, s[76:77]
	v_readfirstlane_b32 s42, v32
	s_mov_b32 m0, s42
	s_mov_b64 s[76:77], 0x8140
	global_load_lds_dwordx4 v[150:151], off
	s_mov_b64 s[46:47], 0x8100
	s_mov_b64 s[44:45], 0x80c0
	v_mfma_f32_16x16x32_bf16 v[62:65], v[90:93], v[62:65], 0
	v_mfma_f32_16x16x32_bf16 v[70:73], v[90:93], v[70:73], 0
	v_readfirstlane_b32 s43, v152
	s_mov_b32 m0, s43
	s_nop 0
	global_load_lds_dwordx4 v[142:143], off
	v_mfma_f32_16x16x32_bf16 v[74:77], v[90:93], v[74:77], 0
	v_mfma_f32_16x16x32_bf16 v[78:81], v[90:93], v[78:81], 0
	s_setprio 0
	s_waitcnt vmcnt(3)
	s_waitcnt lgkmcnt(0)
	s_barrier
	ds_read_b128 v[166:169], v157 offset:20480
	ds_read_b128 v[90:93], v155 offset:12288
	ds_read_b128 v[150:153], v155 offset:13312
	ds_read_b128 v[158:161], v155 offset:14336
	ds_read_b128 v[162:165], v155 offset:15360
	ds_read_b128 v[170:173], v157 offset:21504
	s_setprio 1
	s_mov_b64 s[40:41], 0x1a000c0
	s_waitcnt lgkmcnt(4)
	v_mfma_f32_16x16x32_bf16 v[132:135], v[166:169], v[90:93], v[132:135]
	v_lshl_add_u64 v[142:143], v[60:61], 0, s[40:41]
	v_lshl_add_u64 v[174:175], v[58:59], 0, s[56:57]
	s_waitcnt lgkmcnt(3)
	v_mfma_f32_16x16x32_bf16 v[138:141], v[166:169], v[150:153], v[138:141]
	s_mov_b32 m0, s38
	s_nop 0
	global_load_lds_dwordx4 v[174:175], off
	s_waitcnt lgkmcnt(2)
	v_mfma_f32_16x16x32_bf16 v[146:149], v[166:169], v[158:161], v[146:149]
	s_waitcnt lgkmcnt(1)
	v_mfma_f32_16x16x32_bf16 v[86:89], v[166:169], v[162:165], v[86:89]
	v_lshl_add_u64 v[166:167], v[58:59], 0, s[44:45]
	s_mov_b32 m0, s35
	s_nop 0
	global_load_lds_dwordx4 v[166:167], off
	s_waitcnt lgkmcnt(0)
	v_mfma_f32_16x16x32_bf16 v[62:65], v[170:173], v[90:93], v[62:65]
	v_mfma_f32_16x16x32_bf16 v[70:73], v[170:173], v[150:153], v[70:73]
	s_mov_b32 m0, s34
	s_nop 0
	global_load_lds_dwordx4 v[142:143], off
	v_mfma_f32_16x16x32_bf16 v[74:77], v[170:173], v[158:161], v[74:77]
	v_mfma_f32_16x16x32_bf16 v[78:81], v[170:173], v[162:165], v[78:81]
	s_setprio 0
	s_waitcnt vmcnt(3)
	s_waitcnt lgkmcnt(0)
	s_barrier
	ds_read_b128 v[166:169], v157 offset:32768
	ds_read_b128 v[90:93], v155 offset:24576
	ds_read_b128 v[150:153], v155 offset:25600
	ds_read_b128 v[158:161], v155 offset:26624
	ds_read_b128 v[162:165], v155 offset:27648
	ds_read_b128 v[170:173], v157 offset:33792
	s_setprio 1
	s_mov_b64 s[40:41], 0x1a00100
	s_waitcnt lgkmcnt(4)
	v_mfma_f32_16x16x32_bf16 v[132:135], v[166:169], v[90:93], v[132:135]
	v_lshl_add_u64 v[142:143], v[60:61], 0, s[40:41]
	v_lshl_add_u64 v[174:175], v[58:59], 0, s[58:59]
	s_waitcnt lgkmcnt(3)
	v_mfma_f32_16x16x32_bf16 v[138:141], v[166:169], v[150:153], v[138:141]
	s_mov_b32 m0, s31
	s_nop 0
	global_load_lds_dwordx4 v[174:175], off
	s_waitcnt lgkmcnt(2)
	v_mfma_f32_16x16x32_bf16 v[146:149], v[166:169], v[158:161], v[146:149]
	s_waitcnt lgkmcnt(1)
	v_mfma_f32_16x16x32_bf16 v[86:89], v[166:169], v[162:165], v[86:89]
	v_lshl_add_u64 v[166:167], v[58:59], 0, s[46:47]
	s_mov_b32 m0, s19
	s_nop 0
	global_load_lds_dwordx4 v[166:167], off
	s_waitcnt lgkmcnt(0)
	v_mfma_f32_16x16x32_bf16 v[62:65], v[170:173], v[90:93], v[62:65]
	v_mfma_f32_16x16x32_bf16 v[70:73], v[170:173], v[150:153], v[70:73]
	s_mov_b32 m0, s18
	s_nop 0
	global_load_lds_dwordx4 v[142:143], off
	v_mfma_f32_16x16x32_bf16 v[74:77], v[170:173], v[158:161], v[74:77]
	v_mfma_f32_16x16x32_bf16 v[78:81], v[170:173], v[162:165], v[78:81]
	s_setprio 0
	s_waitcnt vmcnt(3)
	s_waitcnt lgkmcnt(0)
	s_barrier
	ds_read_b128 v[166:169], v157 offset:8192
	ds_read_b128 v[90:93], v155
	ds_read_b128 v[150:153], v155 offset:1024
	ds_read_b128 v[158:161], v155 offset:2048
	ds_read_b128 v[162:165], v155 offset:3072
	ds_read_b128 v[170:173], v157 offset:9216
	s_setprio 1
	s_mov_b64 s[40:41], 0x1a00140
	s_waitcnt lgkmcnt(4)
	v_mfma_f32_16x16x32_bf16 v[132:135], v[166:169], v[90:93], v[132:135]
	v_lshl_add_u64 v[142:143], v[60:61], 0, s[40:41]
	v_lshl_add_u64 v[174:175], v[58:59], 0, s[60:61]
	s_waitcnt lgkmcnt(3)
	v_mfma_f32_16x16x32_bf16 v[138:141], v[166:169], v[150:153], v[138:141]
	s_mov_b32 m0, s39
	s_nop 0
	global_load_lds_dwordx4 v[174:175], off
	s_waitcnt lgkmcnt(2)
	v_mfma_f32_16x16x32_bf16 v[146:149], v[166:169], v[158:161], v[146:149]
	s_waitcnt lgkmcnt(1)
	v_mfma_f32_16x16x32_bf16 v[86:89], v[166:169], v[162:165], v[86:89]
	v_lshl_add_u64 v[166:167], v[58:59], 0, s[76:77]
	s_mov_b32 m0, s42
	s_mov_b64 s[46:47], 0x81c0
	global_load_lds_dwordx4 v[166:167], off
	s_mov_b64 s[44:45], 0x8180
	s_waitcnt lgkmcnt(0)
	v_mfma_f32_16x16x32_bf16 v[62:65], v[170:173], v[90:93], v[62:65]
	v_mfma_f32_16x16x32_bf16 v[70:73], v[170:173], v[150:153], v[70:73]
	s_mov_b32 m0, s43
	s_nop 0
	global_load_lds_dwordx4 v[142:143], off
	v_mfma_f32_16x16x32_bf16 v[74:77], v[170:173], v[158:161], v[74:77]
	v_mfma_f32_16x16x32_bf16 v[78:81], v[170:173], v[162:165], v[78:81]
	s_setprio 0
	s_waitcnt vmcnt(3)
	s_waitcnt lgkmcnt(0)
	s_barrier
;     __device__ __forceinline__ bf16_t* G() const { return (bf16_t*)(ws + OFF_G); }
; DEV void ld_bf4(const bf16_t* p, float (&v)[4]) { uint2 w = *(const uint2*)p; v[0] = bf_lo(w.x); v[1] = bf_hi(w.x); v[2] = bf_lo(w.y); v[3] = bf_hi(w.y); }
; #define RAW_BARRIER() do { asm volatile("s_waitcnt lgkmcnt(0)" ::: "memory"); __builtin_amdgcn_s_barrier(); } while (0)
; #define GLDS_TILE(kt, st) do { _Pragma("unroll") for (int _i = 0; _i < NP; ++_i) GLDS_PIECE(_i, kt, st); } while (0)
;     ...
;     constexpr int NH = NI >= 4 ? NI / 2 : NI;
;     constexpr int NP = 2 + NB, IVL = (4 * NI) / NP;
;     RAW_BARRIER();
;     GLDS_TILE(0, 0);
;     GLDS_TILE(1, 1);
;     int st = 0;
;     for (int kt = 0; kt < nk - 1; ++kt) {
;         if (NI == 8) asm volatile("s_waitcnt vmcnt(6)" ::: "memory"); else if (NI == 4) asm volatile("s_waitcnt vmcnt(4)" ::: "memory"); else asm volatile("s_waitcnt vmcnt(3)" ::: "memory");
;         RAW_BARRIER();
;         const int s2 = st >= 1 ? st - 1 : 2;
;         const bool ld = kt + 2 < nk;
;         STEP_TILE(st, ld, kt + 2, s2);
;         st = st == 2 ? 0 : st + 1;
;     }
;     asm volatile("s_waitcnt vmcnt(0)" ::: "memory");
;     RAW_BARRIER();
;     STEP_TILE(st, false, 0, 0);
; DEV void merge_big(const Params& p, int l, int mt, int nt, char* smem) {
;     ...
; #pragma unroll
;         for (int mi = 0; mi < 4; ++mi)
; #pragma unroll
;             for (int ni = 0; ni < 2; ++ni) {
;                 float g[4]; ld_bf4(p.G() + (size_t)(rbase + mi * 16) * 3072 + br * 1024 + c0 + ni * 16, g);
;                 const f32x4 gv = (f32x4){g[0], g[1], g[2], g[3]};
;                 if (br == 0) mg[mi][ni] = gv * acc[mi][ni]; else mg[mi][ni] += gv * acc[mi][ni];
	ds_read_b128 v[166:169], v157 offset:20480
	ds_read_b128 v[90:93], v155 offset:12288
	ds_read_b128 v[150:153], v155 offset:13312
	ds_read_b128 v[158:161], v155 offset:14336
	ds_read_b128 v[162:165], v155 offset:15360
	ds_read_b128 v[170:173], v157 offset:21504
	s_setprio 1
	s_mov_b64 s[40:41], 0x1a00180
	s_waitcnt lgkmcnt(4)
	v_mfma_f32_16x16x32_bf16 v[132:135], v[166:169], v[90:93], v[132:135]
	v_lshl_add_u64 v[142:143], v[60:61], 0, s[40:41]
	v_lshl_add_u64 v[174:175], v[58:59], 0, s[62:63]
	s_waitcnt lgkmcnt(3)
	v_mfma_f32_16x16x32_bf16 v[138:141], v[166:169], v[150:153], v[138:141]
	s_mov_b32 m0, s38
	s_nop 0
	global_load_lds_dwordx4 v[174:175], off
	s_waitcnt lgkmcnt(2)
	v_mfma_f32_16x16x32_bf16 v[146:149], v[166:169], v[158:161], v[146:149]
	s_waitcnt lgkmcnt(1)
	v_mfma_f32_16x16x32_bf16 v[86:89], v[166:169], v[162:165], v[86:89]
	v_lshl_add_u64 v[166:167], v[58:59], 0, s[44:45]
	s_mov_b32 m0, s35
	s_nop 0
	global_load_lds_dwordx4 v[166:167], off
	s_waitcnt lgkmcnt(0)
	v_mfma_f32_16x16x32_bf16 v[62:65], v[170:173], v[90:93], v[62:65]
	v_mfma_f32_16x16x32_bf16 v[70:73], v[170:173], v[150:153], v[70:73]
	s_mov_b32 m0, s34
	s_nop 0
	global_load_lds_dwordx4 v[142:143], off
	v_mfma_f32_16x16x32_bf16 v[74:77], v[170:173], v[158:161], v[74:77]
	v_mfma_f32_16x16x32_bf16 v[78:81], v[170:173], v[162:165], v[78:81]
	s_setprio 0
	s_waitcnt vmcnt(3)
	s_waitcnt lgkmcnt(0)
	s_barrier
	ds_read_b128 v[166:169], v157 offset:32768
	ds_read_b128 v[90:93], v155 offset:24576
	ds_read_b128 v[150:153], v155 offset:25600
	ds_read_b128 v[158:161], v155 offset:26624
	ds_read_b128 v[162:165], v155 offset:27648
	ds_read_b128 v[170:173], v157 offset:33792
	s_setprio 1
	s_mov_b64 s[34:35], 0x1a001c0
	s_waitcnt lgkmcnt(4)
	v_mfma_f32_16x16x32_bf16 v[132:135], v[166:169], v[90:93], v[132:135]
	v_lshl_add_u64 v[142:143], v[60:61], 0, s[34:35]
	v_lshl_add_u64 v[60:61], v[58:59], 0, s[64:65]
	s_waitcnt lgkmcnt(3)
	v_mfma_f32_16x16x32_bf16 v[138:141], v[166:169], v[150:153], v[138:141]
	s_mov_b32 m0, s31
	s_nop 0
	global_load_lds_dwordx4 v[60:61], off
	s_waitcnt lgkmcnt(2)
	v_mfma_f32_16x16x32_bf16 v[146:149], v[166:169], v[158:161], v[146:149]
	s_waitcnt lgkmcnt(1)
	v_mfma_f32_16x16x32_bf16 v[86:89], v[166:169], v[162:165], v[86:89]
	v_lshl_add_u64 v[58:59], v[58:59], 0, s[46:47]
	s_mov_b32 m0, s19
	s_nop 0
	global_load_lds_dwordx4 v[58:59], off
	s_waitcnt lgkmcnt(0)
	v_mfma_f32_16x16x32_bf16 v[58:61], v[170:173], v[90:93], v[62:65]
	v_mfma_f32_16x16x32_bf16 v[62:65], v[170:173], v[150:153], v[70:73]
	s_mov_b32 m0, s18
	s_nop 0
	global_load_lds_dwordx4 v[142:143], off
	v_mfma_f32_16x16x32_bf16 v[70:73], v[170:173], v[158:161], v[74:77]
	v_mfma_f32_16x16x32_bf16 v[74:77], v[170:173], v[162:165], v[78:81]
	s_setprio 0
	s_waitcnt vmcnt(3)
	s_waitcnt lgkmcnt(0)
	s_barrier
	s_nop 0
	ds_read_b128 v[78:81], v155
	ds_read_b128 v[90:93], v155 offset:1024
	ds_read_b128 v[150:153], v155 offset:2048
	ds_read_b128 v[158:161], v155 offset:3072
	ds_read_b128 v[162:165], v157 offset:8192
	ds_read_b128 v[166:169], v157 offset:9216
	s_setprio 1
	s_waitcnt lgkmcnt(0)
	v_mfma_f32_16x16x32_bf16 v[132:135], v[162:165], v[78:81], v[132:135]
	v_mfma_f32_16x16x32_bf16 v[138:141], v[162:165], v[90:93], v[138:141]
	v_mfma_f32_16x16x32_bf16 v[146:149], v[162:165], v[150:153], v[146:149]
	v_mfma_f32_16x16x32_bf16 v[86:89], v[162:165], v[158:161], v[86:89]
	v_mfma_f32_16x16x32_bf16 v[162:165], v[166:169], v[78:81], v[58:61]
	v_mfma_f32_16x16x32_bf16 v[170:173], v[166:169], v[90:93], v[62:65]
	v_mfma_f32_16x16x32_bf16 v[150:153], v[166:169], v[150:153], v[70:73]
	v_mfma_f32_16x16x32_bf16 v[158:161], v[166:169], v[158:161], v[74:77]
	s_setprio 0
	s_waitcnt vmcnt(0)
	s_waitcnt lgkmcnt(0)
	s_barrier
	ds_read_b128 v[90:93], v157 offset:20480
	ds_read_b128 v[62:65], v155 offset:12288
	ds_read_b128 v[74:77], v155 offset:13312
	ds_read_b128 v[166:169], v155 offset:14336
	ds_read_b128 v[174:177], v155 offset:15360
	ds_read_b128 v[178:181], v157 offset:21504
	s_setprio 1
	s_waitcnt lgkmcnt(4)
	v_mfma_f32_16x16x32_bf16 v[58:61], v[90:93], v[62:65], v[132:135]
	s_waitcnt lgkmcnt(3)
	v_mfma_f32_16x16x32_bf16 v[70:73], v[90:93], v[74:77], v[138:141]
	s_waitcnt lgkmcnt(2)
	v_mfma_f32_16x16x32_bf16 v[78:81], v[90:93], v[166:169], v[146:149]
	s_waitcnt lgkmcnt(1)
	v_mfma_f32_16x16x32_bf16 v[90:93], v[90:93], v[174:177], v[86:89]
	s_waitcnt lgkmcnt(0)
	v_mfma_f32_16x16x32_bf16 v[62:65], v[178:181], v[62:65], v[162:165]
	v_mfma_f32_16x16x32_bf16 v[74:77], v[178:181], v[74:77], v[170:173]
	v_mfma_f32_16x16x32_bf16 v[86:89], v[178:181], v[166:169], v[150:153]
	v_mfma_f32_16x16x32_bf16 v[148:151], v[178:181], v[174:177], v[158:161]
	s_setprio 0
	s_nop 0
	v_lshl_add_u64 v[152:153], s[12:13], 0, v[96:97]
	s_waitcnt vmcnt(0)
	v_lshlrev_b32_e32 v162, 16, v144
	v_and_b32_e32 v163, 0xffff0000, v144
	v_lshlrev_b32_e32 v144, 16, v145
	v_and_b32_e32 v145, 0xffff0000, v145
	v_mad_i64_i32 v[134:135], s[18:19], v94, s51, v[152:153]
	v_mad_i64_i32 v[140:141], s[18:19], v102, s51, v[152:153]
	v_mad_i64_i32 v[146:147], s[18:19], v100, s51, v[152:153]
	v_mad_i64_i32 v[152:153], s[18:19], v98, s51, v[152:153]
	v_lshlrev_b32_e32 v160, 16, v122
	v_and_b32_e32 v161, 0xffff0000, v122
	v_lshlrev_b32_e32 v122, 16, v123
	v_and_b32_e32 v123, 0xffff0000, v123
	v_pk_mul_f32 v[84:85], v[84:85], v[144:145]
	v_pk_mul_f32 v[82:83], v[82:83], v[162:163]
	s_waitcnt lgkmcnt(0)
	s_barrier
;     __device__ __forceinline__ bf16_t* G() const { return (bf16_t*)(ws + OFF_G); }
;     __device__ __forceinline__ bf16_t* Mg() const { return (bf16_t*)(ws + OFF_Mg); }
; DEV void st_bf4(bf16_t* p, float a, float b, float c, float d) { uint2 w; w.x = pk_bf16(a, b); w.y = pk_bf16(c, d); *(uint2*)p = w; }
; DEV void ld_bf4(const bf16_t* p, float (&v)[4]) { uint2 w = *(const uint2*)p; v[0] = bf_lo(w.x); v[1] = bf_hi(w.x); v[2] = bf_lo(w.y); v[3] = bf_hi(w.y); }
; DEV void merge_big(const Params& p, int l, int mt, int nt, char* smem) {
;     ...
; #pragma unroll
;         for (int mi = 0; mi < 4; ++mi)
; #pragma unroll
;             for (int ni = 0; ni < 2; ++ni) {
;                 float g[4]; ld_bf4(p.G() + (size_t)(rbase + mi * 16) * 3072 + br * 1024 + c0 + ni * 16, g);
;                 const f32x4 gv = (f32x4){g[0], g[1], g[2], g[3]};
;                 if (br == 0) mg[mi][ni] = gv * acc[mi][ni]; else mg[mi][ni] += gv * acc[mi][ni];
;             }
;     }
; #pragma unroll
;     for (int mi = 0; mi < 4; ++mi)
; #pragma unroll
;         for (int ni = 0; ni < 2; ++ni) st_bf4(p.Mg() + (size_t)(rbase + mi * 16) * 1024 + c0 + ni * 16, mg[mi][ni][0], mg[mi][ni][1], mg[mi][ni][2], mg[mi][ni][3]);
	flat_load_dwordx2 v[132:133], v[134:135]
	s_nop 0
	flat_load_dwordx2 v[134:135], v[134:135] offset:32
	s_nop 0
	flat_load_dwordx2 v[138:139], v[140:141]
	s_nop 0
	flat_load_dwordx2 v[140:141], v[140:141] offset:32
	s_nop 0
	flat_load_dwordx2 v[142:143], v[146:147]
	s_nop 0
	flat_load_dwordx2 v[146:147], v[146:147] offset:32
	v_pk_fma_f32 v[82:83], v[38:39], v[160:161], v[82:83]
	flat_load_dwordx2 v[158:159], v[152:153]
	v_pk_fma_f32 v[38:39], v[40:41], v[122:123], v[84:85]
	flat_load_dwordx2 v[40:41], v[152:153] offset:32
	v_lshlrev_b32_e32 v122, 16, v137
	v_and_b32_e32 v123, 0xffff0000, v137
	v_pk_mul_f32 v[68:69], v[68:69], v[122:123]
	s_add_i32 s30, s30, s82
	s_add_i32 s20, s20, s21
	s_mul_i32 s18, s82, 0xc000
	s_add_u32 s22, s22, s18
	s_mul_hi_i32 s18, s82, 0xc000
	s_addc_u32 s23, s23, s18
	s_add_u32 s28, s28, s16
	s_addc_u32 s29, s29, s17
	s_cmp_gt_i32 s30, 15
	s_waitcnt vmcnt(0) lgkmcnt(0)
	v_lshlrev_b32_e32 v84, 16, v40
	v_and_b32_e32 v85, 0xffff0000, v40
	v_lshlrev_b32_e32 v40, 16, v41
	v_and_b32_e32 v41, 0xffff0000, v41
	v_pk_fma_f32 v[38:39], v[150:151], v[40:41], v[38:39]
	v_pk_fma_f32 v[40:41], v[148:149], v[84:85], v[82:83]
	v_lshlrev_b32_e32 v82, 16, v116
	v_and_b32_e32 v83, 0xffff0000, v116
	v_lshlrev_b32_e32 v84, 16, v117
	v_and_b32_e32 v85, 0xffff0000, v117
	v_lshlrev_b32_e32 v116, 16, v136
	v_and_b32_e32 v117, 0xffff0000, v136
	v_pk_mul_f32 v[66:67], v[66:67], v[116:117]
	s_nop 0
	v_pk_fma_f32 v[66:67], v[24:25], v[82:83], v[66:67]
	v_pk_fma_f32 v[24:25], v[26:27], v[84:85], v[68:69]
	v_lshlrev_b32_e32 v26, 16, v158
	v_and_b32_e32 v27, 0xffff0000, v158
	v_lshlrev_b32_e32 v68, 16, v159
	v_and_b32_e32 v69, 0xffff0000, v159
	v_lshlrev_b32_e32 v82, 16, v130
	v_and_b32_e32 v83, 0xffff0000, v130
	v_lshlrev_b32_e32 v84, 16, v131
	v_and_b32_e32 v85, 0xffff0000, v131
	v_pk_fma_f32 v[24:25], v[92:93], v[68:69], v[24:25]
	v_pk_fma_f32 v[26:27], v[90:91], v[26:27], v[66:67]
	v_lshlrev_b32_e32 v66, 16, v114
	v_and_b32_e32 v67, 0xffff0000, v114
	v_lshlrev_b32_e32 v68, 16, v115
	v_and_b32_e32 v69, 0xffff0000, v115
	v_pk_mul_f32 v[56:57], v[56:57], v[84:85]
	v_pk_mul_f32 v[54:55], v[54:55], v[82:83]
	s_nop 0
	v_pk_fma_f32 v[54:55], v[20:21], v[66:67], v[54:55]
	v_pk_fma_f32 v[20:21], v[22:23], v[68:69], v[56:57]
	v_lshlrev_b32_e32 v22, 16, v146
	v_and_b32_e32 v23, 0xffff0000, v146
	v_lshlrev_b32_e32 v66, 16, v128
	v_and_b32_e32 v67, 0xffff0000, v128
	v_lshlrev_b32_e32 v56, 16, v147
	v_and_b32_e32 v57, 0xffff0000, v147
	v_pk_fma_f32 v[22:23], v[86:87], v[22:23], v[54:55]
	v_lshlrev_b32_e32 v54, 16, v112
	v_and_b32_e32 v55, 0xffff0000, v112
	v_lshlrev_b32_e32 v68, 16, v129
	v_and_b32_e32 v69, 0xffff0000, v129
	v_pk_mul_f32 v[50:51], v[50:51], v[66:67]
	v_pk_fma_f32 v[20:21], v[88:89], v[56:57], v[20:21]
	v_lshlrev_b32_e32 v56, 16, v113
	v_and_b32_e32 v57, 0xffff0000, v113
	v_pk_mul_f32 v[52:53], v[52:53], v[68:69]
	v_pk_fma_f32 v[16:17], v[16:17], v[54:55], v[50:51]
	v_lshlrev_b32_e32 v50, 16, v142
	v_and_b32_e32 v51, 0xffff0000, v142
	v_lshlrev_b32_e32 v54, 16, v126
	v_and_b32_e32 v55, 0xffff0000, v126
	v_pk_fma_f32 v[18:19], v[18:19], v[56:57], v[52:53]
	v_lshlrev_b32_e32 v52, 16, v143
	v_and_b32_e32 v53, 0xffff0000, v143
	v_pk_fma_f32 v[16:17], v[78:79], v[50:51], v[16:17]
	v_lshlrev_b32_e32 v50, 16, v110
	v_and_b32_e32 v51, 0xffff0000, v110
	v_lshlrev_b32_e32 v56, 16, v127
	v_and_b32_e32 v57, 0xffff0000, v127
	v_pk_mul_f32 v[46:47], v[46:47], v[54:55]
	v_pk_fma_f32 v[18:19], v[80:81], v[52:53], v[18:19]
	v_lshlrev_b32_e32 v52, 16, v111
	v_and_b32_e32 v53, 0xffff0000, v111
	v_pk_mul_f32 v[48:49], v[48:49], v[56:57]
	v_pk_fma_f32 v[12:13], v[12:13], v[50:51], v[46:47]
	v_lshlrev_b32_e32 v46, 16, v140
	v_and_b32_e32 v47, 0xffff0000, v140
	v_lshlrev_b32_e32 v50, 16, v124
	v_and_b32_e32 v51, 0xffff0000, v124
	v_pk_fma_f32 v[14:15], v[14:15], v[52:53], v[48:49]
	v_lshlrev_b32_e32 v48, 16, v141
	v_and_b32_e32 v49, 0xffff0000, v141
	v_pk_fma_f32 v[12:13], v[74:75], v[46:47], v[12:13]
	v_lshlrev_b32_e32 v46, 16, v108
	v_and_b32_e32 v47, 0xffff0000, v108
;     __device__ __forceinline__ bf16_t* G() const { return (bf16_t*)(ws + OFF_G); }
;     __device__ __forceinline__ bf16_t* Mg() const { return (bf16_t*)(ws + OFF_Mg); }
; DEV void st_bf4(bf16_t* p, float a, float b, float c, float d) { uint2 w; w.x = pk_bf16(a, b); w.y = pk_bf16(c, d); *(uint2*)p = w; }
; DEV void ld_bf4(const bf16_t* p, float (&v)[4]) { uint2 w = *(const uint2*)p; v[0] = bf_lo(w.x); v[1] = bf_hi(w.x); v[2] = bf_lo(w.y); v[3] = bf_hi(w.y); }
; DEV void merge_big(const Params& p, int l, int mt, int nt, char* smem) {
;     ...
; #pragma unroll
;         for (int mi = 0; mi < 4; ++mi)
; #pragma unroll
;             for (int ni = 0; ni < 2; ++ni) {
;                 float g[4]; ld_bf4(p.G() + (size_t)(rbase + mi * 16) * 3072 + br * 1024 + c0 + ni * 16, g);
;                 const f32x4 gv = (f32x4){g[0], g[1], g[2], g[3]};
;                 if (br == 0) mg[mi][ni] = gv * acc[mi][ni]; else mg[mi][ni] += gv * acc[mi][ni];
;             }
;     }
; #pragma unroll
;     for (int mi = 0; mi < 4; ++mi)
; #pragma unroll
;         for (int ni = 0; ni < 2; ++ni) st_bf4(p.Mg() + (size_t)(rbase + mi * 16) * 1024 + c0 + ni * 16, mg[mi][ni][0], mg[mi][ni][1], mg[mi][ni][2], mg[mi][ni][3]);
	v_lshlrev_b32_e32 v52, 16, v125
	v_and_b32_e32 v53, 0xffff0000, v125
	v_pk_mul_f32 v[42:43], v[42:43], v[50:51]
	v_pk_fma_f32 v[14:15], v[76:77], v[48:49], v[14:15]
	v_lshlrev_b32_e32 v48, 16, v109
	v_and_b32_e32 v49, 0xffff0000, v109
	v_pk_mul_f32 v[44:45], v[44:45], v[52:53]
	v_pk_fma_f32 v[8:9], v[8:9], v[46:47], v[42:43]
	v_lshlrev_b32_e32 v42, 16, v138
	v_and_b32_e32 v43, 0xffff0000, v138
	v_lshlrev_b32_e32 v46, 16, v120
	v_and_b32_e32 v47, 0xffff0000, v120
	v_pk_fma_f32 v[10:11], v[10:11], v[48:49], v[44:45]
	v_lshlrev_b32_e32 v44, 16, v139
	v_and_b32_e32 v45, 0xffff0000, v139
	v_pk_fma_f32 v[8:9], v[70:71], v[42:43], v[8:9]
	v_lshlrev_b32_e32 v42, 16, v106
	v_and_b32_e32 v43, 0xffff0000, v106
	v_lshlrev_b32_e32 v48, 16, v121
	v_and_b32_e32 v49, 0xffff0000, v121
	v_pk_mul_f32 v[34:35], v[34:35], v[46:47]
	v_pk_fma_f32 v[10:11], v[72:73], v[44:45], v[10:11]
	v_lshlrev_b32_e32 v44, 16, v107
	v_and_b32_e32 v45, 0xffff0000, v107
	v_pk_mul_f32 v[36:37], v[36:37], v[48:49]
	v_pk_fma_f32 v[4:5], v[4:5], v[42:43], v[34:35]
	v_lshlrev_b32_e32 v34, 16, v134
	v_and_b32_e32 v35, 0xffff0000, v134
	v_lshlrev_b32_e32 v42, 16, v118
	v_and_b32_e32 v43, 0xffff0000, v118
	v_pk_fma_f32 v[6:7], v[6:7], v[44:45], v[36:37]
	v_lshlrev_b32_e32 v36, 16, v135
	v_and_b32_e32 v37, 0xffff0000, v135
	v_pk_fma_f32 v[4:5], v[62:63], v[34:35], v[4:5]
	v_lshlrev_b32_e32 v34, 16, v104
	v_and_b32_e32 v35, 0xffff0000, v104
	v_lshlrev_b32_e32 v44, 16, v119
	v_and_b32_e32 v45, 0xffff0000, v119
	v_pk_mul_f32 v[28:29], v[28:29], v[42:43]
	v_pk_fma_f32 v[6:7], v[64:65], v[36:37], v[6:7]
	v_lshlrev_b32_e32 v36, 16, v105
	v_and_b32_e32 v37, 0xffff0000, v105
	v_pk_mul_f32 v[30:31], v[30:31], v[44:45]
	v_pk_fma_f32 v[0:1], v[0:1], v[34:35], v[28:29]
	v_lshlrev_b32_e32 v28, 16, v132
	v_and_b32_e32 v29, 0xffff0000, v132
	v_pk_fma_f32 v[2:3], v[2:3], v[36:37], v[30:31]
	v_lshlrev_b32_e32 v30, 16, v133
	v_and_b32_e32 v31, 0xffff0000, v133
	v_pk_fma_f32 v[0:1], v[58:59], v[28:29], v[0:1]
	v_lshlrev_b64 v[28:29], 11, v[94:95]
	v_pk_fma_f32 v[2:3], v[60:61], v[30:31], v[2:3]
	v_lshl_add_u64 v[30:31], s[14:15], 0, v[28:29]
	v_lshl_add_u64 v[30:31], v[30:31], 0, v[96:97]
	v_cvt_pk_bf16_f32 v0, v0, v1
	v_cvt_pk_bf16_f32 v1, v2, v3
	flat_store_dwordx2 v[30:31], v[0:1]
	v_lshl_add_u64 v[0:1], s[2:3], 0, v[28:29]
	v_lshl_add_u64 v[0:1], v[0:1], 0, v[96:97]
	v_add_co_u32_e32 v0, vcc, s52, v0
	v_cvt_pk_bf16_f32 v2, v4, v5
	v_cvt_pk_bf16_f32 v3, v6, v7
	v_addc_co_u32_e32 v1, vcc, 0, v1, vcc
	flat_store_dwordx2 v[0:1], v[2:3] offset:32
	v_lshlrev_b64 v[0:1], 11, v[102:103]
	v_lshl_add_u64 v[2:3], s[14:15], 0, v[0:1]
	v_lshl_add_u64 v[0:1], s[2:3], 0, v[0:1]
	v_lshl_add_u64 v[0:1], v[0:1], 0, v[96:97]
	v_lshl_add_u64 v[2:3], v[2:3], 0, v[96:97]
	v_cvt_pk_bf16_f32 v4, v8, v9
	v_cvt_pk_bf16_f32 v5, v10, v11
	v_add_co_u32_e32 v0, vcc, s52, v0
	flat_store_dwordx2 v[2:3], v[4:5]
	v_cvt_pk_bf16_f32 v2, v12, v13
	v_cvt_pk_bf16_f32 v3, v14, v15
	v_addc_co_u32_e32 v1, vcc, 0, v1, vcc
	flat_store_dwordx2 v[0:1], v[2:3] offset:32
	v_lshlrev_b64 v[0:1], 11, v[100:101]
	v_lshl_add_u64 v[2:3], s[14:15], 0, v[0:1]
	v_lshl_add_u64 v[0:1], s[2:3], 0, v[0:1]
	v_lshl_add_u64 v[0:1], v[0:1], 0, v[96:97]
	v_lshl_add_u64 v[2:3], v[2:3], 0, v[96:97]
	v_cvt_pk_bf16_f32 v4, v16, v17
	v_cvt_pk_bf16_f32 v5, v18, v19
	v_add_co_u32_e32 v0, vcc, s52, v0
	flat_store_dwordx2 v[2:3], v[4:5]
	v_cvt_pk_bf16_f32 v2, v22, v23
	v_cvt_pk_bf16_f32 v3, v20, v21
	v_addc_co_u32_e32 v1, vcc, 0, v1, vcc
	flat_store_dwordx2 v[0:1], v[2:3] offset:32
	v_lshlrev_b64 v[0:1], 11, v[98:99]
	v_lshl_add_u64 v[2:3], s[14:15], 0, v[0:1]
	v_lshl_add_u64 v[0:1], s[2:3], 0, v[0:1]
	v_lshl_add_u64 v[0:1], v[0:1], 0, v[96:97]
	v_lshl_add_u64 v[2:3], v[2:3], 0, v[96:97]
	v_cvt_pk_bf16_f32 v4, v26, v27
	v_cvt_pk_bf16_f32 v5, v24, v25
	v_add_co_u32_e32 v0, vcc, s52, v0
	flat_store_dwordx2 v[2:3], v[4:5]
	v_cvt_pk_bf16_f32 v2, v40, v41
	v_cvt_pk_bf16_f32 v3, v38, v39
	v_addc_co_u32_e32 v1, vcc, 0, v1, vcc
	flat_store_dwordx2 v[0:1], v[2:3] offset:32
	s_cbranch_scc0 .LBB0_109
